# gMLP/pooling phase output (mix) stores marked nt (all 40 sites), on top of nt attention output stores
# baseline (speedup 1.0000x reference)
.LBB0_332:
	s_or_b64 exec, exec, s[0:1]
	s_lshl_b32 s0, s6, 7
	s_waitcnt vmcnt(16)
	v_or_b32_e32 v128, s0, v188
	v_lshlrev_b32_e32 v128, 2, v128
	global_load_dword v128, v128, s[8:9]
	s_nop 0
	ds_read_b128 v[130:133], v246
	ds_read_b128 v[134:137], v247
	v_ashrrev_i32_e32 v167, 31, v166
	s_lshl_b32 s12, s7, 1
	s_waitcnt vmcnt(0) lgkmcnt(0)
	v_pk_mul_f32 v[134:135], v[128:129], v[134:135] op_sel_hi:[0,1]
	v_pk_fma_f32 v[48:49], v[48:49], v[130:131], v[134:135]
	s_nop 0
	v_cvt_pk_f16_f32 v134, v48, v49
	v_pk_mul_f32 v[48:49], v[128:129], v[136:137] op_sel_hi:[0,1]
	v_pk_fma_f32 v[48:49], v[50:51], v[132:133], v[48:49]
	s_nop 0
	v_cvt_pk_f16_f32 v135, v48, v49
	ds_read_b128 v[48:51], v246 offset:32
	ds_read_b128 v[130:133], v247 offset:32
	s_waitcnt lgkmcnt(0)
	v_pk_mul_f32 v[130:131], v[128:129], v[130:131] op_sel_hi:[0,1]
	v_pk_fma_f32 v[48:49], v[52:53], v[48:49], v[130:131]
	v_pk_mul_f32 v[52:53], v[128:129], v[132:133] op_sel_hi:[0,1]
	v_pk_fma_f32 v[50:51], v[54:55], v[50:51], v[52:53]
	v_cvt_pk_f16_f32 v48, v48, v49
	v_cvt_pk_f16_f32 v49, v50, v51
	ds_write2_b64 v214, v[134:135], v[48:49] offset1:2
	ds_read_b128 v[48:51], v246 offset:64
	ds_read_b128 v[52:55], v247 offset:64
	s_waitcnt lgkmcnt(0)
	v_pk_mul_f32 v[52:53], v[128:129], v[52:53] op_sel_hi:[0,1]
	v_pk_fma_f32 v[48:49], v[56:57], v[48:49], v[52:53]
	s_nop 0
	v_cvt_pk_f16_f32 v56, v48, v49
	v_pk_mul_f32 v[48:49], v[128:129], v[54:55] op_sel_hi:[0,1]
	v_pk_fma_f32 v[48:49], v[58:59], v[50:51], v[48:49]
	s_nop 0
	v_cvt_pk_f16_f32 v57, v48, v49
	ds_read_b128 v[48:51], v246 offset:96
	ds_read_b128 v[52:55], v247 offset:96
	s_waitcnt lgkmcnt(0)
	v_pk_mul_f32 v[52:53], v[128:129], v[52:53] op_sel_hi:[0,1]
	v_pk_fma_f32 v[48:49], v[60:61], v[48:49], v[52:53]
	v_pk_mul_f32 v[52:53], v[128:129], v[54:55] op_sel_hi:[0,1]
	v_pk_fma_f32 v[50:51], v[62:63], v[50:51], v[52:53]
	v_cvt_pk_f16_f32 v48, v48, v49
	v_cvt_pk_f16_f32 v49, v50, v51
	ds_write2_b64 v214, v[56:57], v[48:49] offset0:4 offset1:6
	ds_read_b128 v[48:51], v246 offset:128
	ds_read_b128 v[52:55], v247 offset:128
	s_waitcnt lgkmcnt(0)
	v_pk_mul_f32 v[52:53], v[128:129], v[52:53] op_sel_hi:[0,1]
	v_pk_fma_f32 v[32:33], v[32:33], v[48:49], v[52:53]
	s_nop 0
	v_cvt_pk_f16_f32 v52, v32, v33
	v_pk_mul_f32 v[32:33], v[128:129], v[54:55] op_sel_hi:[0,1]
	v_pk_fma_f32 v[32:33], v[34:35], v[50:51], v[32:33]
	s_nop 0
	v_cvt_pk_f16_f32 v53, v32, v33
	ds_read_b128 v[32:35], v246 offset:160
	ds_read_b128 v[48:51], v247 offset:160
	s_waitcnt lgkmcnt(0)
	v_pk_mul_f32 v[48:49], v[128:129], v[48:49] op_sel_hi:[0,1]
	v_pk_fma_f32 v[32:33], v[36:37], v[32:33], v[48:49]
	v_pk_mul_f32 v[36:37], v[128:129], v[50:51] op_sel_hi:[0,1]
	v_pk_fma_f32 v[34:35], v[38:39], v[34:35], v[36:37]
	v_cvt_pk_f16_f32 v32, v32, v33
	v_cvt_pk_f16_f32 v33, v34, v35
	ds_write2_b64 v214, v[52:53], v[32:33] offset0:8 offset1:10
	ds_read_b128 v[32:35], v246 offset:192
	ds_read_b128 v[36:39], v247 offset:192
	s_waitcnt lgkmcnt(0)
	v_pk_mul_f32 v[36:37], v[128:129], v[36:37] op_sel_hi:[0,1]
	v_pk_fma_f32 v[32:33], v[40:41], v[32:33], v[36:37]
	s_nop 0
	v_cvt_pk_f16_f32 v40, v32, v33
	v_pk_mul_f32 v[32:33], v[128:129], v[38:39] op_sel_hi:[0,1]
	v_pk_fma_f32 v[32:33], v[42:43], v[34:35], v[32:33]
	s_nop 0
	v_cvt_pk_f16_f32 v41, v32, v33
	ds_read_b128 v[32:35], v246 offset:224
	ds_read_b128 v[36:39], v247 offset:224
	s_waitcnt lgkmcnt(0)
	v_pk_mul_f32 v[36:37], v[128:129], v[36:37] op_sel_hi:[0,1]
	v_pk_fma_f32 v[32:33], v[44:45], v[32:33], v[36:37]
	v_pk_mul_f32 v[36:37], v[128:129], v[38:39] op_sel_hi:[0,1]
	v_pk_fma_f32 v[34:35], v[46:47], v[34:35], v[36:37]
	v_cvt_pk_f16_f32 v32, v32, v33
	v_cvt_pk_f16_f32 v33, v34, v35
	ds_write2_b64 v214, v[40:41], v[32:33] offset0:12 offset1:14
	ds_read_b128 v[32:35], v246 offset:256
	ds_read_b128 v[36:39], v247 offset:256
	s_waitcnt lgkmcnt(0)
	v_pk_mul_f32 v[36:37], v[128:129], v[36:37] op_sel_hi:[0,1]
	v_pk_fma_f32 v[16:17], v[16:17], v[32:33], v[36:37]
	s_nop 0
	v_cvt_pk_f16_f32 v36, v16, v17
	v_pk_mul_f32 v[16:17], v[128:129], v[38:39] op_sel_hi:[0,1]
	v_pk_fma_f32 v[16:17], v[18:19], v[34:35], v[16:17]
	s_nop 0
	v_cvt_pk_f16_f32 v37, v16, v17
	ds_read_b128 v[16:19], v246 offset:288
	ds_read_b128 v[32:35], v247 offset:288
	s_waitcnt lgkmcnt(0)
	v_pk_mul_f32 v[32:33], v[128:129], v[32:33] op_sel_hi:[0,1]
	v_pk_fma_f32 v[16:17], v[20:21], v[16:17], v[32:33]
	v_pk_mul_f32 v[20:21], v[128:129], v[34:35] op_sel_hi:[0,1]
	v_pk_fma_f32 v[18:19], v[22:23], v[18:19], v[20:21]
	v_cvt_pk_f16_f32 v16, v16, v17
	v_cvt_pk_f16_f32 v17, v18, v19
	ds_write2_b64 v214, v[36:37], v[16:17] offset0:16 offset1:18
	ds_read_b128 v[16:19], v246 offset:320
	ds_read_b128 v[20:23], v247 offset:320
	s_waitcnt lgkmcnt(0)
	v_pk_mul_f32 v[20:21], v[128:129], v[20:21] op_sel_hi:[0,1]
	v_pk_fma_f32 v[16:17], v[24:25], v[16:17], v[20:21]
	s_nop 0
	v_cvt_pk_f16_f32 v24, v16, v17
	v_pk_mul_f32 v[16:17], v[128:129], v[22:23] op_sel_hi:[0,1]
	v_pk_fma_f32 v[16:17], v[26:27], v[18:19], v[16:17]
	s_nop 0
	v_cvt_pk_f16_f32 v25, v16, v17
	ds_read_b128 v[16:19], v246 offset:352
	ds_read_b128 v[20:23], v247 offset:352
	s_waitcnt lgkmcnt(0)
	v_pk_mul_f32 v[20:21], v[128:129], v[20:21] op_sel_hi:[0,1]
	v_pk_fma_f32 v[16:17], v[28:29], v[16:17], v[20:21]
	v_pk_mul_f32 v[20:21], v[128:129], v[22:23] op_sel_hi:[0,1]
	v_pk_fma_f32 v[18:19], v[30:31], v[18:19], v[20:21]
	v_cvt_pk_f16_f32 v16, v16, v17
	v_cvt_pk_f16_f32 v17, v18, v19
	ds_write2_b64 v214, v[24:25], v[16:17] offset0:20 offset1:22
	ds_read_b128 v[16:19], v246 offset:384
	ds_read_b128 v[20:23], v247 offset:384
	s_waitcnt lgkmcnt(0)
	v_pk_mul_f32 v[20:21], v[128:129], v[20:21] op_sel_hi:[0,1]
	v_pk_fma_f32 v[0:1], v[0:1], v[16:17], v[20:21]
	s_nop 0
	v_cvt_pk_f16_f32 v20, v0, v1
	v_pk_mul_f32 v[0:1], v[128:129], v[22:23] op_sel_hi:[0,1]
	v_pk_fma_f32 v[0:1], v[2:3], v[18:19], v[0:1]
	s_nop 0
	v_cvt_pk_f16_f32 v21, v0, v1
	ds_read_b128 v[0:3], v246 offset:416
	ds_read_b128 v[16:19], v247 offset:416
	s_waitcnt lgkmcnt(0)
	v_pk_mul_f32 v[16:17], v[128:129], v[16:17] op_sel_hi:[0,1]
	v_pk_fma_f32 v[0:1], v[4:5], v[0:1], v[16:17]
	v_pk_mul_f32 v[4:5], v[128:129], v[18:19] op_sel_hi:[0,1]
	v_pk_fma_f32 v[2:3], v[6:7], v[2:3], v[4:5]
	v_cvt_pk_f16_f32 v0, v0, v1
	v_cvt_pk_f16_f32 v1, v2, v3
	ds_write2_b64 v214, v[20:21], v[0:1] offset0:24 offset1:26
	ds_read_b128 v[0:3], v246 offset:448
	ds_read_b128 v[4:7], v247 offset:448
	s_waitcnt lgkmcnt(0)
	v_pk_mul_f32 v[4:5], v[128:129], v[4:5] op_sel_hi:[0,1]
	v_pk_fma_f32 v[0:1], v[8:9], v[0:1], v[4:5]
	s_nop 0
	v_cvt_pk_f16_f32 v8, v0, v1
	v_pk_mul_f32 v[0:1], v[128:129], v[6:7] op_sel_hi:[0,1]
	v_pk_fma_f32 v[0:1], v[10:11], v[2:3], v[0:1]
	v_lshlrev_b32_e32 v10, 16, v108
	v_cvt_pk_f16_f32 v9, v0, v1
	ds_read_b128 v[0:3], v246 offset:480
	ds_read_b128 v[4:7], v247 offset:480
	v_and_b32_e32 v11, 0xffff0000, v108
	s_waitcnt lgkmcnt(0)
	v_pk_mul_f32 v[4:5], v[128:129], v[4:5] op_sel_hi:[0,1]
	v_pk_fma_f32 v[0:1], v[12:13], v[0:1], v[4:5]
	v_pk_mul_f32 v[4:5], v[128:129], v[6:7] op_sel_hi:[0,1]
	v_pk_fma_f32 v[2:3], v[14:15], v[2:3], v[4:5]
	v_cvt_pk_f16_f32 v0, v0, v1
	v_cvt_pk_f16_f32 v1, v2, v3
	v_add_u32_e32 v2, s0, v187
	v_ashrrev_i32_e32 v3, 31, v2
	v_lshl_add_u64 v[2:3], v[2:3], 2, s[58:59]
	ds_write2_b64 v214, v[8:9], v[0:1] offset0:28 offset1:30
	s_waitcnt lgkmcnt(0)
	s_barrier
	global_load_dword v8, v[2:3], off
	ds_read_b128 v[4:7], v215
	v_lshlrev_b32_e32 v12, 16, v124
	v_and_b32_e32 v13, 0xffff0000, v124
	v_lshlrev_b64 v[0:1], 12, v[166:167]
	v_lshl_add_u64 v[0:1], s[18:19], 0, v[0:1]
	s_waitcnt lgkmcnt(0)
	v_cvt_f32_f16_e32 v14, v4
	v_cvt_f32_f16_sdwa v15, v4 dst_sel:DWORD dst_unused:UNUSED_PAD src0_sel:WORD_1
	v_lshl_add_u64 v[0:1], v[0:1], 0, s[12:13]
	v_lshl_add_u64 v[0:1], v[0:1], 0, v[150:151]
	s_waitcnt vmcnt(0)
	v_pk_add_f32 v[14:15], v[8:9], v[14:15] op_sel_hi:[0,1]
	v_pk_mul_f32 v[10:11], v[14:15], v[10:11]
	v_cvt_f32_f16_e32 v14, v5
	v_cvt_f32_f16_sdwa v15, v5 dst_sel:DWORD dst_unused:UNUSED_PAD src0_sel:WORD_1
	v_pk_mul_f32 v[10:11], v[10:11], v[12:13]
	v_lshlrev_b32_e32 v12, 16, v125
	v_cvt_pk_bf16_f32 v4, v10, v11
	v_lshlrev_b32_e32 v10, 16, v109
	v_and_b32_e32 v11, 0xffff0000, v109
	v_pk_add_f32 v[14:15], v[8:9], v[14:15] op_sel_hi:[0,1]
	v_pk_mul_f32 v[10:11], v[14:15], v[10:11]
	v_cvt_f32_f16_e32 v14, v6
	v_cvt_f32_f16_sdwa v15, v6 dst_sel:DWORD dst_unused:UNUSED_PAD src0_sel:WORD_1
	v_and_b32_e32 v13, 0xffff0000, v125
	v_pk_mul_f32 v[10:11], v[10:11], v[12:13]
	v_lshlrev_b32_e32 v12, 16, v126
	v_cvt_pk_bf16_f32 v5, v10, v11
	v_lshlrev_b32_e32 v10, 16, v110
	v_and_b32_e32 v11, 0xffff0000, v110
	v_pk_add_f32 v[14:15], v[8:9], v[14:15] op_sel_hi:[0,1]
	v_pk_mul_f32 v[10:11], v[14:15], v[10:11]
	v_cvt_f32_f16_e32 v14, v7
	v_cvt_f32_f16_sdwa v15, v7 dst_sel:DWORD dst_unused:UNUSED_PAD src0_sel:WORD_1
	v_and_b32_e32 v13, 0xffff0000, v126
	v_pk_mul_f32 v[10:11], v[10:11], v[12:13]
	v_lshlrev_b32_e32 v12, 16, v127
	v_cvt_pk_bf16_f32 v6, v10, v11
	v_lshlrev_b32_e32 v10, 16, v111
	v_and_b32_e32 v11, 0xffff0000, v111
	v_pk_add_f32 v[8:9], v[8:9], v[14:15] op_sel_hi:[0,1]
	v_and_b32_e32 v13, 0xffff0000, v127
	v_pk_mul_f32 v[8:9], v[8:9], v[10:11]
	v_lshlrev_b32_e32 v10, 16, v100
	v_pk_mul_f32 v[8:9], v[8:9], v[12:13]
	v_and_b32_e32 v11, 0xffff0000, v100
	v_cvt_pk_bf16_f32 v7, v8, v9
	global_store_dwordx4 v[0:1], v[4:7], off nt
	global_load_dword v4, v[2:3], off offset:64
	ds_read_b128 v[6:9], v215 offset:8448
	v_lshlrev_b32_e32 v12, 16, v120
	v_and_b32_e32 v13, 0xffff0000, v120
	s_waitcnt lgkmcnt(0)
	v_cvt_f32_f16_e32 v14, v6
	v_cvt_f32_f16_sdwa v15, v6 dst_sel:DWORD dst_unused:UNUSED_PAD src0_sel:WORD_1
	s_waitcnt vmcnt(0)
	v_pk_add_f32 v[14:15], v[4:5], v[14:15] op_sel_hi:[0,1]
	v_pk_mul_f32 v[10:11], v[14:15], v[10:11]
	v_cvt_f32_f16_e32 v14, v7
	v_cvt_f32_f16_sdwa v15, v7 dst_sel:DWORD dst_unused:UNUSED_PAD src0_sel:WORD_1
	v_pk_mul_f32 v[10:11], v[10:11], v[12:13]
	v_lshlrev_b32_e32 v12, 16, v121
	v_cvt_pk_bf16_f32 v6, v10, v11
	v_lshlrev_b32_e32 v10, 16, v101
	v_and_b32_e32 v11, 0xffff0000, v101
	v_pk_add_f32 v[14:15], v[4:5], v[14:15] op_sel_hi:[0,1]
	v_pk_mul_f32 v[10:11], v[14:15], v[10:11]
	v_cvt_f32_f16_e32 v14, v8
	v_cvt_f32_f16_sdwa v15, v8 dst_sel:DWORD dst_unused:UNUSED_PAD src0_sel:WORD_1
	v_and_b32_e32 v13, 0xffff0000, v121
	v_pk_mul_f32 v[10:11], v[10:11], v[12:13]
	v_lshlrev_b32_e32 v12, 16, v122
	v_cvt_pk_bf16_f32 v7, v10, v11
	v_lshlrev_b32_e32 v10, 16, v102
	v_and_b32_e32 v11, 0xffff0000, v102
	v_pk_add_f32 v[14:15], v[4:5], v[14:15] op_sel_hi:[0,1]
	v_pk_mul_f32 v[10:11], v[14:15], v[10:11]
	v_cvt_f32_f16_e32 v14, v9
	v_cvt_f32_f16_sdwa v15, v9 dst_sel:DWORD dst_unused:UNUSED_PAD src0_sel:WORD_1
	v_and_b32_e32 v13, 0xffff0000, v122
	v_pk_mul_f32 v[10:11], v[10:11], v[12:13]
	v_lshlrev_b32_e32 v12, 16, v123
	v_cvt_pk_bf16_f32 v8, v10, v11
	v_lshlrev_b32_e32 v10, 16, v103
	v_and_b32_e32 v11, 0xffff0000, v103
	v_pk_add_f32 v[4:5], v[4:5], v[14:15] op_sel_hi:[0,1]
	v_and_b32_e32 v13, 0xffff0000, v123
	v_pk_mul_f32 v[4:5], v[4:5], v[10:11]
	v_lshlrev_b32_e32 v10, 16, v92
	v_pk_mul_f32 v[4:5], v[4:5], v[12:13]
	v_and_b32_e32 v11, 0xffff0000, v92
	v_cvt_pk_bf16_f32 v9, v4, v5
	v_add_co_u32_e32 v4, vcc, s3, v0
	v_lshlrev_b32_e32 v12, 16, v116
	s_nop 0
	v_addc_co_u32_e32 v5, vcc, 0, v1, vcc
	global_store_dwordx4 v[4:5], v[6:9], off nt
	global_load_dword v8, v[2:3], off offset:128
	ds_read_b128 v[4:7], v215 offset:16896
	v_and_b32_e32 v13, 0xffff0000, v116
	s_waitcnt lgkmcnt(0)
	v_cvt_f32_f16_e32 v14, v4
	v_cvt_f32_f16_sdwa v15, v4 dst_sel:DWORD dst_unused:UNUSED_PAD src0_sel:WORD_1
	s_waitcnt vmcnt(0)
	v_pk_add_f32 v[14:15], v[8:9], v[14:15] op_sel_hi:[0,1]
	v_pk_mul_f32 v[10:11], v[14:15], v[10:11]
	v_cvt_f32_f16_e32 v14, v5
	v_cvt_f32_f16_sdwa v15, v5 dst_sel:DWORD dst_unused:UNUSED_PAD src0_sel:WORD_1
	v_pk_mul_f32 v[10:11], v[10:11], v[12:13]
	v_lshlrev_b32_e32 v12, 16, v117
	v_cvt_pk_bf16_f32 v4, v10, v11
	v_lshlrev_b32_e32 v10, 16, v93
	v_and_b32_e32 v11, 0xffff0000, v93
	v_pk_add_f32 v[14:15], v[8:9], v[14:15] op_sel_hi:[0,1]
	v_pk_mul_f32 v[10:11], v[14:15], v[10:11]
	v_cvt_f32_f16_e32 v14, v6
	v_cvt_f32_f16_sdwa v15, v6 dst_sel:DWORD dst_unused:UNUSED_PAD src0_sel:WORD_1
	v_and_b32_e32 v13, 0xffff0000, v117
	v_pk_mul_f32 v[10:11], v[10:11], v[12:13]
	v_lshlrev_b32_e32 v12, 16, v118
	v_cvt_pk_bf16_f32 v5, v10, v11
	v_lshlrev_b32_e32 v10, 16, v94
	v_and_b32_e32 v11, 0xffff0000, v94
	v_pk_add_f32 v[14:15], v[8:9], v[14:15] op_sel_hi:[0,1]
	v_pk_mul_f32 v[10:11], v[14:15], v[10:11]
	v_cvt_f32_f16_e32 v14, v7
	v_cvt_f32_f16_sdwa v15, v7 dst_sel:DWORD dst_unused:UNUSED_PAD src0_sel:WORD_1
	v_and_b32_e32 v13, 0xffff0000, v118
	v_pk_mul_f32 v[10:11], v[10:11], v[12:13]
	v_lshlrev_b32_e32 v12, 16, v119
	v_cvt_pk_bf16_f32 v6, v10, v11
	v_lshlrev_b32_e32 v10, 16, v95
	v_and_b32_e32 v11, 0xffff0000, v95
	v_pk_add_f32 v[8:9], v[8:9], v[14:15] op_sel_hi:[0,1]
	v_and_b32_e32 v13, 0xffff0000, v119
	v_pk_mul_f32 v[8:9], v[8:9], v[10:11]
	v_lshlrev_b32_e32 v10, 16, v84
	v_pk_mul_f32 v[8:9], v[8:9], v[12:13]
	v_and_b32_e32 v11, 0xffff0000, v84
	v_cvt_pk_bf16_f32 v7, v8, v9
	v_add_co_u32_e32 v8, vcc, s87, v0
	v_lshlrev_b32_e32 v12, 16, v112
	s_nop 0
	v_addc_co_u32_e32 v9, vcc, 0, v1, vcc
	global_store_dwordx4 v[8:9], v[4:7], off nt
	global_load_dword v8, v[2:3], off offset:192
	ds_read_b128 v[4:7], v215 offset:25344
	v_and_b32_e32 v13, 0xffff0000, v112
	s_waitcnt lgkmcnt(0)
	v_cvt_f32_f16_e32 v14, v4
	v_cvt_f32_f16_sdwa v15, v4 dst_sel:DWORD dst_unused:UNUSED_PAD src0_sel:WORD_1
	s_waitcnt vmcnt(0)
	v_pk_add_f32 v[14:15], v[8:9], v[14:15] op_sel_hi:[0,1]
	v_pk_mul_f32 v[10:11], v[14:15], v[10:11]
	v_cvt_f32_f16_e32 v14, v5
	v_cvt_f32_f16_sdwa v15, v5 dst_sel:DWORD dst_unused:UNUSED_PAD src0_sel:WORD_1
	v_pk_mul_f32 v[10:11], v[10:11], v[12:13]
	v_lshlrev_b32_e32 v12, 16, v113
	v_cvt_pk_bf16_f32 v4, v10, v11
	v_lshlrev_b32_e32 v10, 16, v85
	v_and_b32_e32 v11, 0xffff0000, v85
	v_pk_add_f32 v[14:15], v[8:9], v[14:15] op_sel_hi:[0,1]
	v_pk_mul_f32 v[10:11], v[14:15], v[10:11]
	v_cvt_f32_f16_e32 v14, v6
	v_cvt_f32_f16_sdwa v15, v6 dst_sel:DWORD dst_unused:UNUSED_PAD src0_sel:WORD_1
	v_and_b32_e32 v13, 0xffff0000, v113
	v_pk_mul_f32 v[10:11], v[10:11], v[12:13]
	v_lshlrev_b32_e32 v12, 16, v114
	v_cvt_pk_bf16_f32 v5, v10, v11
	v_lshlrev_b32_e32 v10, 16, v86
	v_and_b32_e32 v11, 0xffff0000, v86
	v_pk_add_f32 v[14:15], v[8:9], v[14:15] op_sel_hi:[0,1]
	v_pk_mul_f32 v[10:11], v[14:15], v[10:11]
	v_cvt_f32_f16_e32 v14, v7
	v_cvt_f32_f16_sdwa v15, v7 dst_sel:DWORD dst_unused:UNUSED_PAD src0_sel:WORD_1
	v_and_b32_e32 v13, 0xffff0000, v114
	v_pk_mul_f32 v[10:11], v[10:11], v[12:13]
	v_lshlrev_b32_e32 v12, 16, v115
	v_cvt_pk_bf16_f32 v6, v10, v11
	v_lshlrev_b32_e32 v10, 16, v87
	v_and_b32_e32 v11, 0xffff0000, v87
	v_pk_add_f32 v[8:9], v[8:9], v[14:15] op_sel_hi:[0,1]
	v_and_b32_e32 v13, 0xffff0000, v115
	v_pk_mul_f32 v[8:9], v[8:9], v[10:11]
	v_lshlrev_b32_e32 v10, 16, v76
	v_pk_mul_f32 v[8:9], v[8:9], v[12:13]
	v_and_b32_e32 v11, 0xffff0000, v76
	v_cvt_pk_bf16_f32 v7, v8, v9
	v_add_co_u32_e32 v8, vcc, s88, v0
	v_lshlrev_b32_e32 v12, 16, v104
	s_nop 0
	v_addc_co_u32_e32 v9, vcc, 0, v1, vcc
	global_store_dwordx4 v[8:9], v[4:7], off nt
	global_load_dword v8, v[2:3], off offset:256
	ds_read_b128 v[4:7], v215 offset:33792
	v_and_b32_e32 v13, 0xffff0000, v104
	s_waitcnt lgkmcnt(0)
	v_cvt_f32_f16_e32 v14, v4
	v_cvt_f32_f16_sdwa v15, v4 dst_sel:DWORD dst_unused:UNUSED_PAD src0_sel:WORD_1
	s_waitcnt vmcnt(0)
	v_pk_add_f32 v[14:15], v[8:9], v[14:15] op_sel_hi:[0,1]
	v_pk_mul_f32 v[10:11], v[14:15], v[10:11]
	v_cvt_f32_f16_e32 v14, v5
	v_cvt_f32_f16_sdwa v15, v5 dst_sel:DWORD dst_unused:UNUSED_PAD src0_sel:WORD_1
	v_pk_mul_f32 v[10:11], v[10:11], v[12:13]
	v_lshlrev_b32_e32 v12, 16, v105
	v_cvt_pk_bf16_f32 v4, v10, v11
	v_lshlrev_b32_e32 v10, 16, v77
	v_and_b32_e32 v11, 0xffff0000, v77
	v_pk_add_f32 v[14:15], v[8:9], v[14:15] op_sel_hi:[0,1]
	v_pk_mul_f32 v[10:11], v[14:15], v[10:11]
	v_cvt_f32_f16_e32 v14, v6
	v_cvt_f32_f16_sdwa v15, v6 dst_sel:DWORD dst_unused:UNUSED_PAD src0_sel:WORD_1
	v_and_b32_e32 v13, 0xffff0000, v105
	v_pk_mul_f32 v[10:11], v[10:11], v[12:13]
	v_lshlrev_b32_e32 v12, 16, v106
	v_cvt_pk_bf16_f32 v5, v10, v11
	v_lshlrev_b32_e32 v10, 16, v78
	v_and_b32_e32 v11, 0xffff0000, v78
	v_pk_add_f32 v[14:15], v[8:9], v[14:15] op_sel_hi:[0,1]
	v_pk_mul_f32 v[10:11], v[14:15], v[10:11]
	v_cvt_f32_f16_e32 v14, v7
	v_cvt_f32_f16_sdwa v15, v7 dst_sel:DWORD dst_unused:UNUSED_PAD src0_sel:WORD_1
	v_and_b32_e32 v13, 0xffff0000, v106
	v_pk_mul_f32 v[10:11], v[10:11], v[12:13]
	v_lshlrev_b32_e32 v12, 16, v107
	v_cvt_pk_bf16_f32 v6, v10, v11
	v_lshlrev_b32_e32 v10, 16, v79
	v_and_b32_e32 v11, 0xffff0000, v79
	v_pk_add_f32 v[8:9], v[8:9], v[14:15] op_sel_hi:[0,1]
	v_and_b32_e32 v13, 0xffff0000, v107
	v_pk_mul_f32 v[8:9], v[8:9], v[10:11]
	v_lshlrev_b32_e32 v10, 16, v72
	v_pk_mul_f32 v[8:9], v[8:9], v[12:13]
	v_and_b32_e32 v11, 0xffff0000, v72
	v_cvt_pk_bf16_f32 v7, v8, v9
	v_add_co_u32_e32 v8, vcc, s89, v0
	v_lshlrev_b32_e32 v12, 16, v96
	s_nop 0
	v_addc_co_u32_e32 v9, vcc, 0, v1, vcc
	global_store_dwordx4 v[8:9], v[4:7], off nt
	global_load_dword v8, v[2:3], off offset:320
	ds_read_b128 v[4:7], v215 offset:42240
	v_and_b32_e32 v13, 0xffff0000, v96
	s_waitcnt lgkmcnt(0)
	v_cvt_f32_f16_e32 v14, v4
	v_cvt_f32_f16_sdwa v15, v4 dst_sel:DWORD dst_unused:UNUSED_PAD src0_sel:WORD_1
	s_waitcnt vmcnt(0)
	v_pk_add_f32 v[14:15], v[8:9], v[14:15] op_sel_hi:[0,1]
	v_pk_mul_f32 v[10:11], v[14:15], v[10:11]
	v_cvt_f32_f16_e32 v14, v5
	v_cvt_f32_f16_sdwa v15, v5 dst_sel:DWORD dst_unused:UNUSED_PAD src0_sel:WORD_1
	v_pk_mul_f32 v[10:11], v[10:11], v[12:13]
	v_lshlrev_b32_e32 v12, 16, v97
	v_cvt_pk_bf16_f32 v4, v10, v11
	v_lshlrev_b32_e32 v10, 16, v73
	v_and_b32_e32 v11, 0xffff0000, v73
	v_pk_add_f32 v[14:15], v[8:9], v[14:15] op_sel_hi:[0,1]
	v_pk_mul_f32 v[10:11], v[14:15], v[10:11]
	v_cvt_f32_f16_e32 v14, v6
	v_cvt_f32_f16_sdwa v15, v6 dst_sel:DWORD dst_unused:UNUSED_PAD src0_sel:WORD_1
	v_and_b32_e32 v13, 0xffff0000, v97
	v_pk_mul_f32 v[10:11], v[10:11], v[12:13]
	v_lshlrev_b32_e32 v12, 16, v98
	v_cvt_pk_bf16_f32 v5, v10, v11
	v_lshlrev_b32_e32 v10, 16, v74
	v_and_b32_e32 v11, 0xffff0000, v74
	v_pk_add_f32 v[14:15], v[8:9], v[14:15] op_sel_hi:[0,1]
	v_pk_mul_f32 v[10:11], v[14:15], v[10:11]
	v_cvt_f32_f16_e32 v14, v7
	v_cvt_f32_f16_sdwa v15, v7 dst_sel:DWORD dst_unused:UNUSED_PAD src0_sel:WORD_1
	v_and_b32_e32 v13, 0xffff0000, v98
	v_pk_mul_f32 v[10:11], v[10:11], v[12:13]
	v_lshlrev_b32_e32 v12, 16, v99
	v_cvt_pk_bf16_f32 v6, v10, v11
	v_lshlrev_b32_e32 v10, 16, v75
	v_and_b32_e32 v11, 0xffff0000, v75
	v_pk_add_f32 v[8:9], v[8:9], v[14:15] op_sel_hi:[0,1]
	v_and_b32_e32 v13, 0xffff0000, v99
	v_pk_mul_f32 v[8:9], v[8:9], v[10:11]
	v_lshlrev_b32_e32 v10, 16, v68
	v_pk_mul_f32 v[8:9], v[8:9], v[12:13]
	v_and_b32_e32 v11, 0xffff0000, v68
	v_cvt_pk_bf16_f32 v7, v8, v9
	v_add_co_u32_e32 v8, vcc, s73, v0
	v_lshlrev_b32_e32 v12, 16, v88
	s_nop 0
	v_addc_co_u32_e32 v9, vcc, 0, v1, vcc
	global_store_dwordx4 v[8:9], v[4:7], off nt
	global_load_dword v8, v[2:3], off offset:384
	ds_read_b128 v[4:7], v215 offset:50688
	v_and_b32_e32 v13, 0xffff0000, v88
	s_waitcnt lgkmcnt(0)
	v_cvt_f32_f16_e32 v14, v4
	v_cvt_f32_f16_sdwa v15, v4 dst_sel:DWORD dst_unused:UNUSED_PAD src0_sel:WORD_1
	s_waitcnt vmcnt(0)
	v_pk_add_f32 v[14:15], v[8:9], v[14:15] op_sel_hi:[0,1]
	v_pk_mul_f32 v[10:11], v[14:15], v[10:11]
	v_cvt_f32_f16_e32 v14, v5
	v_cvt_f32_f16_sdwa v15, v5 dst_sel:DWORD dst_unused:UNUSED_PAD src0_sel:WORD_1
	v_pk_mul_f32 v[10:11], v[10:11], v[12:13]
	v_lshlrev_b32_e32 v12, 16, v89
	v_cvt_pk_bf16_f32 v4, v10, v11
	v_lshlrev_b32_e32 v10, 16, v69
	v_and_b32_e32 v11, 0xffff0000, v69
	v_pk_add_f32 v[14:15], v[8:9], v[14:15] op_sel_hi:[0,1]
	v_pk_mul_f32 v[10:11], v[14:15], v[10:11]
	v_cvt_f32_f16_e32 v14, v6
	v_cvt_f32_f16_sdwa v15, v6 dst_sel:DWORD dst_unused:UNUSED_PAD src0_sel:WORD_1
	v_and_b32_e32 v13, 0xffff0000, v89
	v_pk_mul_f32 v[10:11], v[10:11], v[12:13]
	v_lshlrev_b32_e32 v12, 16, v90
	v_cvt_pk_bf16_f32 v5, v10, v11
	v_lshlrev_b32_e32 v10, 16, v70
	v_and_b32_e32 v11, 0xffff0000, v70
	v_pk_add_f32 v[14:15], v[8:9], v[14:15] op_sel_hi:[0,1]
	v_pk_mul_f32 v[10:11], v[14:15], v[10:11]
	v_cvt_f32_f16_e32 v14, v7
	v_cvt_f32_f16_sdwa v15, v7 dst_sel:DWORD dst_unused:UNUSED_PAD src0_sel:WORD_1
	v_and_b32_e32 v13, 0xffff0000, v90
	v_pk_mul_f32 v[10:11], v[10:11], v[12:13]
	v_lshlrev_b32_e32 v12, 16, v91
	v_cvt_pk_bf16_f32 v6, v10, v11
	v_lshlrev_b32_e32 v10, 16, v71
	v_and_b32_e32 v11, 0xffff0000, v71
	v_pk_add_f32 v[8:9], v[8:9], v[14:15] op_sel_hi:[0,1]
	v_and_b32_e32 v13, 0xffff0000, v91
	v_pk_mul_f32 v[8:9], v[8:9], v[10:11]
	v_lshlrev_b32_e32 v10, 16, v80
	v_pk_mul_f32 v[8:9], v[8:9], v[12:13]
	v_and_b32_e32 v11, 0xffff0000, v80
	v_cvt_pk_bf16_f32 v7, v8, v9
	v_add_co_u32_e32 v8, vcc, s90, v0
	s_nop 1
	v_addc_co_u32_e32 v9, vcc, 0, v1, vcc
	global_store_dwordx4 v[8:9], v[4:7], off nt
	global_load_dword v6, v[2:3], off offset:448
	ds_read_b128 v[2:5], v215 offset:59136
	v_lshlrev_b32_e32 v8, 16, v64
	v_and_b32_e32 v9, 0xffff0000, v64
	v_add_co_u32_e32 v0, vcc, 0x70000, v0
	s_waitcnt lgkmcnt(0)
	v_cvt_f32_f16_e32 v12, v2
	v_cvt_f32_f16_sdwa v13, v2 dst_sel:DWORD dst_unused:UNUSED_PAD src0_sel:WORD_1
	v_addc_co_u32_e32 v1, vcc, 0, v1, vcc
	s_waitcnt vmcnt(0)
	v_pk_add_f32 v[12:13], v[6:7], v[12:13] op_sel_hi:[0,1]
	v_pk_mul_f32 v[8:9], v[12:13], v[8:9]
	v_cvt_f32_f16_e32 v12, v3
	v_cvt_f32_f16_sdwa v13, v3 dst_sel:DWORD dst_unused:UNUSED_PAD src0_sel:WORD_1
	v_pk_mul_f32 v[8:9], v[8:9], v[10:11]
	v_lshlrev_b32_e32 v10, 16, v81
	v_cvt_pk_bf16_f32 v2, v8, v9
	v_lshlrev_b32_e32 v8, 16, v65
	v_and_b32_e32 v9, 0xffff0000, v65
	v_pk_add_f32 v[12:13], v[6:7], v[12:13] op_sel_hi:[0,1]
	v_pk_mul_f32 v[8:9], v[12:13], v[8:9]
	v_cvt_f32_f16_e32 v12, v4
	v_cvt_f32_f16_sdwa v13, v4 dst_sel:DWORD dst_unused:UNUSED_PAD src0_sel:WORD_1
	v_and_b32_e32 v11, 0xffff0000, v81
	v_pk_mul_f32 v[8:9], v[8:9], v[10:11]
	v_lshlrev_b32_e32 v10, 16, v82
	v_cvt_pk_bf16_f32 v3, v8, v9
	v_lshlrev_b32_e32 v8, 16, v66
	v_and_b32_e32 v9, 0xffff0000, v66
	v_pk_add_f32 v[12:13], v[6:7], v[12:13] op_sel_hi:[0,1]
	v_pk_mul_f32 v[8:9], v[12:13], v[8:9]
	v_cvt_f32_f16_e32 v12, v5
	v_cvt_f32_f16_sdwa v13, v5 dst_sel:DWORD dst_unused:UNUSED_PAD src0_sel:WORD_1
	v_and_b32_e32 v11, 0xffff0000, v82
	v_pk_mul_f32 v[8:9], v[8:9], v[10:11]
	v_lshlrev_b32_e32 v10, 16, v83
	v_cvt_pk_bf16_f32 v4, v8, v9
	v_lshlrev_b32_e32 v8, 16, v67
	v_and_b32_e32 v9, 0xffff0000, v67
	v_pk_add_f32 v[6:7], v[6:7], v[12:13] op_sel_hi:[0,1]
	v_and_b32_e32 v11, 0xffff0000, v83
	v_pk_mul_f32 v[6:7], v[6:7], v[8:9]
	s_nop 0
	v_pk_mul_f32 v[6:7], v[6:7], v[10:11]
	s_nop 0
	v_cvt_pk_bf16_f32 v5, v6, v7
	global_store_dwordx4 v[0:1], v[2:5], off nt

.LBB0_368:
	s_or_b64 exec, exec, s[60:61]
	v_add_co_u32_e32 v0, vcc, 0x2000, v128
	s_waitcnt vmcnt(0)
	v_lshlrev_b32_e32 v182, 16, v40
	v_addc_co_u32_e32 v1, vcc, 0, v129, vcc
	v_add_co_u32_e32 v2, vcc, 0x5000, v128
	v_and_b32_e32 v183, 0xffff0000, v40
	s_nop 0
	v_addc_co_u32_e32 v3, vcc, 0, v129, vcc
	global_load_dwordx4 v[86:89], v[0:1], off offset:2048
	global_load_dwordx4 v[62:65], v[2:3], off
	v_add_co_u32_e32 v0, vcc, 0x7000, v128
	v_lshlrev_b32_e32 v170, 16, v28
	s_nop 0
	v_addc_co_u32_e32 v1, vcc, 0, v129, vcc
	v_add_co_u32_e32 v4, vcc, 0xa000, v128
	v_and_b32_e32 v171, 0xffff0000, v28
	s_nop 0
	v_addc_co_u32_e32 v5, vcc, 0, v129, vcc
	v_add_co_u32_e32 v6, vcc, s66, v128
	v_lshlrev_b32_e32 v168, 16, v29
	s_nop 0
	v_addc_co_u32_e32 v7, vcc, 0, v129, vcc
	v_add_co_u32_e32 v12, vcc, s63, v128
	v_and_b32_e32 v169, 0xffff0000, v29
	s_nop 0
	v_addc_co_u32_e32 v13, vcc, 0, v129, vcc
	global_load_dwordx4 v[16:19], v[6:7], off offset:2048
	global_load_dwordx4 v[8:11], v[12:13], off
	v_add_co_u32_e32 v6, vcc, s64, v128
	global_load_dwordx4 v[118:121], v[128:129], off
	global_load_dwordx4 v[122:125], v[128:129], off offset:2048
	v_addc_co_u32_e32 v7, vcc, 0, v129, vcc
	v_add_co_u32_e32 v14, vcc, s65, v128
	global_load_dwordx4 v[50:53], v[0:1], off offset:2048
	global_load_dwordx4 v[70:73], v[2:3], off offset:2048
	v_addc_co_u32_e32 v15, vcc, 0, v129, vcc
	v_add_co_u32_e32 v0, vcc, s51, v128
	v_pk_add_f32 v[28:29], v[182:183], 0 op_sel_hi:[1,0]
	s_nop 0
	v_addc_co_u32_e32 v1, vcc, 0, v129, vcc
	v_pk_add_f32 v[28:29], v[28:29], v[170:171]
	v_lshlrev_b32_e32 v142, 16, v24
	v_and_b32_e32 v143, 0xffff0000, v24
	global_load_dwordx4 v[98:101], v[14:15], off
	global_load_dwordx4 v[54:57], v[0:1], off
	global_load_dwordx4 v[32:35], v[4:5], off
	global_load_dwordx4 v[36:39], v[4:5], off offset:2048
	v_add_co_u32_e32 v4, vcc, s67, v128
	v_pk_add_f32 v[28:29], v[28:29], v[142:143]
	v_lshlrev_b32_e32 v138, 16, v46
	v_and_b32_e32 v139, 0xffff0000, v46
	v_addc_co_u32_e32 v5, vcc, 0, v129, vcc
	v_pk_add_f32 v[28:29], v[28:29], v[138:139]
	v_lshlrev_b32_e32 v134, 16, v66
	v_and_b32_e32 v135, 0xffff0000, v66
	global_load_dwordx4 v[0:3], v[6:7], off offset:2048
	s_nop 0
	global_load_dwordx4 v[12:15], v[12:13], off offset:2048
	v_add_co_u32_e32 v6, vcc, s70, v128
	v_pk_add_f32 v[28:29], v[28:29], v[134:135]
	v_lshlrev_b32_e32 v130, 16, v58
	v_and_b32_e32 v131, 0xffff0000, v58
	v_addc_co_u32_e32 v7, vcc, 0, v129, vcc
	v_pk_add_f32 v[28:29], v[28:29], v[130:131]
	v_lshlrev_b32_e32 v128, 16, v78
	v_and_b32_e32 v129, 0xffff0000, v78
	v_lshlrev_b32_e32 v166, 16, v30
	v_and_b32_e32 v167, 0xffff0000, v30
	v_lshlrev_b32_e32 v146, 16, v31
	v_and_b32_e32 v147, 0xffff0000, v31
	v_pk_add_f32 v[28:29], v[28:29], v[128:129]
	v_lshlrev_b32_e32 v30, 16, v74
	v_and_b32_e32 v31, 0xffff0000, v74
	v_pk_add_f32 v[28:29], v[28:29], v[30:31]
	v_lshlrev_b32_e32 v30, 16, v94
	v_and_b32_e32 v31, 0xffff0000, v94
	v_lshlrev_b32_e32 v180, 16, v41
	v_and_b32_e32 v181, 0xffff0000, v41
	v_pk_add_f32 v[28:29], v[28:29], v[30:31]
	v_lshlrev_b32_e32 v30, 16, v90
	v_and_b32_e32 v31, 0xffff0000, v90
	v_pk_add_f32 v[184:185], v[28:29], v[30:31]
	v_pk_add_f32 v[28:29], v[180:181], 0 op_sel_hi:[1,0]
	v_lshlrev_b32_e32 v144, 16, v25
	v_pk_add_f32 v[28:29], v[28:29], v[168:169]
	v_and_b32_e32 v145, 0xffff0000, v25
	v_pk_add_f32 v[24:25], v[28:29], v[144:145]
	v_lshlrev_b32_e32 v140, 16, v47
	v_and_b32_e32 v141, 0xffff0000, v47
	v_pk_add_f32 v[24:25], v[24:25], v[140:141]
	v_lshlrev_b32_e32 v136, 16, v67
	v_and_b32_e32 v137, 0xffff0000, v67
	v_pk_add_f32 v[24:25], v[24:25], v[136:137]
	v_lshlrev_b32_e32 v132, 16, v59
	v_and_b32_e32 v133, 0xffff0000, v59
	v_pk_add_f32 v[24:25], v[24:25], v[132:133]
	v_lshlrev_b32_e32 v58, 16, v79
	v_and_b32_e32 v59, 0xffff0000, v79
	v_pk_add_f32 v[24:25], v[24:25], v[58:59]
	v_lshlrev_b32_e32 v28, 16, v75
	v_and_b32_e32 v29, 0xffff0000, v75
	v_pk_add_f32 v[24:25], v[24:25], v[28:29]
	v_lshlrev_b32_e32 v28, 16, v95
	v_and_b32_e32 v29, 0xffff0000, v95
	v_lshlrev_b32_e32 v178, 16, v42
	v_and_b32_e32 v179, 0xffff0000, v42
	v_pk_add_f32 v[24:25], v[24:25], v[28:29]
	v_lshlrev_b32_e32 v28, 16, v91
	v_and_b32_e32 v29, 0xffff0000, v91
	v_pk_add_f32 v[218:219], v[24:25], v[28:29]
	v_pk_add_f32 v[24:25], v[178:179], 0 op_sel_hi:[1,0]
	v_lshlrev_b32_e32 v94, 16, v26
	v_pk_add_f32 v[24:25], v[24:25], v[166:167]
	v_and_b32_e32 v95, 0xffff0000, v26
	v_pk_add_f32 v[24:25], v[24:25], v[94:95]
	v_lshlrev_b32_e32 v90, 16, v48
	v_and_b32_e32 v91, 0xffff0000, v48
	v_pk_add_f32 v[24:25], v[24:25], v[90:91]
	v_lshlrev_b32_e32 v78, 16, v68
	v_and_b32_e32 v79, 0xffff0000, v68
	v_pk_add_f32 v[24:25], v[24:25], v[78:79]
	v_lshlrev_b32_e32 v74, 16, v60
	v_and_b32_e32 v75, 0xffff0000, v60
	v_pk_add_f32 v[24:25], v[24:25], v[74:75]
	v_lshlrev_b32_e32 v66, 16, v80
	v_and_b32_e32 v67, 0xffff0000, v80
	v_pk_add_f32 v[24:25], v[24:25], v[66:67]
	v_lshlrev_b32_e32 v28, 16, v76
	v_and_b32_e32 v29, 0xffff0000, v76
	v_pk_add_f32 v[24:25], v[24:25], v[28:29]
	v_lshlrev_b32_e32 v28, 16, v96
	v_and_b32_e32 v29, 0xffff0000, v96
	v_lshlrev_b32_e32 v176, 16, v43
	v_and_b32_e32 v177, 0xffff0000, v43
	v_pk_add_f32 v[24:25], v[24:25], v[28:29]
	v_lshlrev_b32_e32 v28, 16, v92
	v_and_b32_e32 v29, 0xffff0000, v92
	v_pk_add_f32 v[220:221], v[24:25], v[28:29]
	v_pk_add_f32 v[24:25], v[176:177], 0 op_sel_hi:[1,0]
	global_load_dwordx4 v[20:23], v[4:5], off
	s_nop 0
	global_load_dwordx4 v[4:7], v[6:7], off
	v_pk_add_f32 v[172:173], v[24:25], v[146:147]
	v_lshlrev_b32_e32 v174, 16, v27
	v_and_b32_e32 v175, 0xffff0000, v27
	global_load_dwordx4 v[24:27], v[154:155], off offset:16
	global_load_dwordx4 v[40:43], v[154:155], off
	global_load_dwordx4 v[28:31], v[156:157], off offset:16
	global_load_dwordx4 v[44:47], v[156:157], off
	v_min_u32_e32 v165, 15, v217
	v_add_u32_e32 v165, 1, v165
	v_cvt_f32_ubyte0_e32 v165, v165
	v_pk_add_f32 v[222:223], v[172:173], v[174:175]
	v_lshlrev_b32_e32 v172, 16, v49
	v_and_b32_e32 v173, 0xffff0000, v49
	v_div_scale_f32 v190, s[6:7], v165, v165, 1.0
	v_pk_add_f32 v[48:49], v[222:223], v[172:173]
	v_lshlrev_b32_e32 v68, 16, v69
	v_and_b32_e32 v69, 0xffff0000, v69
	v_rcp_f32_e32 v228, v190
	v_pk_add_f32 v[48:49], v[48:49], v[68:69]
	v_lshlrev_b32_e32 v60, 16, v61
	v_and_b32_e32 v61, 0xffff0000, v61
	v_pk_add_f32 v[222:223], v[48:49], v[60:61]
	v_lshlrev_b32_e32 v48, 16, v81
	v_and_b32_e32 v49, 0xffff0000, v81
	v_pk_add_f32 v[80:81], v[222:223], v[48:49]
	v_lshlrev_b32_e32 v76, 16, v77
	v_and_b32_e32 v77, 0xffff0000, v77
	v_pk_add_f32 v[76:77], v[80:81], v[76:77]
	v_lshlrev_b32_e32 v80, 16, v97
	v_and_b32_e32 v81, 0xffff0000, v97
	v_fma_f32 v229, -v190, v228, 1.0
	v_pk_add_f32 v[76:77], v[76:77], v[80:81]
	v_lshlrev_b32_e32 v80, 16, v93
	v_and_b32_e32 v81, 0xffff0000, v93
	v_lshlrev_b32_e32 v96, 16, v112
	v_and_b32_e32 v97, 0xffff0000, v112
	v_fmac_f32_e32 v228, v229, v228
	v_div_scale_f32 v229, vcc, 1.0, v165, 1.0
	v_pk_add_f32 v[76:77], v[76:77], v[80:81]
	v_lshlrev_b32_e32 v80, 16, v110
	v_and_b32_e32 v81, 0xffff0000, v110
	v_lshlrev_b32_e32 v92, 16, v111
	v_and_b32_e32 v93, 0xffff0000, v111
	v_lshlrev_b32_e32 v110, 16, v113
	v_and_b32_e32 v111, 0xffff0000, v113
	v_lshlrev_b32_e32 v222, 16, v108
	v_and_b32_e32 v223, 0xffff0000, v108
	v_mul_f32_e32 v230, v229, v228
	v_pk_add_f32 v[96:97], v[220:221], v[96:97]
	v_lshlrev_b32_e32 v112, 16, v106
	v_and_b32_e32 v113, 0xffff0000, v106
	v_lshlrev_b32_e32 v106, 16, v107
	v_and_b32_e32 v107, 0xffff0000, v107
	v_lshlrev_b32_e32 v108, 16, v109
	v_and_b32_e32 v109, 0xffff0000, v109
	v_lshlrev_b32_e32 v226, 16, v116
	v_and_b32_e32 v227, 0xffff0000, v116
	v_fma_f32 v231, -v190, v230, v229
	v_pk_add_f32 v[80:81], v[184:185], v[80:81]
	v_pk_add_f32 v[92:93], v[218:219], v[92:93]
	v_pk_add_f32 v[96:97], v[96:97], v[222:223]
	v_pk_add_f32 v[76:77], v[76:77], v[110:111]
	v_lshlrev_b32_e32 v224, 16, v114
	v_and_b32_e32 v225, 0xffff0000, v114
	v_lshlrev_b32_e32 v114, 16, v115
	v_and_b32_e32 v115, 0xffff0000, v115
	v_lshlrev_b32_e32 v116, 16, v117
	v_and_b32_e32 v117, 0xffff0000, v117
	v_fmac_f32_e32 v230, v231, v228
	v_pk_add_f32 v[80:81], v[80:81], v[112:113]
	v_pk_add_f32 v[92:93], v[92:93], v[106:107]
	v_pk_add_f32 v[96:97], v[96:97], v[226:227]
	v_lshlrev_b32_e32 v106, 16, v84
	v_and_b32_e32 v107, 0xffff0000, v84
	v_pk_add_f32 v[76:77], v[76:77], v[108:109]
	v_fma_f32 v190, -v190, v230, v229
	v_pk_add_f32 v[80:81], v[80:81], v[224:225]
	v_lshlrev_b32_e32 v112, 16, v82
	v_and_b32_e32 v113, 0xffff0000, v82
	v_pk_add_f32 v[92:93], v[92:93], v[114:115]
	v_lshlrev_b32_e32 v82, 16, v83
	v_and_b32_e32 v83, 0xffff0000, v83
	v_pk_add_f32 v[96:97], v[96:97], v[106:107]
	v_lshlrev_b32_e32 v106, 16, v104
	v_and_b32_e32 v107, 0xffff0000, v104
	v_pk_add_f32 v[76:77], v[76:77], v[116:117]
	v_lshlrev_b32_e32 v84, 16, v85
	v_and_b32_e32 v85, 0xffff0000, v85
	v_div_fmas_f32 v190, v190, v228, v230
	v_pk_add_f32 v[80:81], v[80:81], v[112:113]
	v_lshlrev_b32_e32 v112, 16, v102
	v_and_b32_e32 v113, 0xffff0000, v102
	v_pk_add_f32 v[82:83], v[92:93], v[82:83]
	v_lshlrev_b32_e32 v92, 16, v103
	v_and_b32_e32 v93, 0xffff0000, v103
	v_pk_add_f32 v[96:97], v[96:97], v[106:107]
	s_waitcnt vmcnt(15)
	v_lshlrev_b32_e32 v106, 16, v120
	v_and_b32_e32 v107, 0xffff0000, v120
	v_pk_add_f32 v[76:77], v[76:77], v[84:85]
	v_lshlrev_b32_e32 v84, 16, v105
	v_and_b32_e32 v85, 0xffff0000, v105
	v_div_fixup_f32 v228, v190, v165, 1.0
	v_pk_add_f32 v[80:81], v[80:81], v[112:113]
	v_lshlrev_b32_e32 v112, 16, v118
	v_and_b32_e32 v113, 0xffff0000, v118
	v_pk_add_f32 v[82:83], v[82:83], v[92:93]
	v_lshlrev_b32_e32 v92, 16, v119
	v_and_b32_e32 v93, 0xffff0000, v119
	v_pk_add_f32 v[96:97], v[96:97], v[106:107]
	v_pk_add_f32 v[76:77], v[76:77], v[84:85]
	v_lshlrev_b32_e32 v84, 16, v121
	v_and_b32_e32 v85, 0xffff0000, v121
	v_pk_add_f32 v[184:185], v[80:81], v[112:113]
	v_pk_add_f32 v[102:103], v[82:83], v[92:93]
	v_pk_fma_f32 v[106:107], v[228:229], v[96:97], v[106:107] op_sel_hi:[0,1,1] neg_lo:[0,0,1] neg_hi:[0,0,1]
	v_pk_add_f32 v[76:77], v[76:77], v[84:85]
	v_pk_fma_f32 v[80:81], v[228:229], v[184:185], v[112:113] op_sel_hi:[0,1,1] neg_lo:[0,0,1] neg_hi:[0,0,1]
	v_pk_fma_f32 v[82:83], v[228:229], v[102:103], v[92:93] op_sel_hi:[0,1,1] neg_lo:[0,0,1] neg_hi:[0,0,1]
	s_waitcnt vmcnt(3)
	v_pk_add_f32 v[106:107], v[106:107], v[24:25]
	v_pk_fma_f32 v[84:85], v[228:229], v[76:77], v[84:85] op_sel_hi:[0,1,1] neg_lo:[0,0,1] neg_hi:[0,0,1]
	s_waitcnt vmcnt(2)
	v_pk_add_f32 v[80:81], v[80:81], v[40:41]
	v_pk_add_f32 v[82:83], v[82:83], v[42:43]
	v_lshlrev_b32_e32 v92, 16, v124
	v_and_b32_e32 v93, 0xffff0000, v124
	s_waitcnt vmcnt(1)
	v_pk_mul_f32 v[106:107], v[106:107], v[28:29]
	v_pk_add_f32 v[84:85], v[84:85], v[26:27]
	v_lshlrev_b32_e32 v230, 16, v122
	v_and_b32_e32 v231, 0xffff0000, v122
	s_waitcnt vmcnt(0)
	v_pk_mul_f32 v[80:81], v[80:81], v[44:45]
	v_lshlrev_b32_e32 v112, 16, v123
	v_and_b32_e32 v113, 0xffff0000, v123
	v_pk_mul_f32 v[82:83], v[82:83], v[46:47]
	v_pk_mul_f32 v[92:93], v[106:107], v[92:93]
	v_lshlrev_b32_e32 v106, 16, v125
	v_and_b32_e32 v107, 0xffff0000, v125
	v_pk_mul_f32 v[84:85], v[84:85], v[30:31]
	v_pk_mul_f32 v[80:81], v[80:81], v[230:231]
	v_pk_mul_f32 v[82:83], v[82:83], v[112:113]
	v_pk_mul_f32 v[84:85], v[84:85], v[106:107]
	v_cvt_pk_bf16_f32 v80, v80, v81
	v_cvt_pk_bf16_f32 v81, v82, v83
	v_cvt_pk_bf16_f32 v83, v84, v85
	v_min_u32_e32 v84, 14, v217
	v_add_u32_e32 v84, 2, v84
	v_cvt_pk_bf16_f32 v82, v92, v93
	v_cvt_f32_ubyte0_e32 v92, v84
	v_div_scale_f32 v93, s[6:7], v92, v92, 1.0
	v_rcp_f32_e32 v104, v93
	v_lshlrev_b64 v[84:85], 12, v[126:127]
	v_lshl_add_u64 v[84:85], v[162:163], 0, v[84:85]
	global_store_dwordx4 v[84:85], v[80:83], off offset:2048 nt
	v_pk_add_f32 v[84:85], v[184:185], v[182:183] neg_lo:[0,1] neg_hi:[0,1]
	v_pk_add_f32 v[96:97], v[96:97], v[178:179] neg_lo:[0,1] neg_hi:[0,1]
	v_fma_f32 v80, -v93, v104, 1.0
	v_fmac_f32_e32 v104, v80, v104
	v_div_scale_f32 v80, vcc, 1.0, v92, 1.0
	v_mul_f32_e32 v81, v80, v104
	v_fma_f32 v82, -v93, v81, v80
	v_fmac_f32_e32 v81, v82, v104
	v_fma_f32 v80, -v93, v81, v80
	v_div_fmas_f32 v80, v80, v104, v81
	v_div_fixup_f32 v80, v80, v92, 1.0
	v_lshlrev_b32_e32 v92, 16, v86
	v_and_b32_e32 v93, 0xffff0000, v86
	v_pk_add_f32 v[84:85], v[84:85], v[92:93]
	v_lshlrev_b32_e32 v82, 16, v98
	v_pk_fma_f32 v[92:93], v[80:81], v[84:85], v[92:93] op_sel_hi:[0,1,1] neg_lo:[0,0,1] neg_hi:[0,0,1]
	v_pk_add_f32 v[92:93], v[92:93], v[40:41]
	v_and_b32_e32 v83, 0xffff0000, v98
	v_pk_mul_f32 v[92:93], v[92:93], v[44:45]
	v_lshlrev_b32_e32 v86, 16, v87
	v_pk_mul_f32 v[82:83], v[92:93], v[82:83]
	v_lshlrev_b32_e32 v92, 16, v99
	v_and_b32_e32 v93, 0xffff0000, v99
	v_pk_add_f32 v[98:99], v[102:103], v[180:181] neg_lo:[0,1] neg_hi:[0,1]
	v_and_b32_e32 v87, 0xffff0000, v87
	v_pk_add_f32 v[98:99], v[98:99], v[86:87]
	v_lshlrev_b32_e32 v102, 16, v88
	v_and_b32_e32 v103, 0xffff0000, v88
	v_pk_add_f32 v[76:77], v[76:77], v[176:177] neg_lo:[0,1] neg_hi:[0,1]
	v_lshlrev_b32_e32 v88, 16, v89
	v_and_b32_e32 v89, 0xffff0000, v89
	v_pk_fma_f32 v[86:87], v[80:81], v[98:99], v[86:87] op_sel_hi:[0,1,1] neg_lo:[0,0,1] neg_hi:[0,0,1]
	v_pk_add_f32 v[96:97], v[96:97], v[102:103]
	v_pk_add_f32 v[76:77], v[76:77], v[88:89]
	v_pk_add_f32 v[86:87], v[86:87], v[42:43]
	v_pk_fma_f32 v[102:103], v[80:81], v[96:97], v[102:103] op_sel_hi:[0,1,1] neg_lo:[0,0,1] neg_hi:[0,0,1]
	v_pk_fma_f32 v[80:81], v[80:81], v[76:77], v[88:89] op_sel_hi:[0,1,1] neg_lo:[0,0,1] neg_hi:[0,0,1]
	v_pk_mul_f32 v[86:87], v[86:87], v[46:47]
	v_pk_add_f32 v[80:81], v[80:81], v[26:27]
	v_pk_mul_f32 v[86:87], v[86:87], v[92:93]
	v_lshlrev_b32_e32 v92, 16, v100
	v_and_b32_e32 v93, 0xffff0000, v100
	v_lshlrev_b32_e32 v100, 16, v101
	v_and_b32_e32 v101, 0xffff0000, v101
	v_pk_mul_f32 v[80:81], v[80:81], v[30:31]
	v_pk_add_f32 v[102:103], v[102:103], v[24:25]
	v_pk_mul_f32 v[88:89], v[80:81], v[100:101]
	v_cvt_pk_bf16_f32 v80, v82, v83
	v_cvt_pk_bf16_f32 v83, v88, v89
	v_min_u32_e32 v88, 13, v217
	v_add_u32_e32 v88, 3, v88
	v_pk_mul_f32 v[102:103], v[102:103], v[28:29]
	v_cvt_f32_ubyte0_e32 v88, v88
	v_pk_mul_f32 v[92:93], v[102:103], v[92:93]
	v_div_scale_f32 v89, s[6:7], v88, v88, 1.0
	v_cvt_pk_bf16_f32 v81, v86, v87
	v_cvt_pk_bf16_f32 v82, v92, v93
	v_add_u32_e32 v86, 0xffff8001, v150
	v_rcp_f32_e32 v92, v89
	v_ashrrev_i32_e32 v87, 31, v86
	v_lshlrev_b64 v[86:87], 12, v[86:87]
	v_lshl_add_u64 v[86:87], v[162:163], 0, v[86:87]
	global_store_dwordx4 v[86:87], v[80:83], off offset:2048 nt
	v_pk_add_f32 v[84:85], v[84:85], v[170:171] neg_lo:[0,1] neg_hi:[0,1]
	v_lshlrev_b32_e32 v86, 16, v62
	v_fma_f32 v80, -v89, v92, 1.0
	v_fmac_f32_e32 v92, v80, v92
	v_div_scale_f32 v80, vcc, 1.0, v88, 1.0
	v_mul_f32_e32 v81, v80, v92
	v_fma_f32 v82, -v89, v81, v80
	v_fmac_f32_e32 v81, v82, v92
	v_fma_f32 v80, -v89, v81, v80
	v_div_fmas_f32 v80, v80, v92, v81
	v_and_b32_e32 v87, 0xffff0000, v62
	v_div_fixup_f32 v80, v80, v88, 1.0
	v_pk_add_f32 v[84:85], v[84:85], v[86:87]
	v_lshlrev_b32_e32 v82, 16, v70
	v_pk_fma_f32 v[86:87], v[80:81], v[84:85], v[86:87] op_sel_hi:[0,1,1] neg_lo:[0,0,1] neg_hi:[0,0,1]
	v_pk_add_f32 v[86:87], v[86:87], v[40:41]
	v_and_b32_e32 v83, 0xffff0000, v70
	v_pk_mul_f32 v[86:87], v[86:87], v[44:45]
	v_lshlrev_b32_e32 v62, 16, v63
	v_pk_mul_f32 v[82:83], v[86:87], v[82:83]
	v_pk_add_f32 v[86:87], v[98:99], v[168:169] neg_lo:[0,1] neg_hi:[0,1]
	v_and_b32_e32 v63, 0xffff0000, v63
	v_pk_add_f32 v[86:87], v[86:87], v[62:63]
	v_pk_add_f32 v[88:89], v[96:97], v[166:167] neg_lo:[0,1] neg_hi:[0,1]
	v_lshlrev_b32_e32 v92, 16, v64
	v_and_b32_e32 v93, 0xffff0000, v64
	v_pk_fma_f32 v[62:63], v[80:81], v[86:87], v[62:63] op_sel_hi:[0,1,1] neg_lo:[0,0,1] neg_hi:[0,0,1]
	v_pk_add_f32 v[88:89], v[88:89], v[92:93]
	v_pk_add_f32 v[62:63], v[62:63], v[42:43]
	v_pk_fma_f32 v[92:93], v[80:81], v[88:89], v[92:93] op_sel_hi:[0,1,1] neg_lo:[0,0,1] neg_hi:[0,0,1]
	v_lshlrev_b32_e32 v70, 16, v71
	v_and_b32_e32 v71, 0xffff0000, v71
	v_pk_mul_f32 v[62:63], v[62:63], v[46:47]
	v_pk_add_f32 v[92:93], v[92:93], v[24:25]
	v_pk_mul_f32 v[70:71], v[62:63], v[70:71]
	v_lshlrev_b32_e32 v62, 16, v72
	v_and_b32_e32 v63, 0xffff0000, v72
	v_pk_mul_f32 v[92:93], v[92:93], v[28:29]
	v_lshlrev_b32_e32 v64, 16, v65
	v_pk_mul_f32 v[92:93], v[92:93], v[62:63]
	v_lshlrev_b32_e32 v62, 16, v73
	v_and_b32_e32 v63, 0xffff0000, v73
	v_pk_add_f32 v[72:73], v[76:77], v[146:147] neg_lo:[0,1] neg_hi:[0,1]
	v_and_b32_e32 v65, 0xffff0000, v65
	v_pk_add_f32 v[72:73], v[72:73], v[64:65]
	s_nop 0
	v_pk_fma_f32 v[64:65], v[80:81], v[72:73], v[64:65] op_sel_hi:[0,1,1] neg_lo:[0,0,1] neg_hi:[0,0,1]
	v_pk_add_f32 v[64:65], v[64:65], v[26:27]
	s_nop 0
	v_pk_mul_f32 v[64:65], v[64:65], v[30:31]
	s_nop 0
	v_pk_mul_f32 v[76:77], v[64:65], v[62:63]
	v_cvt_pk_bf16_f32 v63, v70, v71
	v_cvt_pk_bf16_f32 v65, v76, v77
	v_min_u32_e32 v76, 12, v217
	v_add_u32_e32 v76, 4, v76
	v_cvt_f32_ubyte0_e32 v76, v76
	v_div_scale_f32 v77, s[6:7], v76, v76, 1.0
	v_add_u32_e32 v70, 0xffff8002, v150
	v_rcp_f32_e32 v80, v77
	v_ashrrev_i32_e32 v71, 31, v70
	v_lshlrev_b64 v[70:71], 12, v[70:71]
	v_cvt_pk_bf16_f32 v62, v82, v83
	v_cvt_pk_bf16_f32 v64, v92, v93
	v_lshl_add_u64 v[70:71], v[162:163], 0, v[70:71]
	global_store_dwordx4 v[70:71], v[62:65], off offset:2048 nt
	v_pk_add_f32 v[70:71], v[84:85], v[142:143] neg_lo:[0,1] neg_hi:[0,1]
	v_lshlrev_b32_e32 v82, 16, v52
	v_fma_f32 v62, -v77, v80, 1.0
	v_fmac_f32_e32 v80, v62, v80
	v_div_scale_f32 v62, vcc, 1.0, v76, 1.0
	v_mul_f32_e32 v63, v62, v80
	v_fma_f32 v64, -v77, v63, v62
	v_fmac_f32_e32 v63, v64, v80
	v_fma_f32 v62, -v77, v63, v62
	v_div_fmas_f32 v62, v62, v80, v63
	v_div_fixup_f32 v62, v62, v76, 1.0
	v_lshlrev_b32_e32 v76, 16, v50
	v_and_b32_e32 v77, 0xffff0000, v50
	v_pk_add_f32 v[70:71], v[70:71], v[76:77]
	v_lshlrev_b32_e32 v64, 16, v54
	v_pk_fma_f32 v[76:77], v[62:63], v[70:71], v[76:77] op_sel_hi:[0,1,1] neg_lo:[0,0,1] neg_hi:[0,0,1]
	v_pk_add_f32 v[76:77], v[76:77], v[40:41]
	v_and_b32_e32 v65, 0xffff0000, v54
	v_pk_mul_f32 v[76:77], v[76:77], v[44:45]
	v_lshlrev_b32_e32 v50, 16, v51
	v_pk_mul_f32 v[64:65], v[76:77], v[64:65]
	v_pk_add_f32 v[76:77], v[86:87], v[144:145] neg_lo:[0,1] neg_hi:[0,1]
	v_and_b32_e32 v51, 0xffff0000, v51
	v_pk_add_f32 v[76:77], v[76:77], v[50:51]
	v_pk_add_f32 v[80:81], v[88:89], v[94:95] neg_lo:[0,1] neg_hi:[0,1]
	v_and_b32_e32 v83, 0xffff0000, v52
	v_pk_fma_f32 v[50:51], v[62:63], v[76:77], v[50:51] op_sel_hi:[0,1,1] neg_lo:[0,0,1] neg_hi:[0,0,1]
	v_pk_add_f32 v[80:81], v[80:81], v[82:83]
	v_pk_add_f32 v[50:51], v[50:51], v[42:43]
	v_pk_fma_f32 v[82:83], v[62:63], v[80:81], v[82:83] op_sel_hi:[0,1,1] neg_lo:[0,0,1] neg_hi:[0,0,1]
	v_lshlrev_b32_e32 v54, 16, v55
	v_and_b32_e32 v55, 0xffff0000, v55
	v_pk_mul_f32 v[50:51], v[50:51], v[46:47]
	v_pk_add_f32 v[82:83], v[82:83], v[24:25]
	v_pk_mul_f32 v[54:55], v[50:51], v[54:55]
	v_lshlrev_b32_e32 v50, 16, v56
	v_and_b32_e32 v51, 0xffff0000, v56
	v_pk_mul_f32 v[82:83], v[82:83], v[28:29]
	v_lshlrev_b32_e32 v52, 16, v53
	v_pk_mul_f32 v[82:83], v[82:83], v[50:51]
	v_lshlrev_b32_e32 v50, 16, v57
	v_and_b32_e32 v51, 0xffff0000, v57
	v_pk_add_f32 v[56:57], v[72:73], v[174:175] neg_lo:[0,1] neg_hi:[0,1]
	v_and_b32_e32 v53, 0xffff0000, v53
	v_pk_add_f32 v[56:57], v[56:57], v[52:53]
	s_nop 0
	v_pk_fma_f32 v[52:53], v[62:63], v[56:57], v[52:53] op_sel_hi:[0,1,1] neg_lo:[0,0,1] neg_hi:[0,0,1]
	v_pk_add_f32 v[52:53], v[52:53], v[26:27]
	s_nop 0
	v_pk_mul_f32 v[52:53], v[52:53], v[30:31]
	s_nop 0
	v_pk_mul_f32 v[62:63], v[52:53], v[50:51]
	v_cvt_pk_bf16_f32 v50, v64, v65
	v_cvt_pk_bf16_f32 v53, v62, v63
	v_min_u32_e32 v62, 11, v217
	v_add_u32_e32 v62, 5, v62
	v_cvt_f32_ubyte0_e32 v62, v62
	v_div_scale_f32 v63, s[6:7], v62, v62, 1.0
	v_cvt_pk_bf16_f32 v51, v54, v55
	v_add_u32_e32 v54, 0xffff8003, v150
	v_rcp_f32_e32 v64, v63
	v_ashrrev_i32_e32 v55, 31, v54
	v_lshlrev_b64 v[54:55], 12, v[54:55]
	v_cvt_pk_bf16_f32 v52, v82, v83
	v_lshl_add_u64 v[54:55], v[162:163], 0, v[54:55]
	global_store_dwordx4 v[54:55], v[50:53], off offset:2048 nt
	v_pk_add_f32 v[54:55], v[70:71], v[138:139] neg_lo:[0,1] neg_hi:[0,1]
	v_lshlrev_b32_e32 v70, 16, v34
	v_fma_f32 v50, -v63, v64, 1.0
	v_fmac_f32_e32 v64, v50, v64
	v_div_scale_f32 v50, vcc, 1.0, v62, 1.0
	v_mul_f32_e32 v51, v50, v64
	v_fma_f32 v52, -v63, v51, v50
	v_fmac_f32_e32 v51, v52, v64
	v_fma_f32 v50, -v63, v51, v50
	v_div_fmas_f32 v50, v50, v64, v51
	v_div_fixup_f32 v50, v50, v62, 1.0
	v_lshlrev_b32_e32 v62, 16, v32
	v_and_b32_e32 v63, 0xffff0000, v32
	v_pk_add_f32 v[54:55], v[54:55], v[62:63]
	v_lshlrev_b32_e32 v52, 16, v36
	v_pk_fma_f32 v[62:63], v[50:51], v[54:55], v[62:63] op_sel_hi:[0,1,1] neg_lo:[0,0,1] neg_hi:[0,0,1]
	v_pk_add_f32 v[62:63], v[62:63], v[40:41]
	v_and_b32_e32 v53, 0xffff0000, v36
	v_pk_mul_f32 v[62:63], v[62:63], v[44:45]
	v_lshlrev_b32_e32 v32, 16, v33
	v_pk_mul_f32 v[52:53], v[62:63], v[52:53]
	v_pk_add_f32 v[62:63], v[76:77], v[140:141] neg_lo:[0,1] neg_hi:[0,1]
	v_and_b32_e32 v33, 0xffff0000, v33
	v_pk_add_f32 v[62:63], v[62:63], v[32:33]
	v_pk_add_f32 v[64:65], v[80:81], v[90:91] neg_lo:[0,1] neg_hi:[0,1]
	v_and_b32_e32 v71, 0xffff0000, v34
	v_pk_fma_f32 v[32:33], v[50:51], v[62:63], v[32:33] op_sel_hi:[0,1,1] neg_lo:[0,0,1] neg_hi:[0,0,1]
	v_pk_add_f32 v[64:65], v[64:65], v[70:71]
	v_pk_add_f32 v[32:33], v[32:33], v[42:43]
	v_pk_fma_f32 v[70:71], v[50:51], v[64:65], v[70:71] op_sel_hi:[0,1,1] neg_lo:[0,0,1] neg_hi:[0,0,1]
	v_lshlrev_b32_e32 v36, 16, v37
	v_and_b32_e32 v37, 0xffff0000, v37
	v_pk_mul_f32 v[32:33], v[32:33], v[46:47]
	v_pk_add_f32 v[70:71], v[70:71], v[24:25]
	v_pk_mul_f32 v[36:37], v[32:33], v[36:37]
	v_lshlrev_b32_e32 v32, 16, v38
	v_and_b32_e32 v33, 0xffff0000, v38
	v_pk_mul_f32 v[70:71], v[70:71], v[28:29]
	v_lshlrev_b32_e32 v34, 16, v35
	v_pk_mul_f32 v[70:71], v[70:71], v[32:33]
	v_lshlrev_b32_e32 v32, 16, v39
	v_and_b32_e32 v33, 0xffff0000, v39
	v_pk_add_f32 v[38:39], v[56:57], v[172:173] neg_lo:[0,1] neg_hi:[0,1]
	v_and_b32_e32 v35, 0xffff0000, v35
	v_pk_add_f32 v[38:39], v[38:39], v[34:35]
	s_nop 0
	v_pk_fma_f32 v[34:35], v[50:51], v[38:39], v[34:35] op_sel_hi:[0,1,1] neg_lo:[0,0,1] neg_hi:[0,0,1]
	v_pk_add_f32 v[34:35], v[34:35], v[26:27]
	s_nop 0
	v_pk_mul_f32 v[34:35], v[34:35], v[30:31]
	s_nop 0
	v_pk_mul_f32 v[50:51], v[34:35], v[32:33]
	v_cvt_pk_bf16_f32 v32, v52, v53
	v_cvt_pk_bf16_f32 v35, v50, v51
	v_min_u32_e32 v50, 10, v217
	v_add_u32_e32 v50, 6, v50
	v_cvt_f32_ubyte0_e32 v50, v50
	v_div_scale_f32 v51, s[6:7], v50, v50, 1.0
	v_cvt_pk_bf16_f32 v33, v36, v37
	v_add_u32_e32 v36, 0xffff8004, v150
	v_rcp_f32_e32 v52, v51
	v_ashrrev_i32_e32 v37, 31, v36
	v_lshlrev_b64 v[36:37], 12, v[36:37]
	v_cvt_pk_bf16_f32 v34, v70, v71
	v_lshl_add_u64 v[36:37], v[162:163], 0, v[36:37]
	global_store_dwordx4 v[36:37], v[32:35], off offset:2048 nt
	v_pk_add_f32 v[36:37], v[54:55], v[134:135] neg_lo:[0,1] neg_hi:[0,1]
	v_lshlrev_b32_e32 v54, 16, v18
	v_fma_f32 v32, -v51, v52, 1.0
	v_fmac_f32_e32 v52, v32, v52
	v_div_scale_f32 v32, vcc, 1.0, v50, 1.0
	v_mul_f32_e32 v33, v32, v52
	v_fma_f32 v34, -v51, v33, v32
	v_fmac_f32_e32 v33, v34, v52
	v_fma_f32 v32, -v51, v33, v32
	v_div_fmas_f32 v32, v32, v52, v33
	v_div_fixup_f32 v32, v32, v50, 1.0
	v_lshlrev_b32_e32 v50, 16, v16
	v_and_b32_e32 v51, 0xffff0000, v16
	v_pk_add_f32 v[36:37], v[36:37], v[50:51]
	v_lshlrev_b32_e32 v34, 16, v20
	v_pk_fma_f32 v[50:51], v[32:33], v[36:37], v[50:51] op_sel_hi:[0,1,1] neg_lo:[0,0,1] neg_hi:[0,0,1]
	v_pk_add_f32 v[50:51], v[50:51], v[40:41]
	v_and_b32_e32 v35, 0xffff0000, v20
	v_pk_mul_f32 v[50:51], v[50:51], v[44:45]
	v_lshlrev_b32_e32 v16, 16, v17
	v_pk_mul_f32 v[34:35], v[50:51], v[34:35]
	v_pk_add_f32 v[50:51], v[62:63], v[136:137] neg_lo:[0,1] neg_hi:[0,1]
	v_and_b32_e32 v17, 0xffff0000, v17
	v_pk_add_f32 v[50:51], v[50:51], v[16:17]
	v_pk_add_f32 v[52:53], v[64:65], v[78:79] neg_lo:[0,1] neg_hi:[0,1]
	v_and_b32_e32 v55, 0xffff0000, v18
	v_pk_fma_f32 v[16:17], v[32:33], v[50:51], v[16:17] op_sel_hi:[0,1,1] neg_lo:[0,0,1] neg_hi:[0,0,1]
	v_pk_add_f32 v[52:53], v[52:53], v[54:55]
	v_pk_add_f32 v[16:17], v[16:17], v[42:43]
	v_pk_fma_f32 v[54:55], v[32:33], v[52:53], v[54:55] op_sel_hi:[0,1,1] neg_lo:[0,0,1] neg_hi:[0,0,1]
	v_lshlrev_b32_e32 v20, 16, v21
	v_and_b32_e32 v21, 0xffff0000, v21
	v_pk_mul_f32 v[16:17], v[16:17], v[46:47]
	v_pk_add_f32 v[54:55], v[54:55], v[24:25]
	v_pk_mul_f32 v[20:21], v[16:17], v[20:21]
	v_lshlrev_b32_e32 v16, 16, v22
	v_and_b32_e32 v17, 0xffff0000, v22
	v_pk_mul_f32 v[54:55], v[54:55], v[28:29]
	v_lshlrev_b32_e32 v18, 16, v19
	v_pk_mul_f32 v[54:55], v[54:55], v[16:17]
	v_lshlrev_b32_e32 v16, 16, v23
	v_and_b32_e32 v17, 0xffff0000, v23
	v_pk_add_f32 v[22:23], v[38:39], v[68:69] neg_lo:[0,1] neg_hi:[0,1]
	v_and_b32_e32 v19, 0xffff0000, v19
	v_pk_add_f32 v[22:23], v[22:23], v[18:19]
	s_nop 0
	v_pk_fma_f32 v[18:19], v[32:33], v[22:23], v[18:19] op_sel_hi:[0,1,1] neg_lo:[0,0,1] neg_hi:[0,0,1]
	v_pk_add_f32 v[18:19], v[18:19], v[26:27]
	s_nop 0
	v_pk_mul_f32 v[18:19], v[18:19], v[30:31]
	s_nop 0
	v_pk_mul_f32 v[32:33], v[18:19], v[16:17]
	v_cvt_pk_bf16_f32 v16, v34, v35
	v_cvt_pk_bf16_f32 v19, v32, v33
	v_min_u32_e32 v32, 9, v217
	v_add_u32_e32 v32, 7, v32
	v_cvt_f32_ubyte0_e32 v32, v32
	v_div_scale_f32 v33, s[6:7], v32, v32, 1.0
	v_cvt_pk_bf16_f32 v17, v20, v21
	v_add_u32_e32 v20, 0xffff8005, v150
	v_rcp_f32_e32 v34, v33
	v_ashrrev_i32_e32 v21, 31, v20
	v_lshlrev_b64 v[20:21], 12, v[20:21]
	v_cvt_pk_bf16_f32 v18, v54, v55
	v_lshl_add_u64 v[20:21], v[162:163], 0, v[20:21]
	global_store_dwordx4 v[20:21], v[16:19], off offset:2048 nt
	v_pk_add_f32 v[20:21], v[36:37], v[130:131] neg_lo:[0,1] neg_hi:[0,1]
	v_lshlrev_b32_e32 v36, 16, v10
	v_fma_f32 v16, -v33, v34, 1.0
	v_fmac_f32_e32 v34, v16, v34
	v_div_scale_f32 v16, vcc, 1.0, v32, 1.0
	v_mul_f32_e32 v17, v16, v34
	v_fma_f32 v18, -v33, v17, v16
	v_fmac_f32_e32 v17, v18, v34
	v_fma_f32 v16, -v33, v17, v16
	v_div_fmas_f32 v16, v16, v34, v17
	v_div_fixup_f32 v16, v16, v32, 1.0
	v_lshlrev_b32_e32 v32, 16, v8
	v_and_b32_e32 v33, 0xffff0000, v8
	v_pk_add_f32 v[20:21], v[20:21], v[32:33]
	v_lshlrev_b32_e32 v18, 16, v12
	v_pk_fma_f32 v[32:33], v[16:17], v[20:21], v[32:33] op_sel_hi:[0,1,1] neg_lo:[0,0,1] neg_hi:[0,0,1]
	v_pk_add_f32 v[32:33], v[32:33], v[40:41]
	v_and_b32_e32 v19, 0xffff0000, v12
	v_pk_mul_f32 v[32:33], v[32:33], v[44:45]
	v_lshlrev_b32_e32 v8, 16, v9
	v_pk_mul_f32 v[18:19], v[32:33], v[18:19]
	v_pk_add_f32 v[32:33], v[50:51], v[132:133] neg_lo:[0,1] neg_hi:[0,1]
	v_and_b32_e32 v9, 0xffff0000, v9
	v_pk_add_f32 v[32:33], v[32:33], v[8:9]
	v_pk_add_f32 v[34:35], v[52:53], v[74:75] neg_lo:[0,1] neg_hi:[0,1]
	v_and_b32_e32 v37, 0xffff0000, v10
	v_pk_fma_f32 v[8:9], v[16:17], v[32:33], v[8:9] op_sel_hi:[0,1,1] neg_lo:[0,0,1] neg_hi:[0,0,1]
	v_pk_add_f32 v[34:35], v[34:35], v[36:37]
	v_pk_add_f32 v[8:9], v[8:9], v[42:43]
	v_pk_fma_f32 v[36:37], v[16:17], v[34:35], v[36:37] op_sel_hi:[0,1,1] neg_lo:[0,0,1] neg_hi:[0,0,1]
	v_lshlrev_b32_e32 v12, 16, v13
	v_and_b32_e32 v13, 0xffff0000, v13
	v_pk_mul_f32 v[8:9], v[8:9], v[46:47]
	v_pk_add_f32 v[36:37], v[36:37], v[24:25]
	v_pk_mul_f32 v[12:13], v[8:9], v[12:13]
	v_lshlrev_b32_e32 v8, 16, v14
	v_and_b32_e32 v9, 0xffff0000, v14
	v_pk_mul_f32 v[36:37], v[36:37], v[28:29]
	v_lshlrev_b32_e32 v10, 16, v11
	v_pk_mul_f32 v[36:37], v[36:37], v[8:9]
	v_lshlrev_b32_e32 v8, 16, v15
	v_and_b32_e32 v9, 0xffff0000, v15
	v_pk_add_f32 v[14:15], v[22:23], v[60:61] neg_lo:[0,1] neg_hi:[0,1]
	v_and_b32_e32 v11, 0xffff0000, v11
	v_pk_add_f32 v[14:15], v[14:15], v[10:11]
	s_nop 0
	v_pk_fma_f32 v[10:11], v[16:17], v[14:15], v[10:11] op_sel_hi:[0,1,1] neg_lo:[0,0,1] neg_hi:[0,0,1]
	v_pk_add_f32 v[10:11], v[10:11], v[26:27]
	s_nop 0
	v_pk_mul_f32 v[10:11], v[10:11], v[30:31]
	s_nop 0
	v_pk_mul_f32 v[16:17], v[10:11], v[8:9]
	v_cvt_pk_bf16_f32 v8, v18, v19
	v_cvt_pk_bf16_f32 v11, v16, v17
	v_min_u32_e32 v16, 8, v217
	v_add_u32_e32 v16, 8, v16
	v_cvt_f32_ubyte0_e32 v16, v16
	v_div_scale_f32 v17, s[6:7], v16, v16, 1.0
	v_cvt_pk_bf16_f32 v9, v12, v13
	v_add_u32_e32 v12, 0xffff8006, v150
	v_rcp_f32_e32 v18, v17
	v_ashrrev_i32_e32 v13, 31, v12
	v_lshlrev_b64 v[12:13], 12, v[12:13]
	v_cvt_pk_bf16_f32 v10, v36, v37
	v_lshl_add_u64 v[12:13], v[162:163], 0, v[12:13]
	global_store_dwordx4 v[12:13], v[8:11], off offset:2048 nt
	v_pk_add_f32 v[12:13], v[20:21], v[128:129] neg_lo:[0,1] neg_hi:[0,1]
	s_nop 0
	v_fma_f32 v8, -v17, v18, 1.0
	v_fmac_f32_e32 v18, v8, v18
	v_div_scale_f32 v8, vcc, 1.0, v16, 1.0
	v_mul_f32_e32 v9, v8, v18
	v_fma_f32 v10, -v17, v9, v8
	v_fmac_f32_e32 v9, v10, v18
	v_fma_f32 v8, -v17, v9, v8
	v_div_fmas_f32 v8, v8, v18, v9
	v_div_fixup_f32 v8, v8, v16, 1.0
	v_lshlrev_b32_e32 v16, 16, v0
	v_and_b32_e32 v17, 0xffff0000, v0
	v_pk_add_f32 v[12:13], v[12:13], v[16:17]
	v_lshlrev_b32_e32 v10, 16, v4
	v_pk_fma_f32 v[12:13], v[8:9], v[12:13], v[16:17] op_sel_hi:[0,1,1] neg_lo:[0,0,1] neg_hi:[0,0,1]
	v_pk_add_f32 v[12:13], v[12:13], v[40:41]
	v_and_b32_e32 v11, 0xffff0000, v4
	v_pk_mul_f32 v[12:13], v[12:13], v[44:45]
	v_lshlrev_b32_e32 v0, 16, v1
	v_pk_mul_f32 v[10:11], v[12:13], v[10:11]
	v_pk_add_f32 v[12:13], v[32:33], v[58:59] neg_lo:[0,1] neg_hi:[0,1]
	v_and_b32_e32 v1, 0xffff0000, v1
	v_pk_add_f32 v[12:13], v[12:13], v[0:1]
	v_lshlrev_b32_e32 v16, 16, v2
	v_pk_fma_f32 v[0:1], v[8:9], v[12:13], v[0:1] op_sel_hi:[0,1,1] neg_lo:[0,0,1] neg_hi:[0,0,1]
	v_pk_add_f32 v[12:13], v[34:35], v[66:67] neg_lo:[0,1] neg_hi:[0,1]
	v_and_b32_e32 v17, 0xffff0000, v2
	v_pk_add_f32 v[12:13], v[12:13], v[16:17]
	v_pk_add_f32 v[0:1], v[0:1], v[42:43]
	v_pk_fma_f32 v[12:13], v[8:9], v[12:13], v[16:17] op_sel_hi:[0,1,1] neg_lo:[0,0,1] neg_hi:[0,0,1]
	v_lshlrev_b32_e32 v4, 16, v5
	v_and_b32_e32 v5, 0xffff0000, v5
	v_pk_mul_f32 v[0:1], v[0:1], v[46:47]
	v_pk_add_f32 v[12:13], v[12:13], v[24:25]
	v_pk_mul_f32 v[4:5], v[0:1], v[4:5]
	v_lshlrev_b32_e32 v0, 16, v6
	v_and_b32_e32 v1, 0xffff0000, v6
	v_pk_mul_f32 v[12:13], v[12:13], v[28:29]
	v_lshlrev_b32_e32 v2, 16, v3
	v_pk_mul_f32 v[12:13], v[12:13], v[0:1]
	v_lshlrev_b32_e32 v0, 16, v7
	v_and_b32_e32 v1, 0xffff0000, v7
	v_pk_add_f32 v[6:7], v[14:15], v[48:49] neg_lo:[0,1] neg_hi:[0,1]
	v_and_b32_e32 v3, 0xffff0000, v3
	v_pk_add_f32 v[6:7], v[6:7], v[2:3]
	s_nop 0
	v_pk_fma_f32 v[2:3], v[8:9], v[6:7], v[2:3] op_sel_hi:[0,1,1] neg_lo:[0,0,1] neg_hi:[0,0,1]
	v_pk_add_f32 v[2:3], v[2:3], v[26:27]
	s_nop 0
	v_pk_mul_f32 v[2:3], v[2:3], v[30:31]
	s_nop 0
	v_pk_mul_f32 v[6:7], v[2:3], v[0:1]
	v_cvt_pk_bf16_f32 v1, v4, v5
	v_add_u32_e32 v4, 0xffff8007, v150
	v_ashrrev_i32_e32 v5, 31, v4
	v_lshlrev_b64 v[4:5], 12, v[4:5]
	v_cvt_pk_bf16_f32 v0, v10, v11
	v_cvt_pk_bf16_f32 v2, v12, v13
	v_cvt_pk_bf16_f32 v3, v6, v7
	v_lshl_add_u64 v[4:5], v[162:163], 0, v[4:5]
	global_store_dwordx4 v[4:5], v[0:3], off offset:2048 nt

.LBB0_384:
	s_or_b64 exec, exec, s[60:61]
	v_add_co_u32_e32 v0, vcc, 0x2000, v128
	s_waitcnt vmcnt(0)
	v_lshlrev_b32_e32 v114, 16, v22
	v_addc_co_u32_e32 v1, vcc, 0, v129, vcc
	v_add_co_u32_e32 v2, vcc, 0x5000, v128
	v_and_b32_e32 v115, 0xffff0000, v22
	s_nop 0
	v_addc_co_u32_e32 v3, vcc, 0, v129, vcc
	global_load_dwordx4 v[72:75], v[0:1], off offset:2048
	global_load_dwordx4 v[60:63], v[2:3], off
	v_add_co_u32_e32 v0, vcc, 0x7000, v128
	v_lshlrev_b32_e32 v120, 16, v17
	s_nop 0
	v_addc_co_u32_e32 v1, vcc, 0, v129, vcc
	v_add_co_u32_e32 v4, vcc, 0xa000, v128
	v_and_b32_e32 v121, 0xffff0000, v17
	s_nop 0
	v_addc_co_u32_e32 v5, vcc, 0, v129, vcc
	v_add_co_u32_e32 v6, vcc, s66, v128
	v_lshlrev_b32_e32 v112, 16, v18
	s_nop 0
	v_addc_co_u32_e32 v7, vcc, 0, v129, vcc
	v_add_co_u32_e32 v12, vcc, s63, v128
	v_and_b32_e32 v113, 0xffff0000, v18
	s_nop 0
	v_addc_co_u32_e32 v13, vcc, 0, v129, vcc
	global_load_dwordx4 v[32:35], v[6:7], off offset:2048
	global_load_dwordx4 v[8:11], v[12:13], off
	global_load_dwordx4 v[136:139], v[128:129], off
	global_load_dwordx4 v[142:145], v[128:129], off offset:2048
	v_add_co_u32_e32 v6, vcc, s64, v128
	global_load_dwordx4 v[52:55], v[0:1], off offset:2048
	global_load_dwordx4 v[68:71], v[2:3], off offset:2048
	v_addc_co_u32_e32 v7, vcc, 0, v129, vcc
	v_add_co_u32_e32 v14, vcc, s65, v128
	v_lshlrev_b32_e32 v108, 16, v23
	s_nop 0
	v_addc_co_u32_e32 v15, vcc, 0, v129, vcc
	v_add_co_u32_e32 v0, vcc, s51, v128
	v_and_b32_e32 v109, 0xffff0000, v23
	s_nop 0
	v_addc_co_u32_e32 v1, vcc, 0, v129, vcc
	global_load_dwordx4 v[166:169], v[14:15], off
	global_load_dwordx4 v[56:59], v[0:1], off
	global_load_dwordx4 v[44:47], v[4:5], off
	global_load_dwordx4 v[48:51], v[4:5], off offset:2048
	v_add_co_u32_e32 v4, vcc, s67, v128
	global_load_dwordx4 v[0:3], v[6:7], off offset:2048
	s_nop 0
	global_load_dwordx4 v[12:15], v[12:13], off offset:2048
	v_addc_co_u32_e32 v5, vcc, 0, v129, vcc
	v_add_co_u32_e32 v6, vcc, s70, v128
	v_lshlrev_b32_e32 v128, 16, v16
	s_nop 0
	v_addc_co_u32_e32 v7, vcc, 0, v129, vcc
	v_and_b32_e32 v129, 0xffff0000, v16
	v_pk_add_f32 v[16:17], v[114:115], 0 op_sel_hi:[1,0]
	v_lshlrev_b32_e32 v106, 16, v19
	v_pk_add_f32 v[118:119], v[16:17], v[112:113]
	v_pk_add_f32 v[16:17], v[108:109], 0 op_sel_hi:[1,0]
	v_and_b32_e32 v107, 0xffff0000, v19
	v_pk_add_f32 v[110:111], v[16:17], v[106:107]
	v_min_u32_e32 v16, 7, v217
	v_add_u32_e32 v16, 1, v16
	v_cvt_f32_ubyte0_e32 v16, v16
	v_div_scale_f32 v17, s[0:1], v16, v16, 1.0
	v_rcp_f32_e32 v18, v17
	v_lshlrev_b32_e32 v122, 16, v21
	v_and_b32_e32 v123, 0xffff0000, v21
	v_lshlrev_b32_e32 v130, 16, v20
	v_fma_f32 v19, -v17, v18, 1.0
	v_and_b32_e32 v131, 0xffff0000, v20
	v_pk_add_f32 v[20:21], v[122:123], 0 op_sel_hi:[1,0]
	v_fmac_f32_e32 v18, v19, v18
	v_div_scale_f32 v19, vcc, 1.0, v16, 1.0
	v_pk_add_f32 v[124:125], v[20:21], v[120:121]
	v_mul_f32_e32 v20, v19, v18
	v_fma_f32 v21, -v17, v20, v19
	v_fmac_f32_e32 v20, v21, v18
	v_fma_f32 v17, -v17, v20, v19
	v_div_fmas_f32 v17, v17, v18, v20
	global_load_dwordx4 v[40:43], v[4:5], off
	s_nop 0
	global_load_dwordx4 v[4:7], v[6:7], off
	v_lshlrev_b32_e32 v104, 16, v24
	v_and_b32_e32 v105, 0xffff0000, v24
	v_lshlrev_b32_e32 v102, 16, v25
	v_and_b32_e32 v103, 0xffff0000, v25
	v_lshlrev_b32_e32 v100, 16, v26
	v_and_b32_e32 v101, 0xffff0000, v26
	v_lshlrev_b32_e32 v98, 16, v27
	v_and_b32_e32 v99, 0xffff0000, v27
	v_lshlrev_b32_e32 v96, 16, v28
	v_and_b32_e32 v97, 0xffff0000, v28
	v_lshlrev_b32_e32 v94, 16, v29
	v_and_b32_e32 v95, 0xffff0000, v29
	v_lshlrev_b32_e32 v92, 16, v30
	v_and_b32_e32 v93, 0xffff0000, v30
	v_lshlrev_b32_e32 v88, 16, v31
	v_and_b32_e32 v89, 0xffff0000, v31
	v_div_fixup_f32 v116, v17, v16, 1.0
	global_load_dwordx4 v[16:19], v[154:155], off offset:16
	global_load_dwordx4 v[24:27], v[154:155], off
	global_load_dwordx4 v[20:23], v[156:157], off offset:16
	global_load_dwordx4 v[28:31], v[156:157], off
	v_lshlrev_b32_e32 v86, 16, v66
	v_and_b32_e32 v87, 0xffff0000, v66
	v_lshlrev_b32_e32 v90, 16, v67
	v_and_b32_e32 v91, 0xffff0000, v67
	v_lshlrev_b32_e32 v66, 16, v79
	v_and_b32_e32 v67, 0xffff0000, v79
	v_min_u32_e32 v79, 6, v217
	v_add_u32_e32 v79, 2, v79
	s_waitcnt vmcnt(15)
	v_lshlrev_b32_e32 v140, 16, v138
	v_and_b32_e32 v141, 0xffff0000, v138
	v_cvt_f32_ubyte0_e32 v138, v79
	v_lshlrev_b32_e32 v170, 16, v136
	v_and_b32_e32 v171, 0xffff0000, v136
	v_lshlrev_b32_e32 v172, 16, v137
	v_and_b32_e32 v173, 0xffff0000, v137
	s_waitcnt vmcnt(14)
	v_lshlrev_b32_e32 v136, 16, v144
	v_and_b32_e32 v137, 0xffff0000, v144
	v_div_scale_f32 v144, s[0:1], v138, v138, 1.0
	v_lshlrev_b32_e32 v134, 16, v145
	v_and_b32_e32 v135, 0xffff0000, v145
	v_rcp_f32_e32 v145, v144
	v_pk_add_f32 v[80:81], v[130:131], 0 op_sel_hi:[1,0]
	v_lshlrev_b32_e32 v82, 16, v64
	v_pk_add_f32 v[132:133], v[80:81], v[128:129]
	v_and_b32_e32 v83, 0xffff0000, v64
	v_lshlrev_b32_e32 v80, 16, v76
	v_and_b32_e32 v81, 0xffff0000, v76
	v_lshlrev_b32_e32 v84, 16, v65
	v_and_b32_e32 v85, 0xffff0000, v65
	v_lshlrev_b32_e32 v64, 16, v77
	v_and_b32_e32 v65, 0xffff0000, v77
	v_lshlrev_b32_e32 v76, 16, v78
	v_and_b32_e32 v77, 0xffff0000, v78
	v_lshlrev_b32_e32 v78, 16, v139
	v_and_b32_e32 v79, 0xffff0000, v139
	v_fma_f32 v139, -v144, v145, 1.0
	v_fmac_f32_e32 v145, v139, v145
	v_div_scale_f32 v139, vcc, 1.0, v138, 1.0
	v_mul_f32_e32 v165, v139, v145
	v_fma_f32 v174, -v144, v165, v139
	v_fmac_f32_e32 v165, v174, v145
	v_fma_f32 v139, -v144, v165, v139
	v_div_fmas_f32 v139, v139, v145, v165
	v_div_fixup_f32 v138, v139, v138, 1.0
	v_min_u32_e32 v139, 5, v217
	v_add_u32_e32 v139, 3, v139
	v_cvt_f32_ubyte0_e32 v139, v139
	v_div_scale_f32 v165, s[0:1], v139, v139, 1.0
	v_rcp_f32_e32 v182, v165
	v_lshlrev_b32_e32 v220, 16, v61
	v_and_b32_e32 v221, 0xffff0000, v61
	v_min_u32_e32 v61, 4, v217
	v_fma_f32 v183, -v165, v182, 1.0
	v_fmac_f32_e32 v182, v183, v182
	v_div_scale_f32 v183, vcc, 1.0, v139, 1.0
	v_mul_f32_e32 v184, v183, v182
	v_fma_f32 v185, -v165, v184, v183
	v_fmac_f32_e32 v184, v185, v182
	v_add_u32_e32 v61, 4, v61
	v_fma_f32 v165, -v165, v184, v183
	v_lshlrev_b32_e32 v224, 16, v62
	v_and_b32_e32 v225, 0xffff0000, v62
	v_cvt_f32_ubyte0_e32 v62, v61
	v_div_fmas_f32 v165, v165, v182, v184
	v_lshlrev_b32_e32 v226, 16, v63
	v_and_b32_e32 v227, 0xffff0000, v63
	v_div_scale_f32 v63, s[0:1], v62, v62, 1.0
	v_div_fixup_f32 v182, v165, v139, 1.0
	v_rcp_f32_e32 v139, v63
	v_lshlrev_b32_e32 v218, 16, v60
	v_and_b32_e32 v219, 0xffff0000, v60
	v_add_u32_e32 v60, 0xffff8002, v150
	v_ashrrev_i32_e32 v61, 31, v60
	v_lshlrev_b64 v[60:61], 12, v[60:61]
	v_lshl_add_u64 v[228:229], v[162:163], 0, v[60:61]
	v_fma_f32 v60, -v63, v139, 1.0
	v_fmac_f32_e32 v139, v60, v139
	v_div_scale_f32 v60, vcc, 1.0, v62, 1.0
	v_mul_f32_e32 v61, v60, v139
	v_fma_f32 v165, -v63, v61, v60
	v_fmac_f32_e32 v61, v165, v139
	v_fma_f32 v60, -v63, v61, v60
	v_div_fmas_f32 v60, v60, v139, v61
	v_lshlrev_b32_e32 v232, 16, v36
	v_and_b32_e32 v233, 0xffff0000, v36
	v_div_fixup_f32 v230, v60, v62, 1.0
	v_pk_add_f32 v[60:61], v[132:133], v[232:233]
	v_lshlrev_b32_e32 v146, 16, v142
	v_pk_add_f32 v[60:61], v[60:61], v[104:105]
	v_and_b32_e32 v147, 0xffff0000, v142
	v_pk_add_f32 v[60:61], v[60:61], v[96:97]
	v_lshlrev_b32_e32 v174, 16, v72
	v_pk_add_f32 v[60:61], v[60:61], v[82:83]
	v_and_b32_e32 v175, 0xffff0000, v72
	v_pk_add_f32 v[60:61], v[60:61], v[80:81]
	s_waitcnt vmcnt(11)
	v_lshlrev_b32_e32 v144, 16, v166
	v_pk_add_f32 v[60:61], v[60:61], v[170:171]
	v_and_b32_e32 v145, 0xffff0000, v166
	v_pk_fma_f32 v[132:133], v[116:117], v[60:61], v[170:171] op_sel_hi:[0,1,1] neg_lo:[0,0,1] neg_hi:[0,0,1]
	s_waitcnt vmcnt(2)
	v_pk_add_f32 v[132:133], v[132:133], v[24:25]
	v_pk_add_f32 v[60:61], v[60:61], v[130:131] neg_lo:[0,1] neg_hi:[0,1]
	s_waitcnt vmcnt(0)
	v_pk_mul_f32 v[132:133], v[132:133], v[28:29]
	v_pk_add_f32 v[60:61], v[60:61], v[174:175]
	v_pk_mul_f32 v[132:133], v[132:133], v[146:147]
	v_pk_fma_f32 v[130:131], v[138:139], v[60:61], v[174:175] op_sel_hi:[0,1,1] neg_lo:[0,0,1] neg_hi:[0,0,1]
	v_cvt_pk_bf16_f32 v36, v132, v133
	v_lshlrev_b32_e32 v132, 16, v37
	v_and_b32_e32 v133, 0xffff0000, v37
	v_pk_add_f32 v[124:125], v[124:125], v[132:133]
	v_pk_add_f32 v[130:131], v[130:131], v[24:25]
	v_pk_add_f32 v[124:125], v[124:125], v[102:103]
	v_pk_mul_f32 v[130:131], v[130:131], v[28:29]
	v_pk_add_f32 v[124:125], v[124:125], v[94:95]
	v_pk_add_f32 v[60:61], v[60:61], v[128:129] neg_lo:[0,1] neg_hi:[0,1]
	v_pk_add_f32 v[124:125], v[124:125], v[84:85]
	v_lshlrev_b32_e32 v72, 16, v73
	v_pk_add_f32 v[124:125], v[124:125], v[64:65]
	v_and_b32_e32 v73, 0xffff0000, v73
	v_pk_add_f32 v[124:125], v[124:125], v[172:173]
	v_pk_mul_f32 v[130:131], v[130:131], v[144:145]
	v_pk_add_f32 v[128:129], v[60:61], v[218:219]
	v_pk_add_f32 v[122:123], v[124:125], v[122:123] neg_lo:[0,1] neg_hi:[0,1]
	v_lshlrev_b32_e32 v62, 16, v56
	v_and_b32_e32 v63, 0xffff0000, v56
	v_cvt_pk_bf16_f32 v56, v130, v131
	v_pk_fma_f32 v[60:61], v[182:183], v[128:129], v[218:219] op_sel_hi:[0,1,1] neg_lo:[0,0,1] neg_hi:[0,0,1]
	v_pk_add_f32 v[128:129], v[128:129], v[232:233] neg_lo:[0,1] neg_hi:[0,1]
	v_lshlrev_b32_e32 v130, 16, v52
	v_and_b32_e32 v131, 0xffff0000, v52
	v_pk_add_f32 v[122:123], v[122:123], v[72:73]
	v_pk_add_f32 v[128:129], v[128:129], v[130:131]
	v_pk_fma_f32 v[72:73], v[138:139], v[122:123], v[72:73] op_sel_hi:[0,1,1] neg_lo:[0,0,1] neg_hi:[0,0,1]
	v_pk_fma_f32 v[130:131], v[230:231], v[128:129], v[130:131] op_sel_hi:[0,1,1] neg_lo:[0,0,1] neg_hi:[0,0,1]
	v_pk_add_f32 v[72:73], v[72:73], v[26:27]
	v_lshlrev_b32_e32 v166, 16, v167
	v_and_b32_e32 v167, 0xffff0000, v167
	v_pk_add_f32 v[130:131], v[130:131], v[24:25]
	v_pk_mul_f32 v[72:73], v[72:73], v[30:31]
	v_pk_mul_f32 v[130:131], v[130:131], v[28:29]
	v_pk_mul_f32 v[72:73], v[72:73], v[166:167]
	v_pk_mul_f32 v[130:131], v[130:131], v[62:63]
	v_lshlrev_b32_e32 v62, 16, v57
	v_and_b32_e32 v63, 0xffff0000, v57
	v_cvt_pk_bf16_f32 v57, v72, v73
	v_pk_add_f32 v[72:73], v[122:123], v[120:121] neg_lo:[0,1] neg_hi:[0,1]
	v_pk_add_f32 v[60:61], v[60:61], v[24:25]
	v_pk_add_f32 v[72:73], v[72:73], v[220:221]
	v_lshlrev_b32_e32 v184, 16, v68
	v_pk_fma_f32 v[120:121], v[182:183], v[72:73], v[220:221] op_sel_hi:[0,1,1] neg_lo:[0,0,1] neg_hi:[0,0,1]
	v_pk_add_f32 v[120:121], v[120:121], v[26:27]
	v_and_b32_e32 v185, 0xffff0000, v68
	v_lshlrev_b32_e32 v68, 16, v69
	v_and_b32_e32 v69, 0xffff0000, v69
	v_pk_mul_f32 v[60:61], v[60:61], v[28:29]
	v_pk_mul_f32 v[120:121], v[120:121], v[30:31]
	v_pk_mul_f32 v[60:61], v[60:61], v[184:185]
	v_pk_mul_f32 v[68:69], v[120:121], v[68:69]
	v_cvt_pk_bf16_f32 v60, v60, v61
	v_cvt_pk_bf16_f32 v61, v68, v69
	v_pk_add_f32 v[68:69], v[72:73], v[132:133] neg_lo:[0,1] neg_hi:[0,1]
	v_lshlrev_b32_e32 v52, 16, v53
	v_and_b32_e32 v53, 0xffff0000, v53
	v_pk_add_f32 v[68:69], v[68:69], v[52:53]
	v_lshlrev_b32_e32 v120, 16, v38
	v_pk_fma_f32 v[52:53], v[230:231], v[68:69], v[52:53] op_sel_hi:[0,1,1] neg_lo:[0,0,1] neg_hi:[0,0,1]
	v_pk_add_f32 v[52:53], v[52:53], v[26:27]
	v_and_b32_e32 v121, 0xffff0000, v38
	v_pk_mul_f32 v[52:53], v[52:53], v[30:31]
	v_lshlrev_b32_e32 v178, 16, v74
	v_pk_mul_f32 v[52:53], v[52:53], v[62:63]
	v_pk_add_f32 v[62:63], v[118:119], v[120:121]
	v_and_b32_e32 v179, 0xffff0000, v74
	v_pk_add_f32 v[62:63], v[62:63], v[100:101]
	v_pk_fma_f32 v[144:145], v[116:117], v[124:125], v[172:173] op_sel_hi:[0,1,1] neg_lo:[0,0,1] neg_hi:[0,0,1]
	v_pk_add_f32 v[62:63], v[62:63], v[92:93]
	v_pk_add_f32 v[144:145], v[144:145], v[26:27]
	v_pk_add_f32 v[62:63], v[62:63], v[86:87]
	v_lshlrev_b32_e32 v142, 16, v143
	v_pk_add_f32 v[62:63], v[62:63], v[76:77]
	v_and_b32_e32 v143, 0xffff0000, v143
	v_pk_add_f32 v[62:63], v[62:63], v[140:141]
	v_pk_mul_f32 v[144:145], v[144:145], v[30:31]
	v_pk_fma_f32 v[118:119], v[116:117], v[62:63], v[140:141] op_sel_hi:[0,1,1] neg_lo:[0,0,1] neg_hi:[0,0,1]
	v_pk_add_f32 v[118:119], v[118:119], v[16:17]
	v_pk_add_f32 v[62:63], v[62:63], v[114:115] neg_lo:[0,1] neg_hi:[0,1]
	v_pk_mul_f32 v[118:119], v[118:119], v[20:21]
	v_pk_add_f32 v[62:63], v[62:63], v[178:179]
	v_pk_mul_f32 v[118:119], v[118:119], v[136:137]
	v_pk_fma_f32 v[114:115], v[138:139], v[62:63], v[178:179] op_sel_hi:[0,1,1] neg_lo:[0,0,1] neg_hi:[0,0,1]
	v_cvt_pk_bf16_f32 v38, v118, v119
	v_lshlrev_b32_e32 v118, 16, v39
	v_and_b32_e32 v119, 0xffff0000, v39
	v_pk_add_f32 v[110:111], v[110:111], v[118:119]
	v_lshlrev_b64 v[126:127], 12, v[126:127]
	v_pk_add_f32 v[110:111], v[110:111], v[98:99]
	v_pk_mul_f32 v[142:143], v[144:145], v[142:143]
	v_pk_add_f32 v[110:111], v[110:111], v[88:89]
	v_pk_add_f32 v[114:115], v[114:115], v[16:17]
	v_pk_add_f32 v[110:111], v[110:111], v[90:91]
	v_lshl_add_u64 v[126:127], v[162:163], 0, v[126:127]
	v_pk_add_f32 v[110:111], v[110:111], v[66:67]
	v_lshlrev_b32_e32 v176, 16, v168
	v_pk_add_f32 v[110:111], v[110:111], v[78:79]
	v_and_b32_e32 v177, 0xffff0000, v168
	v_pk_fma_f32 v[78:79], v[116:117], v[110:111], v[78:79] op_sel_hi:[0,1,1] neg_lo:[0,0,1] neg_hi:[0,0,1]
	v_pk_add_f32 v[78:79], v[78:79], v[18:19]
	v_cvt_pk_bf16_f32 v37, v142, v143
	v_pk_mul_f32 v[78:79], v[78:79], v[22:23]
	v_pk_mul_f32 v[114:115], v[114:115], v[20:21]
	v_pk_mul_f32 v[78:79], v[78:79], v[134:135]
	v_pk_add_f32 v[62:63], v[62:63], v[112:113] neg_lo:[0,1] neg_hi:[0,1]
	v_cvt_pk_bf16_f32 v39, v78, v79
	v_lshlrev_b32_e32 v74, 16, v75
	v_and_b32_e32 v75, 0xffff0000, v75
	v_pk_mul_f32 v[114:115], v[114:115], v[176:177]
	v_pk_add_f32 v[112:113], v[62:63], v[224:225]
	global_store_dwordx4 v[126:127], v[36:39], off offset:2048 nt
	v_lshlrev_b32_e32 v72, 16, v58
	v_and_b32_e32 v73, 0xffff0000, v58
	v_pk_add_f32 v[36:37], v[110:111], v[108:109] neg_lo:[0,1] neg_hi:[0,1]
	v_cvt_pk_bf16_f32 v58, v114, v115
	v_pk_fma_f32 v[62:63], v[182:183], v[112:113], v[224:225] op_sel_hi:[0,1,1] neg_lo:[0,0,1] neg_hi:[0,0,1]
	v_pk_add_f32 v[112:113], v[112:113], v[120:121] neg_lo:[0,1] neg_hi:[0,1]
	v_lshlrev_b32_e32 v114, 16, v54
	v_and_b32_e32 v115, 0xffff0000, v54
	v_pk_add_f32 v[36:37], v[36:37], v[74:75]
	v_pk_add_f32 v[112:113], v[112:113], v[114:115]
	v_pk_fma_f32 v[38:39], v[138:139], v[36:37], v[74:75] op_sel_hi:[0,1,1] neg_lo:[0,0,1] neg_hi:[0,0,1]
	v_pk_fma_f32 v[114:115], v[230:231], v[112:113], v[114:115] op_sel_hi:[0,1,1] neg_lo:[0,0,1] neg_hi:[0,0,1]
	v_pk_add_f32 v[38:39], v[38:39], v[18:19]
	v_lshlrev_b32_e32 v168, 16, v169
	v_and_b32_e32 v169, 0xffff0000, v169
	v_pk_add_f32 v[114:115], v[114:115], v[16:17]
	v_pk_mul_f32 v[38:39], v[38:39], v[22:23]
	v_pk_add_f32 v[36:37], v[36:37], v[106:107] neg_lo:[0,1] neg_hi:[0,1]
	v_pk_mul_f32 v[114:115], v[114:115], v[20:21]
	v_pk_mul_f32 v[38:39], v[38:39], v[168:169]
	v_pk_add_f32 v[36:37], v[36:37], v[226:227]
	v_pk_mul_f32 v[72:73], v[114:115], v[72:73]
	v_lshlrev_b32_e32 v114, 16, v59
	v_and_b32_e32 v115, 0xffff0000, v59
	v_cvt_pk_bf16_f32 v59, v38, v39
	v_pk_fma_f32 v[38:39], v[182:183], v[36:37], v[226:227] op_sel_hi:[0,1,1] neg_lo:[0,0,1] neg_hi:[0,0,1]
	v_pk_add_f32 v[62:63], v[62:63], v[16:17]
	v_pk_add_f32 v[38:39], v[38:39], v[18:19]
	v_lshlrev_b32_e32 v222, 16, v70
	v_and_b32_e32 v223, 0xffff0000, v70
	v_lshlrev_b32_e32 v70, 16, v71
	v_and_b32_e32 v71, 0xffff0000, v71
	v_pk_mul_f32 v[62:63], v[62:63], v[20:21]
	v_pk_mul_f32 v[38:39], v[38:39], v[22:23]
	v_pk_mul_f32 v[62:63], v[62:63], v[222:223]
	v_pk_mul_f32 v[38:39], v[38:39], v[70:71]
	v_cvt_pk_bf16_f32 v62, v62, v63
	v_cvt_pk_bf16_f32 v63, v38, v39
	v_pk_add_f32 v[36:37], v[36:37], v[118:119] neg_lo:[0,1] neg_hi:[0,1]
	v_lshlrev_b32_e32 v38, 16, v55
	v_and_b32_e32 v39, 0xffff0000, v55
	v_add_u32_e32 v180, 0xffff8001, v150
	v_pk_add_f32 v[54:55], v[36:37], v[38:39]
	v_ashrrev_i32_e32 v181, 31, v180
	v_pk_fma_f32 v[36:37], v[230:231], v[54:55], v[38:39] op_sel_hi:[0,1,1] neg_lo:[0,0,1] neg_hi:[0,0,1]
	v_lshlrev_b64 v[180:181], 12, v[180:181]
	v_pk_add_f32 v[36:37], v[36:37], v[18:19]
	v_lshl_add_u64 v[180:181], v[162:163], 0, v[180:181]
	v_pk_mul_f32 v[36:37], v[36:37], v[22:23]
	global_store_dwordx4 v[180:181], v[56:59], off offset:2048 nt
	v_cvt_pk_bf16_f32 v38, v72, v73
	global_store_dwordx4 v[228:229], v[60:63], off offset:2048 nt
	v_pk_mul_f32 v[56:57], v[36:37], v[114:115]
	v_cvt_pk_bf16_f32 v37, v52, v53
	v_cvt_pk_bf16_f32 v39, v56, v57
	v_min_u32_e32 v56, 3, v217
	v_add_u32_e32 v56, 5, v56
	v_cvt_f32_ubyte0_e32 v56, v56
	v_div_scale_f32 v57, s[0:1], v56, v56, 1.0
	v_add_u32_e32 v52, 0xffff8003, v150
	v_rcp_f32_e32 v58, v57
	v_ashrrev_i32_e32 v53, 31, v52
	v_lshlrev_b64 v[52:53], 12, v[52:53]
	v_cvt_pk_bf16_f32 v36, v130, v131
	v_lshl_add_u64 v[52:53], v[162:163], 0, v[52:53]
	global_store_dwordx4 v[52:53], v[36:39], off offset:2048 nt
	v_pk_add_f32 v[52:53], v[128:129], v[104:105] neg_lo:[0,1] neg_hi:[0,1]
	v_lshlrev_b32_e32 v60, 16, v46
	v_fma_f32 v36, -v57, v58, 1.0
	v_fmac_f32_e32 v58, v36, v58
	v_div_scale_f32 v36, vcc, 1.0, v56, 1.0
	v_mul_f32_e32 v37, v36, v58
	v_fma_f32 v38, -v57, v37, v36
	v_fmac_f32_e32 v37, v38, v58
	v_fma_f32 v36, -v57, v37, v36
	v_div_fmas_f32 v36, v36, v58, v37
	v_div_fixup_f32 v36, v36, v56, 1.0
	v_lshlrev_b32_e32 v56, 16, v44
	v_and_b32_e32 v57, 0xffff0000, v44
	v_pk_add_f32 v[52:53], v[52:53], v[56:57]
	v_lshlrev_b32_e32 v38, 16, v48
	v_pk_fma_f32 v[56:57], v[36:37], v[52:53], v[56:57] op_sel_hi:[0,1,1] neg_lo:[0,0,1] neg_hi:[0,0,1]
	v_pk_add_f32 v[56:57], v[56:57], v[24:25]
	v_and_b32_e32 v39, 0xffff0000, v48
	v_pk_mul_f32 v[56:57], v[56:57], v[28:29]
	v_lshlrev_b32_e32 v44, 16, v45
	v_pk_mul_f32 v[38:39], v[56:57], v[38:39]
	v_pk_add_f32 v[56:57], v[68:69], v[102:103] neg_lo:[0,1] neg_hi:[0,1]
	v_and_b32_e32 v45, 0xffff0000, v45
	v_pk_add_f32 v[56:57], v[56:57], v[44:45]
	v_pk_add_f32 v[58:59], v[112:113], v[100:101] neg_lo:[0,1] neg_hi:[0,1]
	v_and_b32_e32 v61, 0xffff0000, v46
	v_pk_add_f32 v[54:55], v[54:55], v[98:99] neg_lo:[0,1] neg_hi:[0,1]
	v_lshlrev_b32_e32 v46, 16, v47
	v_and_b32_e32 v47, 0xffff0000, v47
	v_pk_fma_f32 v[44:45], v[36:37], v[56:57], v[44:45] op_sel_hi:[0,1,1] neg_lo:[0,0,1] neg_hi:[0,0,1]
	v_pk_add_f32 v[58:59], v[58:59], v[60:61]
	v_pk_add_f32 v[54:55], v[54:55], v[46:47]
	v_pk_add_f32 v[44:45], v[44:45], v[26:27]
	v_pk_fma_f32 v[60:61], v[36:37], v[58:59], v[60:61] op_sel_hi:[0,1,1] neg_lo:[0,0,1] neg_hi:[0,0,1]
	v_pk_fma_f32 v[36:37], v[36:37], v[54:55], v[46:47] op_sel_hi:[0,1,1] neg_lo:[0,0,1] neg_hi:[0,0,1]
	v_lshlrev_b32_e32 v48, 16, v49
	v_and_b32_e32 v49, 0xffff0000, v49
	v_pk_mul_f32 v[44:45], v[44:45], v[30:31]
	v_pk_add_f32 v[36:37], v[36:37], v[18:19]
	v_pk_mul_f32 v[44:45], v[44:45], v[48:49]
	v_lshlrev_b32_e32 v48, 16, v50
	v_and_b32_e32 v49, 0xffff0000, v50
	v_lshlrev_b32_e32 v50, 16, v51
	v_and_b32_e32 v51, 0xffff0000, v51
	v_pk_mul_f32 v[36:37], v[36:37], v[22:23]
	v_pk_add_f32 v[60:61], v[60:61], v[16:17]
	v_pk_mul_f32 v[46:47], v[36:37], v[50:51]
	v_cvt_pk_bf16_f32 v36, v38, v39
	v_cvt_pk_bf16_f32 v39, v46, v47
	v_min_u32_e32 v46, 2, v217
	v_add_u32_e32 v46, 6, v46
	v_pk_mul_f32 v[60:61], v[60:61], v[20:21]
	v_cvt_f32_ubyte0_e32 v46, v46
	v_pk_mul_f32 v[48:49], v[60:61], v[48:49]
	v_div_scale_f32 v47, s[0:1], v46, v46, 1.0
	v_cvt_pk_bf16_f32 v37, v44, v45
	v_cvt_pk_bf16_f32 v38, v48, v49
	v_add_u32_e32 v44, 0xffff8004, v150
	v_rcp_f32_e32 v48, v47
	v_ashrrev_i32_e32 v45, 31, v44
	v_lshlrev_b64 v[44:45], 12, v[44:45]
	v_lshl_add_u64 v[44:45], v[162:163], 0, v[44:45]
	global_store_dwordx4 v[44:45], v[36:39], off offset:2048 nt
	v_pk_add_f32 v[44:45], v[52:53], v[96:97] neg_lo:[0,1] neg_hi:[0,1]
	v_lshlrev_b32_e32 v50, 16, v34
	v_fma_f32 v36, -v47, v48, 1.0
	v_fmac_f32_e32 v48, v36, v48
	v_div_scale_f32 v36, vcc, 1.0, v46, 1.0
	v_mul_f32_e32 v37, v36, v48
	v_fma_f32 v38, -v47, v37, v36
	v_fmac_f32_e32 v37, v38, v48
	v_fma_f32 v36, -v47, v37, v36
	v_div_fmas_f32 v36, v36, v48, v37
	v_div_fixup_f32 v36, v36, v46, 1.0
	v_lshlrev_b32_e32 v46, 16, v32
	v_and_b32_e32 v47, 0xffff0000, v32
	v_pk_add_f32 v[44:45], v[44:45], v[46:47]
	v_lshlrev_b32_e32 v38, 16, v40
	v_pk_fma_f32 v[46:47], v[36:37], v[44:45], v[46:47] op_sel_hi:[0,1,1] neg_lo:[0,0,1] neg_hi:[0,0,1]
	v_pk_add_f32 v[46:47], v[46:47], v[24:25]
	v_and_b32_e32 v39, 0xffff0000, v40
	v_pk_mul_f32 v[46:47], v[46:47], v[28:29]
	v_lshlrev_b32_e32 v32, 16, v33
	v_pk_mul_f32 v[38:39], v[46:47], v[38:39]
	v_pk_add_f32 v[46:47], v[56:57], v[94:95] neg_lo:[0,1] neg_hi:[0,1]
	v_and_b32_e32 v33, 0xffff0000, v33
	v_pk_add_f32 v[46:47], v[46:47], v[32:33]
	v_pk_add_f32 v[48:49], v[58:59], v[92:93] neg_lo:[0,1] neg_hi:[0,1]
	v_and_b32_e32 v51, 0xffff0000, v34
	v_pk_fma_f32 v[32:33], v[36:37], v[46:47], v[32:33] op_sel_hi:[0,1,1] neg_lo:[0,0,1] neg_hi:[0,0,1]
	v_pk_add_f32 v[48:49], v[48:49], v[50:51]
	v_pk_add_f32 v[32:33], v[32:33], v[26:27]
	v_pk_fma_f32 v[50:51], v[36:37], v[48:49], v[50:51] op_sel_hi:[0,1,1] neg_lo:[0,0,1] neg_hi:[0,0,1]
	v_lshlrev_b32_e32 v40, 16, v41
	v_and_b32_e32 v41, 0xffff0000, v41
	v_pk_mul_f32 v[32:33], v[32:33], v[30:31]
	v_pk_add_f32 v[50:51], v[50:51], v[16:17]
	v_pk_mul_f32 v[40:41], v[32:33], v[40:41]
	v_lshlrev_b32_e32 v32, 16, v42
	v_and_b32_e32 v33, 0xffff0000, v42
	v_pk_mul_f32 v[50:51], v[50:51], v[20:21]
	v_lshlrev_b32_e32 v34, 16, v35
	v_pk_mul_f32 v[50:51], v[50:51], v[32:33]
	v_lshlrev_b32_e32 v32, 16, v43
	v_and_b32_e32 v33, 0xffff0000, v43
	v_pk_add_f32 v[42:43], v[54:55], v[88:89] neg_lo:[0,1] neg_hi:[0,1]
	v_and_b32_e32 v35, 0xffff0000, v35
	v_pk_add_f32 v[42:43], v[42:43], v[34:35]
	s_nop 0
	v_pk_fma_f32 v[34:35], v[36:37], v[42:43], v[34:35] op_sel_hi:[0,1,1] neg_lo:[0,0,1] neg_hi:[0,0,1]
	v_pk_add_f32 v[34:35], v[34:35], v[18:19]
	s_nop 0
	v_pk_mul_f32 v[34:35], v[34:35], v[22:23]
	s_nop 0
	v_pk_mul_f32 v[36:37], v[34:35], v[32:33]
	v_cvt_pk_bf16_f32 v32, v38, v39
	v_div_scale_f32 v38, s[0:1], v117, v117, 1.0
	v_cvt_pk_bf16_f32 v35, v36, v37
	v_add_u32_e32 v36, 0xffff8005, v150
	v_rcp_f32_e32 v39, v38
	v_ashrrev_i32_e32 v37, 31, v36
	v_lshlrev_b64 v[36:37], 12, v[36:37]
	v_cvt_pk_bf16_f32 v33, v40, v41
	v_cvt_pk_bf16_f32 v34, v50, v51
	v_lshl_add_u64 v[36:37], v[162:163], 0, v[36:37]
	global_store_dwordx4 v[36:37], v[32:35], off offset:2048 nt
	v_pk_add_f32 v[36:37], v[44:45], v[82:83] neg_lo:[0,1] neg_hi:[0,1]
	v_pk_add_f32 v[40:41], v[48:49], v[86:87] neg_lo:[0,1] neg_hi:[0,1]
	v_fma_f32 v32, -v38, v39, 1.0
	v_fmac_f32_e32 v39, v32, v39
	v_div_scale_f32 v32, vcc, 1.0, v117, 1.0
	v_mul_f32_e32 v33, v32, v39
	v_fma_f32 v34, -v38, v33, v32
	v_fmac_f32_e32 v33, v34, v39
	v_fma_f32 v32, -v38, v33, v32
	v_div_fmas_f32 v32, v32, v39, v33
	v_lshlrev_b32_e32 v38, 16, v8
	v_and_b32_e32 v39, 0xffff0000, v8
	v_div_fixup_f32 v32, v32, v117, 1.0
	v_pk_add_f32 v[36:37], v[36:37], v[38:39]
	v_lshlrev_b32_e32 v34, 16, v12
	v_pk_fma_f32 v[38:39], v[32:33], v[36:37], v[38:39] op_sel_hi:[0,1,1] neg_lo:[0,0,1] neg_hi:[0,0,1]
	v_pk_add_f32 v[38:39], v[38:39], v[24:25]
	v_and_b32_e32 v35, 0xffff0000, v12
	v_pk_mul_f32 v[38:39], v[38:39], v[28:29]
	v_lshlrev_b32_e32 v8, 16, v9
	v_pk_mul_f32 v[34:35], v[38:39], v[34:35]
	v_pk_add_f32 v[38:39], v[46:47], v[84:85] neg_lo:[0,1] neg_hi:[0,1]
	v_and_b32_e32 v9, 0xffff0000, v9
	v_pk_add_f32 v[38:39], v[38:39], v[8:9]
	v_lshlrev_b32_e32 v44, 16, v10
	v_and_b32_e32 v45, 0xffff0000, v10
	v_pk_fma_f32 v[8:9], v[32:33], v[38:39], v[8:9] op_sel_hi:[0,1,1] neg_lo:[0,0,1] neg_hi:[0,0,1]
	v_pk_add_f32 v[40:41], v[40:41], v[44:45]
	v_pk_add_f32 v[8:9], v[8:9], v[26:27]
	v_pk_fma_f32 v[44:45], v[32:33], v[40:41], v[44:45] op_sel_hi:[0,1,1] neg_lo:[0,0,1] neg_hi:[0,0,1]
	v_lshlrev_b32_e32 v12, 16, v13
	v_and_b32_e32 v13, 0xffff0000, v13
	v_pk_mul_f32 v[8:9], v[8:9], v[30:31]
	v_pk_add_f32 v[44:45], v[44:45], v[16:17]
	v_pk_mul_f32 v[12:13], v[8:9], v[12:13]
	v_lshlrev_b32_e32 v8, 16, v14
	v_and_b32_e32 v9, 0xffff0000, v14
	v_pk_mul_f32 v[44:45], v[44:45], v[20:21]
	v_lshlrev_b32_e32 v10, 16, v11
	v_pk_mul_f32 v[44:45], v[44:45], v[8:9]
	v_lshlrev_b32_e32 v8, 16, v15
	v_and_b32_e32 v9, 0xffff0000, v15
	v_pk_add_f32 v[14:15], v[42:43], v[90:91] neg_lo:[0,1] neg_hi:[0,1]
	v_and_b32_e32 v11, 0xffff0000, v11
	v_pk_add_f32 v[14:15], v[14:15], v[10:11]
	s_nop 0
	v_pk_fma_f32 v[10:11], v[32:33], v[14:15], v[10:11] op_sel_hi:[0,1,1] neg_lo:[0,0,1] neg_hi:[0,0,1]
	v_pk_add_f32 v[10:11], v[10:11], v[18:19]
	s_nop 0
	v_pk_mul_f32 v[10:11], v[10:11], v[22:23]
	s_nop 0
	v_pk_mul_f32 v[32:33], v[10:11], v[8:9]
	v_cvt_pk_bf16_f32 v9, v12, v13
	v_add_u32_e32 v12, 0xffff8006, v150
	v_ashrrev_i32_e32 v13, 31, v12
	v_lshlrev_b64 v[12:13], 12, v[12:13]
	v_cvt_pk_bf16_f32 v8, v34, v35
	v_cvt_pk_bf16_f32 v10, v44, v45
	v_cvt_pk_bf16_f32 v11, v32, v33
	v_lshl_add_u64 v[12:13], v[162:163], 0, v[12:13]
	global_store_dwordx4 v[12:13], v[8:11], off offset:2048 nt
	v_lshlrev_b32_e32 v12, 16, v0
	v_and_b32_e32 v13, 0xffff0000, v0
	v_pk_add_f32 v[10:11], v[36:37], v[80:81] neg_lo:[0,1] neg_hi:[0,1]
	v_lshlrev_b32_e32 v8, 16, v4
	v_pk_add_f32 v[10:11], v[10:11], v[12:13]
	v_and_b32_e32 v9, 0xffff0000, v4
	v_pk_fma_f32 v[10:11], v[10:11], s[50:51], v[12:13] op_sel_hi:[1,0,1] neg_lo:[0,0,1] neg_hi:[0,0,1]
	v_lshlrev_b32_e32 v0, 16, v1
	v_pk_add_f32 v[10:11], v[10:11], v[24:25]
	v_and_b32_e32 v1, 0xffff0000, v1
	v_pk_mul_f32 v[10:11], v[10:11], v[28:29]
	v_lshlrev_b32_e32 v12, 16, v2
	v_pk_mul_f32 v[8:9], v[10:11], v[8:9]
	v_pk_add_f32 v[10:11], v[38:39], v[64:65] neg_lo:[0,1] neg_hi:[0,1]
	v_and_b32_e32 v13, 0xffff0000, v2
	v_pk_add_f32 v[10:11], v[10:11], v[0:1]
	v_lshlrev_b32_e32 v4, 16, v5
	v_pk_fma_f32 v[0:1], v[10:11], s[50:51], v[0:1] op_sel_hi:[1,0,1] neg_lo:[0,0,1] neg_hi:[0,0,1]
	v_pk_add_f32 v[10:11], v[40:41], v[76:77] neg_lo:[0,1] neg_hi:[0,1]
	v_pk_add_f32 v[0:1], v[0:1], v[26:27]
	v_pk_add_f32 v[10:11], v[10:11], v[12:13]
	v_and_b32_e32 v5, 0xffff0000, v5
	v_pk_fma_f32 v[10:11], v[10:11], s[50:51], v[12:13] op_sel_hi:[1,0,1] neg_lo:[0,0,1] neg_hi:[0,0,1]
	v_pk_mul_f32 v[0:1], v[0:1], v[30:31]
	v_pk_add_f32 v[10:11], v[10:11], v[16:17]
	v_pk_mul_f32 v[4:5], v[0:1], v[4:5]
	v_lshlrev_b32_e32 v0, 16, v6
	v_and_b32_e32 v1, 0xffff0000, v6
	v_pk_mul_f32 v[10:11], v[10:11], v[20:21]
	v_lshlrev_b32_e32 v2, 16, v3
	v_pk_mul_f32 v[10:11], v[10:11], v[0:1]
	v_lshlrev_b32_e32 v0, 16, v7
	v_and_b32_e32 v1, 0xffff0000, v7
	v_pk_add_f32 v[6:7], v[14:15], v[66:67] neg_lo:[0,1] neg_hi:[0,1]
	v_and_b32_e32 v3, 0xffff0000, v3
	v_pk_add_f32 v[6:7], v[6:7], v[2:3]
	s_nop 0
	v_pk_fma_f32 v[2:3], v[6:7], s[50:51], v[2:3] op_sel_hi:[1,0,1] neg_lo:[0,0,1] neg_hi:[0,0,1]
	s_nop 0
	v_pk_add_f32 v[2:3], v[2:3], v[18:19]
	s_nop 0
	v_pk_mul_f32 v[2:3], v[2:3], v[22:23]
	s_nop 0
	v_pk_mul_f32 v[6:7], v[2:3], v[0:1]
	v_cvt_pk_bf16_f32 v1, v4, v5
	v_add_u32_e32 v4, 0xffff8007, v150
	v_ashrrev_i32_e32 v5, 31, v4
	v_lshlrev_b64 v[4:5], 12, v[4:5]
	v_cvt_pk_bf16_f32 v0, v8, v9
	v_cvt_pk_bf16_f32 v2, v10, v11
	v_cvt_pk_bf16_f32 v3, v6, v7
	v_lshl_add_u64 v[4:5], v[162:163], 0, v[4:5]
	global_store_dwordx4 v[4:5], v[0:3], off offset:2048 nt

.LBB0_390:
	s_or_b64 exec, exec, s[56:57]
	v_add_co_u32_e32 v0, vcc, 0x2000, v128
	global_load_dwordx4 v[66:69], v[128:129], off
	global_load_dwordx4 v[70:73], v[128:129], off offset:2048
	v_addc_co_u32_e32 v1, vcc, 0, v129, vcc
	v_add_co_u32_e32 v16, vcc, 0x5000, v128
	v_div_scale_f32 v65, s[56:57], v64, v64, 1.0
	s_nop 0
	v_addc_co_u32_e32 v17, vcc, 0, v129, vcc
	global_load_dwordx4 v[74:77], v[0:1], off offset:2048
	global_load_dwordx4 v[48:51], v[16:17], off
	s_nop 0
	global_load_dwordx4 v[0:3], v[154:155], off offset:16
	global_load_dwordx4 v[8:11], v[154:155], off
	global_load_dwordx4 v[4:7], v[156:157], off offset:16
	global_load_dwordx4 v[12:15], v[156:157], off
	v_add_co_u32_e32 v18, vcc, 0x7000, v128
	v_rcp_f32_e32 v86, v65
	s_nop 0
	v_addc_co_u32_e32 v19, vcc, 0, v129, vcc
	v_add_co_u32_e32 v20, vcc, 0xa000, v128
	v_fma_f32 v87, -v65, v86, 1.0
	s_nop 0
	v_addc_co_u32_e32 v21, vcc, 0, v129, vcc
	v_add_co_u32_e32 v22, vcc, s66, v128
	v_fmac_f32_e32 v86, v87, v86
	s_nop 0
	v_addc_co_u32_e32 v23, vcc, 0, v129, vcc
	v_add_co_u32_e32 v28, vcc, s63, v128
	s_waitcnt vmcnt(8)
	v_lshlrev_b32_e32 v98, 16, v62
	v_addc_co_u32_e32 v29, vcc, 0, v129, vcc
	global_load_dwordx4 v[32:35], v[22:23], off offset:2048
	global_load_dwordx4 v[24:27], v[28:29], off
	v_add_co_u32_e32 v22, vcc, s64, v128
	global_load_dwordx4 v[52:55], v[18:19], off offset:2048
	global_load_dwordx4 v[78:81], v[16:17], off offset:2048
	v_addc_co_u32_e32 v23, vcc, 0, v129, vcc
	v_add_co_u32_e32 v30, vcc, s65, v128
	v_and_b32_e32 v99, 0xffff0000, v62
	s_nop 0
	v_addc_co_u32_e32 v31, vcc, 0, v129, vcc
	v_add_co_u32_e32 v16, vcc, s51, v128
	v_pk_add_f32 v[100:101], v[98:99], 0 op_sel_hi:[1,0]
	s_nop 0
	v_addc_co_u32_e32 v17, vcc, 0, v129, vcc
	global_load_dwordx4 v[82:85], v[30:31], off
	global_load_dwordx4 v[56:59], v[16:17], off
	global_load_dwordx4 v[40:43], v[20:21], off
	global_load_dwordx4 v[44:47], v[20:21], off offset:2048
	v_add_co_u32_e32 v20, vcc, s67, v128
	global_load_dwordx4 v[16:19], v[22:23], off offset:2048
	s_nop 0
	global_load_dwordx4 v[28:31], v[28:29], off offset:2048
	v_addc_co_u32_e32 v21, vcc, 0, v129, vcc
	v_add_co_u32_e32 v22, vcc, s70, v128
	s_waitcnt vmcnt(17)
	v_lshlrev_b32_e32 v92, 16, v66
	v_addc_co_u32_e32 v23, vcc, 0, v129, vcc
	v_div_scale_f32 v87, vcc, 1.0, v64, 1.0
	v_mul_f32_e32 v88, v87, v86
	v_fma_f32 v89, -v65, v88, v87
	v_fmac_f32_e32 v88, v89, v86
	v_fma_f32 v65, -v65, v88, v87
	v_div_fmas_f32 v65, v65, v86, v88
	v_lshlrev_b32_e32 v88, 16, v60
	v_and_b32_e32 v89, 0xffff0000, v60
	v_pk_add_f32 v[90:91], v[88:89], 0 op_sel_hi:[1,0]
	v_and_b32_e32 v93, 0xffff0000, v66
	v_div_fixup_f32 v64, v65, v64, 1.0
	v_pk_add_f32 v[90:91], v[90:91], v[92:93]
	s_waitcnt vmcnt(16)
	v_lshlrev_b32_e32 v86, 16, v70
	v_pk_fma_f32 v[94:95], v[64:65], v[90:91], v[92:93] op_sel_hi:[0,1,1] neg_lo:[0,0,1] neg_hi:[0,0,1]
	s_waitcnt vmcnt(12)
	v_pk_add_f32 v[94:95], v[94:95], v[8:9]
	v_and_b32_e32 v87, 0xffff0000, v70
	s_waitcnt vmcnt(10)
	v_pk_mul_f32 v[94:95], v[94:95], v[12:13]
	v_lshlrev_b32_e32 v66, 16, v67
	v_pk_mul_f32 v[86:87], v[94:95], v[86:87]
	v_lshlrev_b32_e32 v94, 16, v61
	v_and_b32_e32 v95, 0xffff0000, v61
	v_pk_add_f32 v[60:61], v[94:95], 0 op_sel_hi:[1,0]
	v_and_b32_e32 v67, 0xffff0000, v67
	v_pk_add_f32 v[96:97], v[60:61], v[66:67]
	v_lshlrev_b32_e32 v102, 16, v68
	v_and_b32_e32 v103, 0xffff0000, v68
	v_pk_fma_f32 v[60:61], v[64:65], v[96:97], v[66:67] op_sel_hi:[0,1,1] neg_lo:[0,0,1] neg_hi:[0,0,1]
	v_pk_add_f32 v[100:101], v[100:101], v[102:103]
	v_pk_add_f32 v[60:61], v[60:61], v[10:11]
	v_pk_fma_f32 v[104:105], v[64:65], v[100:101], v[102:103] op_sel_hi:[0,1,1] neg_lo:[0,0,1] neg_hi:[0,0,1]
	v_lshlrev_b32_e32 v70, 16, v71
	v_and_b32_e32 v71, 0xffff0000, v71
	v_pk_mul_f32 v[60:61], v[60:61], v[14:15]
	v_pk_add_f32 v[104:105], v[104:105], v[0:1]
	v_pk_mul_f32 v[70:71], v[60:61], v[70:71]
	v_lshlrev_b32_e32 v60, 16, v72
	v_and_b32_e32 v61, 0xffff0000, v72
	v_pk_mul_f32 v[104:105], v[104:105], v[4:5]
	v_lshlrev_b32_e32 v72, 16, v63
	v_pk_mul_f32 v[104:105], v[104:105], v[60:61]
	v_lshlrev_b32_e32 v60, 16, v73
	v_and_b32_e32 v61, 0xffff0000, v73
	v_and_b32_e32 v73, 0xffff0000, v63
	v_pk_add_f32 v[62:63], v[72:73], 0 op_sel_hi:[1,0]
	v_lshlrev_b32_e32 v68, 16, v69
	v_and_b32_e32 v69, 0xffff0000, v69
	v_pk_add_f32 v[106:107], v[62:63], v[68:69]
	global_load_dwordx4 v[36:39], v[20:21], off
	s_nop 0
	global_load_dwordx4 v[20:23], v[22:23], off
	v_pk_fma_f32 v[62:63], v[64:65], v[106:107], v[68:69] op_sel_hi:[0,1,1] neg_lo:[0,0,1] neg_hi:[0,0,1]
	v_pk_add_f32 v[62:63], v[62:63], v[2:3]
	v_pk_add_f32 v[72:73], v[106:107], v[72:73] neg_lo:[0,1] neg_hi:[0,1]
	v_pk_mul_f32 v[62:63], v[62:63], v[6:7]
	s_nop 0
	v_pk_mul_f32 v[64:65], v[62:63], v[60:61]
	v_cvt_pk_bf16_f32 v60, v86, v87
	v_cvt_pk_bf16_f32 v63, v64, v65
	v_lshlrev_b64 v[64:65], 12, v[126:127]
	v_cvt_pk_bf16_f32 v61, v70, v71
	v_cvt_pk_bf16_f32 v62, v104, v105
	v_lshl_add_u64 v[64:65], v[162:163], 0, v[64:65]
	global_store_dwordx4 v[64:65], v[60:63], off offset:2048 nt
	v_lshlrev_b32_e32 v64, 16, v74
	v_and_b32_e32 v65, 0xffff0000, v74
	v_pk_add_f32 v[62:63], v[90:91], v[88:89] neg_lo:[0,1] neg_hi:[0,1]
	s_waitcnt vmcnt(8)
	v_lshlrev_b32_e32 v60, 16, v82
	v_pk_add_f32 v[70:71], v[62:63], v[64:65]
	v_and_b32_e32 v61, 0xffff0000, v82
	v_pk_fma_f32 v[62:63], v[70:71], 0.5, v[64:65] op_sel_hi:[1,0,1] neg_lo:[0,0,1] neg_hi:[0,0,1]
	v_lshlrev_b32_e32 v74, 16, v75
	v_pk_add_f32 v[62:63], v[62:63], v[8:9]
	v_and_b32_e32 v75, 0xffff0000, v75
	v_pk_mul_f32 v[62:63], v[62:63], v[12:13]
	v_pk_add_f32 v[88:89], v[100:101], v[98:99] neg_lo:[0,1] neg_hi:[0,1]
	v_pk_mul_f32 v[60:61], v[62:63], v[60:61]
	v_lshlrev_b32_e32 v62, 16, v83
	v_and_b32_e32 v63, 0xffff0000, v83
	v_pk_add_f32 v[82:83], v[96:97], v[94:95] neg_lo:[0,1] neg_hi:[0,1]
	v_lshlrev_b32_e32 v90, 16, v76
	v_pk_add_f32 v[82:83], v[82:83], v[74:75]
	v_and_b32_e32 v91, 0xffff0000, v76
	v_pk_fma_f32 v[86:87], v[82:83], 0.5, v[74:75] op_sel_hi:[1,0,1] neg_lo:[0,0,1] neg_hi:[0,0,1]
	v_pk_add_f32 v[88:89], v[88:89], v[90:91]
	v_pk_add_f32 v[86:87], v[86:87], v[10:11]
	v_pk_fma_f32 v[94:95], v[88:89], 0.5, v[90:91] op_sel_hi:[1,0,1] neg_lo:[0,0,1] neg_hi:[0,0,1]
	v_pk_mul_f32 v[86:87], v[86:87], v[14:15]
	v_pk_add_f32 v[94:95], v[94:95], v[0:1]
	v_lshlrev_b32_e32 v76, 16, v77
	v_and_b32_e32 v77, 0xffff0000, v77
	v_pk_mul_f32 v[62:63], v[86:87], v[62:63]
	v_lshlrev_b32_e32 v86, 16, v84
	v_and_b32_e32 v87, 0xffff0000, v84
	v_pk_mul_f32 v[94:95], v[94:95], v[4:5]
	v_pk_add_f32 v[72:73], v[72:73], v[76:77]
	v_pk_mul_f32 v[86:87], v[94:95], v[86:87]
	v_pk_fma_f32 v[94:95], v[72:73], 0.5, v[76:77] op_sel_hi:[1,0,1] neg_lo:[0,0,1] neg_hi:[0,0,1]
	v_lshlrev_b32_e32 v84, 16, v85
	v_pk_add_f32 v[94:95], v[94:95], v[2:3]
	v_and_b32_e32 v85, 0xffff0000, v85
	v_pk_mul_f32 v[94:95], v[94:95], v[6:7]
	v_cvt_pk_bf16_f32 v60, v60, v61
	v_pk_mul_f32 v[84:85], v[94:95], v[84:85]
	v_cvt_pk_bf16_f32 v61, v62, v63
	v_cvt_pk_bf16_f32 v63, v84, v85
	v_add_u32_e32 v84, 0xffff8001, v150
	v_ashrrev_i32_e32 v85, 31, v84
	v_lshlrev_b64 v[84:85], 12, v[84:85]
	v_cvt_pk_bf16_f32 v62, v86, v87
	v_lshl_add_u64 v[84:85], v[162:163], 0, v[84:85]
	global_store_dwordx4 v[84:85], v[60:63], off offset:2048 nt
	v_pk_add_f32 v[66:67], v[82:83], v[66:67] neg_lo:[0,1] neg_hi:[0,1]
	v_lshlrev_b32_e32 v82, 16, v49
	v_pk_add_f32 v[62:63], v[70:71], v[92:93] neg_lo:[0,1] neg_hi:[0,1]
	v_lshlrev_b32_e32 v70, 16, v48
	v_and_b32_e32 v71, 0xffff0000, v48
	v_pk_add_f32 v[62:63], v[62:63], v[70:71]
	v_lshlrev_b32_e32 v60, 16, v78
	v_pk_fma_f32 v[84:85], v[62:63], 0.5, v[70:71] op_sel_hi:[1,0,1] neg_lo:[0,0,1] neg_hi:[0,0,1]
	v_and_b32_e32 v61, 0xffff0000, v78
	v_pk_add_f32 v[84:85], v[84:85], v[8:9]
	v_and_b32_e32 v83, 0xffff0000, v49
	v_pk_mul_f32 v[84:85], v[84:85], v[12:13]
	v_pk_add_f32 v[66:67], v[66:67], v[82:83]
	v_pk_mul_f32 v[60:61], v[84:85], v[60:61]
	v_pk_add_f32 v[84:85], v[88:89], v[102:103] neg_lo:[0,1] neg_hi:[0,1]
	v_lshlrev_b32_e32 v86, 16, v50
	v_and_b32_e32 v87, 0xffff0000, v50
	v_pk_fma_f32 v[48:49], v[66:67], 0.5, v[82:83] op_sel_hi:[1,0,1] neg_lo:[0,0,1] neg_hi:[0,0,1]
	v_pk_add_f32 v[84:85], v[84:85], v[86:87]
	v_pk_add_f32 v[68:69], v[72:73], v[68:69] neg_lo:[0,1] neg_hi:[0,1]
	v_lshlrev_b32_e32 v72, 16, v51
	v_and_b32_e32 v73, 0xffff0000, v51
	v_pk_add_f32 v[48:49], v[48:49], v[10:11]
	v_pk_fma_f32 v[88:89], v[84:85], 0.5, v[86:87] op_sel_hi:[1,0,1] neg_lo:[0,0,1] neg_hi:[0,0,1]
	v_pk_add_f32 v[68:69], v[68:69], v[72:73]
	v_lshlrev_b32_e32 v78, 16, v79
	v_and_b32_e32 v79, 0xffff0000, v79
	v_pk_mul_f32 v[48:49], v[48:49], v[14:15]
	v_pk_add_f32 v[88:89], v[88:89], v[0:1]
	v_pk_fma_f32 v[50:51], v[68:69], 0.5, v[72:73] op_sel_hi:[1,0,1] neg_lo:[0,0,1] neg_hi:[0,0,1]
	v_pk_mul_f32 v[78:79], v[48:49], v[78:79]
	v_lshlrev_b32_e32 v48, 16, v80
	v_and_b32_e32 v49, 0xffff0000, v80
	v_pk_mul_f32 v[88:89], v[88:89], v[4:5]
	v_pk_add_f32 v[50:51], v[50:51], v[2:3]
	v_pk_mul_f32 v[88:89], v[88:89], v[48:49]
	v_lshlrev_b32_e32 v48, 16, v81
	v_and_b32_e32 v49, 0xffff0000, v81
	v_pk_mul_f32 v[50:51], v[50:51], v[6:7]
	v_pk_add_f32 v[68:69], v[68:69], v[76:77] neg_lo:[0,1] neg_hi:[0,1]
	v_pk_mul_f32 v[80:81], v[50:51], v[48:49]
	v_cvt_pk_bf16_f32 v48, v60, v61
	v_add_u32_e32 v60, 0xffff8002, v150
	v_ashrrev_i32_e32 v61, 31, v60
	v_lshlrev_b64 v[60:61], 12, v[60:61]
	v_cvt_pk_bf16_f32 v49, v78, v79
	v_cvt_pk_bf16_f32 v50, v88, v89
	v_cvt_pk_bf16_f32 v51, v80, v81
	v_lshl_add_u64 v[60:61], v[162:163], 0, v[60:61]
	global_store_dwordx4 v[60:61], v[48:51], off offset:2048 nt
	v_lshlrev_b32_e32 v60, 16, v52
	v_and_b32_e32 v61, 0xffff0000, v52
	v_pk_add_f32 v[50:51], v[62:63], v[64:65] neg_lo:[0,1] neg_hi:[0,1]
	s_waitcnt vmcnt(9)
	v_lshlrev_b32_e32 v48, 16, v56
	v_pk_add_f32 v[62:63], v[50:51], v[60:61]
	v_and_b32_e32 v49, 0xffff0000, v56
	v_pk_fma_f32 v[50:51], v[62:63], 0.5, v[60:61] op_sel_hi:[1,0,1] neg_lo:[0,0,1] neg_hi:[0,0,1]
	v_lshlrev_b32_e32 v52, 16, v53
	v_pk_add_f32 v[50:51], v[50:51], v[8:9]
	v_and_b32_e32 v53, 0xffff0000, v53
	v_pk_mul_f32 v[50:51], v[50:51], v[12:13]
	s_nop 0
	v_pk_mul_f32 v[48:49], v[50:51], v[48:49]
	v_lshlrev_b32_e32 v50, 16, v57
	v_and_b32_e32 v51, 0xffff0000, v57
	v_pk_add_f32 v[56:57], v[66:67], v[74:75] neg_lo:[0,1] neg_hi:[0,1]
	v_lshlrev_b32_e32 v74, 16, v54
	v_pk_add_f32 v[56:57], v[56:57], v[52:53]
	v_and_b32_e32 v75, 0xffff0000, v54
	v_lshlrev_b32_e32 v54, 16, v55
	v_and_b32_e32 v55, 0xffff0000, v55
	v_pk_fma_f32 v[64:65], v[56:57], 0.5, v[52:53] op_sel_hi:[1,0,1] neg_lo:[0,0,1] neg_hi:[0,0,1]
	v_pk_add_f32 v[68:69], v[68:69], v[54:55]
	v_pk_add_f32 v[64:65], v[64:65], v[10:11]
	v_pk_fma_f32 v[76:77], v[68:69], 0.5, v[54:55] op_sel_hi:[1,0,1] neg_lo:[0,0,1] neg_hi:[0,0,1]
	v_pk_mul_f32 v[64:65], v[64:65], v[14:15]
	v_pk_add_f32 v[66:67], v[84:85], v[90:91] neg_lo:[0,1] neg_hi:[0,1]
	v_pk_add_f32 v[76:77], v[76:77], v[2:3]
	v_pk_mul_f32 v[50:51], v[64:65], v[50:51]
	v_lshlrev_b32_e32 v64, 16, v58
	v_and_b32_e32 v65, 0xffff0000, v58
	v_pk_add_f32 v[66:67], v[66:67], v[74:75]
	v_lshlrev_b32_e32 v58, 16, v59
	v_and_b32_e32 v59, 0xffff0000, v59
	v_pk_mul_f32 v[76:77], v[76:77], v[6:7]
	v_pk_fma_f32 v[78:79], v[66:67], 0.5, v[74:75] op_sel_hi:[1,0,1] neg_lo:[0,0,1] neg_hi:[0,0,1]
	v_pk_mul_f32 v[58:59], v[76:77], v[58:59]
	v_pk_add_f32 v[78:79], v[78:79], v[0:1]
	v_cvt_pk_bf16_f32 v48, v48, v49
	v_cvt_pk_bf16_f32 v49, v50, v51
	v_cvt_pk_bf16_f32 v51, v58, v59
	v_add_u32_e32 v58, 0xffff8003, v150
	v_pk_mul_f32 v[78:79], v[78:79], v[4:5]
	v_ashrrev_i32_e32 v59, 31, v58
	v_pk_mul_f32 v[64:65], v[78:79], v[64:65]
	v_lshlrev_b64 v[58:59], 12, v[58:59]
	v_cvt_pk_bf16_f32 v50, v64, v65
	v_lshl_add_u64 v[58:59], v[162:163], 0, v[58:59]
	global_store_dwordx4 v[58:59], v[48:51], off offset:2048 nt
	s_waitcnt vmcnt(9)
	v_lshlrev_b32_e32 v58, 16, v40
	v_and_b32_e32 v59, 0xffff0000, v40
	v_pk_add_f32 v[50:51], v[62:63], v[70:71] neg_lo:[0,1] neg_hi:[0,1]
	s_waitcnt vmcnt(8)
	v_lshlrev_b32_e32 v48, 16, v44
	v_pk_add_f32 v[50:51], v[50:51], v[58:59]
	v_and_b32_e32 v49, 0xffff0000, v44
	v_pk_fma_f32 v[62:63], v[50:51], 0.5, v[58:59] op_sel_hi:[1,0,1] neg_lo:[0,0,1] neg_hi:[0,0,1]
	v_pk_add_f32 v[56:57], v[56:57], v[82:83] neg_lo:[0,1] neg_hi:[0,1]
	v_pk_add_f32 v[62:63], v[62:63], v[8:9]
	v_pk_add_f32 v[64:65], v[66:67], v[86:87] neg_lo:[0,1] neg_hi:[0,1]
	v_pk_mul_f32 v[62:63], v[62:63], v[12:13]
	v_lshlrev_b32_e32 v66, 16, v42
	v_pk_mul_f32 v[48:49], v[62:63], v[48:49]
	v_lshlrev_b32_e32 v62, 16, v41
	v_and_b32_e32 v63, 0xffff0000, v41
	v_pk_add_f32 v[56:57], v[56:57], v[62:63]
	v_and_b32_e32 v67, 0xffff0000, v42
	v_pk_fma_f32 v[40:41], v[56:57], 0.5, v[62:63] op_sel_hi:[1,0,1] neg_lo:[0,0,1] neg_hi:[0,0,1]
	v_pk_add_f32 v[64:65], v[64:65], v[66:67]
	v_pk_add_f32 v[40:41], v[40:41], v[10:11]
	v_pk_fma_f32 v[70:71], v[64:65], 0.5, v[66:67] op_sel_hi:[1,0,1] neg_lo:[0,0,1] neg_hi:[0,0,1]
	v_lshlrev_b32_e32 v44, 16, v45
	v_and_b32_e32 v45, 0xffff0000, v45
	v_pk_mul_f32 v[40:41], v[40:41], v[14:15]
	v_pk_add_f32 v[70:71], v[70:71], v[0:1]
	v_pk_mul_f32 v[44:45], v[40:41], v[44:45]
	v_lshlrev_b32_e32 v40, 16, v46
	v_and_b32_e32 v41, 0xffff0000, v46
	v_pk_mul_f32 v[70:71], v[70:71], v[4:5]
	s_nop 0
	v_pk_mul_f32 v[70:71], v[70:71], v[40:41]
	v_lshlrev_b32_e32 v40, 16, v47
	v_and_b32_e32 v41, 0xffff0000, v47
	v_pk_add_f32 v[46:47], v[68:69], v[72:73] neg_lo:[0,1] neg_hi:[0,1]
	v_lshlrev_b32_e32 v68, 16, v43
	v_and_b32_e32 v69, 0xffff0000, v43
	v_pk_add_f32 v[46:47], v[46:47], v[68:69]
	s_nop 0
	v_pk_fma_f32 v[42:43], v[46:47], 0.5, v[68:69] op_sel_hi:[1,0,1] neg_lo:[0,0,1] neg_hi:[0,0,1]
	s_nop 0
	v_pk_add_f32 v[42:43], v[42:43], v[2:3]
	s_nop 0
	v_pk_mul_f32 v[42:43], v[42:43], v[6:7]
	s_nop 0
	v_pk_mul_f32 v[72:73], v[42:43], v[40:41]
	v_cvt_pk_bf16_f32 v41, v44, v45
	v_add_u32_e32 v44, 0xffff8004, v150
	v_ashrrev_i32_e32 v45, 31, v44
	v_lshlrev_b64 v[44:45], 12, v[44:45]
	v_cvt_pk_bf16_f32 v40, v48, v49
	v_cvt_pk_bf16_f32 v42, v70, v71
	v_cvt_pk_bf16_f32 v43, v72, v73
	v_lshl_add_u64 v[44:45], v[162:163], 0, v[44:45]
	global_store_dwordx4 v[44:45], v[40:43], off offset:2048 nt
	v_lshlrev_b32_e32 v44, 16, v32
	v_and_b32_e32 v45, 0xffff0000, v32
	v_pk_add_f32 v[42:43], v[50:51], v[60:61] neg_lo:[0,1] neg_hi:[0,1]
	s_waitcnt vmcnt(6)
	v_lshlrev_b32_e32 v40, 16, v36
	v_pk_add_f32 v[42:43], v[42:43], v[44:45]
	v_and_b32_e32 v41, 0xffff0000, v36
	v_pk_fma_f32 v[48:49], v[42:43], 0.5, v[44:45] op_sel_hi:[1,0,1] neg_lo:[0,0,1] neg_hi:[0,0,1]
	v_lshlrev_b32_e32 v50, 16, v33
	v_pk_add_f32 v[48:49], v[48:49], v[8:9]
	v_and_b32_e32 v51, 0xffff0000, v33
	v_pk_mul_f32 v[48:49], v[48:49], v[12:13]
	v_lshlrev_b32_e32 v36, 16, v37
	v_pk_mul_f32 v[40:41], v[48:49], v[40:41]
	v_pk_add_f32 v[48:49], v[56:57], v[52:53] neg_lo:[0,1] neg_hi:[0,1]
	v_pk_add_f32 v[52:53], v[64:65], v[74:75] neg_lo:[0,1] neg_hi:[0,1]
	v_pk_add_f32 v[48:49], v[48:49], v[50:51]
	v_lshlrev_b32_e32 v56, 16, v34
	v_and_b32_e32 v57, 0xffff0000, v34
	v_pk_fma_f32 v[32:33], v[48:49], 0.5, v[50:51] op_sel_hi:[1,0,1] neg_lo:[0,0,1] neg_hi:[0,0,1]
	v_pk_add_f32 v[52:53], v[52:53], v[56:57]
	v_pk_add_f32 v[32:33], v[32:33], v[10:11]
	v_pk_fma_f32 v[60:61], v[52:53], 0.5, v[56:57] op_sel_hi:[1,0,1] neg_lo:[0,0,1] neg_hi:[0,0,1]
	v_and_b32_e32 v37, 0xffff0000, v37
	v_pk_mul_f32 v[32:33], v[32:33], v[14:15]
	v_pk_add_f32 v[60:61], v[60:61], v[0:1]
	v_pk_mul_f32 v[36:37], v[32:33], v[36:37]
	v_lshlrev_b32_e32 v32, 16, v38
	v_and_b32_e32 v33, 0xffff0000, v38
	v_pk_mul_f32 v[60:61], v[60:61], v[4:5]
	s_nop 0
	v_pk_mul_f32 v[60:61], v[60:61], v[32:33]
	v_lshlrev_b32_e32 v32, 16, v39
	v_and_b32_e32 v33, 0xffff0000, v39
	v_pk_add_f32 v[38:39], v[46:47], v[54:55] neg_lo:[0,1] neg_hi:[0,1]
	v_lshlrev_b32_e32 v46, 16, v35
	v_and_b32_e32 v47, 0xffff0000, v35
	v_pk_add_f32 v[38:39], v[38:39], v[46:47]
	s_nop 0
	v_pk_fma_f32 v[34:35], v[38:39], 0.5, v[46:47] op_sel_hi:[1,0,1] neg_lo:[0,0,1] neg_hi:[0,0,1]
	s_nop 0
	v_pk_add_f32 v[34:35], v[34:35], v[2:3]
	s_nop 0
	v_pk_mul_f32 v[34:35], v[34:35], v[6:7]
	s_nop 0
	v_pk_mul_f32 v[54:55], v[34:35], v[32:33]
	v_cvt_pk_bf16_f32 v33, v36, v37
	v_add_u32_e32 v36, 0xffff8005, v150
	v_ashrrev_i32_e32 v37, 31, v36
	v_lshlrev_b64 v[36:37], 12, v[36:37]
	v_cvt_pk_bf16_f32 v32, v40, v41
	v_cvt_pk_bf16_f32 v34, v60, v61
	v_cvt_pk_bf16_f32 v35, v54, v55
	v_lshl_add_u64 v[36:37], v[162:163], 0, v[36:37]
	global_store_dwordx4 v[36:37], v[32:35], off offset:2048 nt
	v_lshlrev_b32_e32 v36, 16, v24
	v_and_b32_e32 v37, 0xffff0000, v24
	v_pk_add_f32 v[34:35], v[42:43], v[58:59] neg_lo:[0,1] neg_hi:[0,1]
	v_lshlrev_b32_e32 v32, 16, v28
	v_pk_add_f32 v[34:35], v[34:35], v[36:37]
	v_and_b32_e32 v33, 0xffff0000, v28
	v_pk_fma_f32 v[36:37], v[34:35], 0.5, v[36:37] op_sel_hi:[1,0,1] neg_lo:[0,0,1] neg_hi:[0,0,1]
	v_lshlrev_b32_e32 v24, 16, v25
	v_pk_add_f32 v[36:37], v[36:37], v[8:9]
	v_and_b32_e32 v25, 0xffff0000, v25
	v_pk_mul_f32 v[36:37], v[36:37], v[12:13]
	v_pk_add_f32 v[40:41], v[52:53], v[66:67] neg_lo:[0,1] neg_hi:[0,1]
	v_pk_mul_f32 v[32:33], v[36:37], v[32:33]
	v_pk_add_f32 v[36:37], v[48:49], v[62:63] neg_lo:[0,1] neg_hi:[0,1]
	v_lshlrev_b32_e32 v42, 16, v26
	v_pk_add_f32 v[36:37], v[36:37], v[24:25]
	v_and_b32_e32 v43, 0xffff0000, v26
	v_pk_fma_f32 v[24:25], v[36:37], 0.5, v[24:25] op_sel_hi:[1,0,1] neg_lo:[0,0,1] neg_hi:[0,0,1]
	v_pk_add_f32 v[40:41], v[40:41], v[42:43]
	v_pk_add_f32 v[24:25], v[24:25], v[10:11]
	v_pk_fma_f32 v[42:43], v[40:41], 0.5, v[42:43] op_sel_hi:[1,0,1] neg_lo:[0,0,1] neg_hi:[0,0,1]
	v_lshlrev_b32_e32 v28, 16, v29
	v_and_b32_e32 v29, 0xffff0000, v29
	v_pk_mul_f32 v[24:25], v[24:25], v[14:15]
	v_pk_add_f32 v[42:43], v[42:43], v[0:1]
	v_pk_mul_f32 v[28:29], v[24:25], v[28:29]
	v_lshlrev_b32_e32 v24, 16, v30
	v_and_b32_e32 v25, 0xffff0000, v30
	v_pk_mul_f32 v[42:43], v[42:43], v[4:5]
	v_lshlrev_b32_e32 v26, 16, v27
	v_pk_mul_f32 v[42:43], v[42:43], v[24:25]
	v_lshlrev_b32_e32 v24, 16, v31
	v_and_b32_e32 v25, 0xffff0000, v31
	v_pk_add_f32 v[30:31], v[38:39], v[68:69] neg_lo:[0,1] neg_hi:[0,1]
	v_and_b32_e32 v27, 0xffff0000, v27
	v_pk_add_f32 v[30:31], v[30:31], v[26:27]
	s_nop 0
	v_pk_fma_f32 v[26:27], v[30:31], 0.5, v[26:27] op_sel_hi:[1,0,1] neg_lo:[0,0,1] neg_hi:[0,0,1]
	s_nop 0
	v_pk_add_f32 v[26:27], v[26:27], v[2:3]
	s_nop 0
	v_pk_mul_f32 v[26:27], v[26:27], v[6:7]
	s_nop 0
	v_pk_mul_f32 v[38:39], v[26:27], v[24:25]
	v_cvt_pk_bf16_f32 v25, v28, v29
	v_add_u32_e32 v28, 0xffff8006, v150
	v_ashrrev_i32_e32 v29, 31, v28
	v_lshlrev_b64 v[28:29], 12, v[28:29]
	v_cvt_pk_bf16_f32 v24, v32, v33
	v_cvt_pk_bf16_f32 v26, v42, v43
	v_cvt_pk_bf16_f32 v27, v38, v39
	v_lshl_add_u64 v[28:29], v[162:163], 0, v[28:29]
	global_store_dwordx4 v[28:29], v[24:27], off offset:2048 nt
	v_lshlrev_b32_e32 v28, 16, v16
	v_and_b32_e32 v29, 0xffff0000, v16
	v_pk_add_f32 v[26:27], v[34:35], v[44:45] neg_lo:[0,1] neg_hi:[0,1]
	s_waitcnt vmcnt(7)
	v_lshlrev_b32_e32 v24, 16, v20
	v_pk_add_f32 v[26:27], v[26:27], v[28:29]
	v_and_b32_e32 v25, 0xffff0000, v20
	v_pk_fma_f32 v[26:27], v[26:27], 0.5, v[28:29] op_sel_hi:[1,0,1] neg_lo:[0,0,1] neg_hi:[0,0,1]
	v_lshlrev_b32_e32 v16, 16, v17
	v_pk_add_f32 v[8:9], v[26:27], v[8:9]
	v_and_b32_e32 v17, 0xffff0000, v17
	v_pk_mul_f32 v[8:9], v[8:9], v[12:13]
	v_lshlrev_b32_e32 v12, 16, v21
	v_and_b32_e32 v13, 0xffff0000, v21
	v_pk_add_f32 v[20:21], v[36:37], v[50:51] neg_lo:[0,1] neg_hi:[0,1]
	v_pk_mul_f32 v[8:9], v[8:9], v[24:25]
	v_pk_add_f32 v[20:21], v[20:21], v[16:17]
	s_nop 0
	v_pk_fma_f32 v[16:17], v[20:21], 0.5, v[16:17] op_sel_hi:[1,0,1] neg_lo:[0,0,1] neg_hi:[0,0,1]
	s_nop 0
	v_pk_add_f32 v[10:11], v[16:17], v[10:11]
	v_lshlrev_b32_e32 v16, 16, v18
	v_pk_mul_f32 v[10:11], v[10:11], v[14:15]
	v_pk_add_f32 v[14:15], v[40:41], v[56:57] neg_lo:[0,1] neg_hi:[0,1]
	v_and_b32_e32 v17, 0xffff0000, v18
	v_pk_add_f32 v[14:15], v[14:15], v[16:17]
	v_pk_mul_f32 v[10:11], v[10:11], v[12:13]
	v_pk_fma_f32 v[14:15], v[14:15], 0.5, v[16:17] op_sel_hi:[1,0,1] neg_lo:[0,0,1] neg_hi:[0,0,1]
	v_lshlrev_b32_e32 v12, 16, v22
	v_pk_add_f32 v[0:1], v[14:15], v[0:1]
	v_and_b32_e32 v13, 0xffff0000, v22
	v_pk_mul_f32 v[0:1], v[0:1], v[4:5]
	v_lshlrev_b32_e32 v14, 16, v19
	v_pk_mul_f32 v[4:5], v[0:1], v[12:13]
	v_pk_add_f32 v[12:13], v[30:31], v[46:47] neg_lo:[0,1] neg_hi:[0,1]
	v_and_b32_e32 v15, 0xffff0000, v19
	v_pk_add_f32 v[12:13], v[12:13], v[14:15]
	v_lshlrev_b32_e32 v0, 16, v23
	v_pk_fma_f32 v[12:13], v[12:13], 0.5, v[14:15] op_sel_hi:[1,0,1] neg_lo:[0,0,1] neg_hi:[0,0,1]
	v_and_b32_e32 v1, 0xffff0000, v23
	v_pk_add_f32 v[2:3], v[12:13], v[2:3]
	s_nop 0
	v_pk_mul_f32 v[2:3], v[2:3], v[6:7]
	s_nop 0
	v_pk_mul_f32 v[6:7], v[2:3], v[0:1]
	v_cvt_pk_bf16_f32 v2, v4, v5
	v_add_u32_e32 v4, 0xffff8007, v150
	v_ashrrev_i32_e32 v5, 31, v4
	v_lshlrev_b64 v[4:5], 12, v[4:5]
	v_cvt_pk_bf16_f32 v0, v8, v9
	v_cvt_pk_bf16_f32 v1, v10, v11
	v_cvt_pk_bf16_f32 v3, v6, v7
	v_lshl_add_u64 v[4:5], v[162:163], 0, v[4:5]
	global_store_dwordx4 v[4:5], v[0:3], off offset:2048 nt

.LBB0_398:
	s_or_b64 exec, exec, s[60:61]
	v_add_co_u32_e32 v0, vcc, 0x2000, v128
	s_waitcnt vmcnt(0)
	v_lshlrev_b32_e32 v100, 16, v76
	v_addc_co_u32_e32 v1, vcc, 0, v129, vcc
	v_add_co_u32_e32 v16, vcc, 0x5000, v128
	v_and_b32_e32 v101, 0xffff0000, v76
	s_nop 0
	v_addc_co_u32_e32 v17, vcc, 0, v129, vcc
	global_load_dwordx4 v[64:67], v[0:1], off offset:2048
	global_load_dwordx4 v[48:51], v[16:17], off
	global_load_dwordx4 v[80:83], v[128:129], off
	global_load_dwordx4 v[92:95], v[128:129], off offset:2048
	s_nop 0
	global_load_dwordx4 v[0:3], v[154:155], off offset:16
	global_load_dwordx4 v[8:11], v[154:155], off
	global_load_dwordx4 v[4:7], v[156:157], off offset:16
	global_load_dwordx4 v[12:15], v[156:157], off
	v_add_co_u32_e32 v18, vcc, 0x7000, v128
	v_min_u32_e32 v76, 3, v217
	s_nop 0
	v_addc_co_u32_e32 v19, vcc, 0, v129, vcc
	v_add_co_u32_e32 v20, vcc, 0xa000, v128
	v_add_u32_e32 v76, 1, v76
	s_nop 0
	v_addc_co_u32_e32 v21, vcc, 0, v129, vcc
	v_add_co_u32_e32 v22, vcc, s66, v128
	v_cvt_f32_ubyte0_e32 v76, v76
	s_nop 0
	v_addc_co_u32_e32 v23, vcc, 0, v129, vcc
	v_add_co_u32_e32 v28, vcc, s63, v128
	v_lshlrev_b32_e32 v102, 16, v77
	s_nop 0
	v_addc_co_u32_e32 v29, vcc, 0, v129, vcc
	global_load_dwordx4 v[32:35], v[22:23], off offset:2048
	global_load_dwordx4 v[24:27], v[28:29], off
	v_add_co_u32_e32 v22, vcc, s64, v128
	global_load_dwordx4 v[52:55], v[18:19], off offset:2048
	global_load_dwordx4 v[68:71], v[16:17], off offset:2048
	v_addc_co_u32_e32 v23, vcc, 0, v129, vcc
	v_add_co_u32_e32 v30, vcc, s65, v128
	v_and_b32_e32 v103, 0xffff0000, v77
	s_nop 0
	v_addc_co_u32_e32 v31, vcc, 0, v129, vcc
	v_add_co_u32_e32 v16, vcc, s51, v128
	v_div_scale_f32 v77, s[0:1], v76, v76, 1.0
	s_nop 0
	v_addc_co_u32_e32 v17, vcc, 0, v129, vcc
	global_load_dwordx4 v[96:99], v[30:31], off
	global_load_dwordx4 v[56:59], v[16:17], off
	global_load_dwordx4 v[40:43], v[20:21], off
	global_load_dwordx4 v[44:47], v[20:21], off offset:2048
	v_rcp_f32_e32 v84, v77
	v_add_co_u32_e32 v20, vcc, s67, v128
	global_load_dwordx4 v[16:19], v[22:23], off offset:2048
	s_nop 0
	global_load_dwordx4 v[28:31], v[28:29], off offset:2048
	v_addc_co_u32_e32 v21, vcc, 0, v129, vcc
	v_add_co_u32_e32 v22, vcc, s70, v128
	v_lshlrev_b32_e32 v104, 16, v78
	s_nop 0
	v_addc_co_u32_e32 v23, vcc, 0, v129, vcc
	v_and_b32_e32 v105, 0xffff0000, v78
	v_fma_f32 v78, -v77, v84, 1.0
	v_fmac_f32_e32 v84, v78, v84
	v_div_scale_f32 v78, vcc, 1.0, v76, 1.0
	v_lshlrev_b32_e32 v106, 16, v79
	v_and_b32_e32 v107, 0xffff0000, v79
	v_mul_f32_e32 v79, v78, v84
	v_fma_f32 v85, -v77, v79, v78
	v_fmac_f32_e32 v79, v85, v84
	v_fma_f32 v77, -v77, v79, v78
	v_div_fmas_f32 v77, v77, v84, v79
	v_div_fixup_f32 v78, v77, v76, 1.0
	v_pk_add_f32 v[76:77], v[100:101], 0 op_sel_hi:[1,0]
	v_lshlrev_b32_e32 v108, 16, v60
	v_and_b32_e32 v109, 0xffff0000, v60
	v_pk_add_f32 v[76:77], v[76:77], v[108:109]
	v_lshlrev_b32_e32 v84, 16, v72
	v_and_b32_e32 v85, 0xffff0000, v72
	v_pk_add_f32 v[88:89], v[76:77], v[84:85]
	v_lshlrev_b32_e32 v114, 16, v61
	v_and_b32_e32 v115, 0xffff0000, v61
	v_lshlrev_b32_e32 v118, 16, v62
	v_and_b32_e32 v119, 0xffff0000, v62
	v_lshlrev_b32_e32 v124, 16, v63
	v_and_b32_e32 v125, 0xffff0000, v63
	global_load_dwordx4 v[36:39], v[20:21], off
	s_nop 0
	global_load_dwordx4 v[20:23], v[22:23], off
	s_waitcnt vmcnt(17)
	v_lshlrev_b32_e32 v76, 16, v80
	v_and_b32_e32 v77, 0xffff0000, v80
	v_pk_add_f32 v[110:111], v[88:89], v[76:77]
	s_waitcnt vmcnt(16)
	v_lshlrev_b32_e32 v86, 16, v92
	v_pk_fma_f32 v[88:89], v[78:79], v[110:111], v[76:77] op_sel_hi:[0,1,1] neg_lo:[0,0,1] neg_hi:[0,0,1]
	s_waitcnt vmcnt(14)
	v_pk_add_f32 v[88:89], v[88:89], v[8:9]
	v_and_b32_e32 v87, 0xffff0000, v92
	s_waitcnt vmcnt(12)
	v_pk_mul_f32 v[88:89], v[88:89], v[12:13]
	v_lshlrev_b32_e32 v116, 16, v94
	v_pk_mul_f32 v[112:113], v[88:89], v[86:87]
	v_pk_add_f32 v[86:87], v[102:103], 0 op_sel_hi:[1,0]
	v_lshlrev_b32_e32 v88, 16, v93
	v_pk_add_f32 v[60:61], v[86:87], v[114:115]
	v_lshlrev_b32_e32 v86, 16, v73
	v_and_b32_e32 v87, 0xffff0000, v73
	v_pk_add_f32 v[72:73], v[60:61], v[86:87]
	v_lshlrev_b32_e32 v60, 16, v81
	v_and_b32_e32 v61, 0xffff0000, v81
	v_and_b32_e32 v89, 0xffff0000, v93
	v_pk_add_f32 v[92:93], v[72:73], v[60:61]
	v_and_b32_e32 v117, 0xffff0000, v94
	v_pk_fma_f32 v[72:73], v[78:79], v[92:93], v[60:61] op_sel_hi:[0,1,1] neg_lo:[0,0,1] neg_hi:[0,0,1]
	v_pk_add_f32 v[72:73], v[72:73], v[10:11]
	v_lshlrev_b32_e32 v94, 16, v95
	v_pk_mul_f32 v[72:73], v[72:73], v[14:15]
	v_and_b32_e32 v95, 0xffff0000, v95
	v_pk_mul_f32 v[80:81], v[72:73], v[88:89]
	v_pk_add_f32 v[72:73], v[104:105], 0 op_sel_hi:[1,0]
	v_lshlrev_b32_e32 v88, 16, v74
	v_pk_add_f32 v[72:73], v[72:73], v[118:119]
	v_and_b32_e32 v89, 0xffff0000, v74
	v_pk_add_f32 v[120:121], v[72:73], v[88:89]
	v_lshlrev_b32_e32 v72, 16, v82
	v_and_b32_e32 v73, 0xffff0000, v82
	v_pk_add_f32 v[120:121], v[120:121], v[72:73]
	v_pk_add_f32 v[92:93], v[92:93], v[102:103] neg_lo:[0,1] neg_hi:[0,1]
	v_pk_fma_f32 v[122:123], v[78:79], v[120:121], v[72:73] op_sel_hi:[0,1,1] neg_lo:[0,0,1] neg_hi:[0,0,1]
	v_pk_add_f32 v[122:123], v[122:123], v[0:1]
	s_nop 0
	v_pk_mul_f32 v[122:123], v[122:123], v[4:5]
	s_nop 0
	v_pk_mul_f32 v[116:117], v[122:123], v[116:117]
	v_pk_add_f32 v[122:123], v[106:107], 0 op_sel_hi:[1,0]
	s_nop 0
	v_pk_add_f32 v[62:63], v[122:123], v[124:125]
	v_lshlrev_b32_e32 v122, 16, v75
	v_and_b32_e32 v123, 0xffff0000, v75
	v_pk_add_f32 v[74:75], v[62:63], v[122:123]
	v_lshlrev_b32_e32 v62, 16, v83
	v_and_b32_e32 v63, 0xffff0000, v83
	v_pk_add_f32 v[82:83], v[74:75], v[62:63]
	s_nop 0
	v_pk_fma_f32 v[74:75], v[78:79], v[82:83], v[62:63] op_sel_hi:[0,1,1] neg_lo:[0,0,1] neg_hi:[0,0,1]
	v_pk_add_f32 v[74:75], v[74:75], v[2:3]
	v_cvt_pk_bf16_f32 v79, v80, v81
	v_pk_mul_f32 v[74:75], v[74:75], v[6:7]
	v_cvt_pk_bf16_f32 v78, v112, v113
	v_pk_mul_f32 v[74:75], v[74:75], v[94:95]
	v_cvt_pk_bf16_f32 v80, v116, v117
	v_cvt_pk_bf16_f32 v81, v74, v75
	v_min_u32_e32 v74, 2, v217
	v_add_u32_e32 v74, 2, v74
	v_cvt_f32_ubyte0_e32 v91, v74
	v_div_scale_f32 v94, s[0:1], v91, v91, 1.0
	v_rcp_f32_e32 v95, v94
	v_lshlrev_b64 v[74:75], 12, v[126:127]
	v_lshl_add_u64 v[74:75], v[162:163], 0, v[74:75]
	global_store_dwordx4 v[74:75], v[78:81], off offset:2048 nt
	v_fma_f32 v74, -v94, v95, 1.0
	v_fmac_f32_e32 v95, v74, v95
	v_div_scale_f32 v74, vcc, 1.0, v91, 1.0
	v_mul_f32_e32 v75, v74, v95
	v_fma_f32 v78, -v94, v75, v74
	v_fmac_f32_e32 v75, v78, v95
	v_fma_f32 v74, -v94, v75, v74
	v_div_fmas_f32 v74, v74, v95, v75
	v_div_fixup_f32 v94, v74, v91, 1.0
	v_pk_add_f32 v[80:81], v[110:111], v[100:101] neg_lo:[0,1] neg_hi:[0,1]
	v_lshlrev_b32_e32 v74, 16, v64
	v_and_b32_e32 v75, 0xffff0000, v64
	v_pk_add_f32 v[100:101], v[80:81], v[74:75]
	s_waitcnt vmcnt(8)
	v_lshlrev_b32_e32 v78, 16, v96
	v_pk_fma_f32 v[80:81], v[94:95], v[100:101], v[74:75] op_sel_hi:[0,1,1] neg_lo:[0,0,1] neg_hi:[0,0,1]
	v_pk_add_f32 v[80:81], v[80:81], v[8:9]
	v_and_b32_e32 v79, 0xffff0000, v96
	v_pk_mul_f32 v[80:81], v[80:81], v[12:13]
	v_pk_add_f32 v[82:83], v[82:83], v[106:107] neg_lo:[0,1] neg_hi:[0,1]
	v_pk_mul_f32 v[110:111], v[80:81], v[78:79]
	v_lshlrev_b32_e32 v80, 16, v65
	v_and_b32_e32 v81, 0xffff0000, v65
	v_lshlrev_b32_e32 v78, 16, v97
	v_and_b32_e32 v79, 0xffff0000, v97
	v_pk_add_f32 v[96:97], v[92:93], v[80:81]
	v_pk_add_f32 v[92:93], v[120:121], v[104:105] neg_lo:[0,1] neg_hi:[0,1]
	v_pk_fma_f32 v[64:65], v[94:95], v[96:97], v[80:81] op_sel_hi:[0,1,1] neg_lo:[0,0,1] neg_hi:[0,0,1]
	v_pk_add_f32 v[64:65], v[64:65], v[10:11]
	v_pk_add_f32 v[96:97], v[96:97], v[114:115] neg_lo:[0,1] neg_hi:[0,1]
	v_pk_mul_f32 v[64:65], v[64:65], v[14:15]
	s_nop 0
	v_pk_mul_f32 v[102:103], v[64:65], v[78:79]
	v_lshlrev_b32_e32 v78, 16, v66
	v_and_b32_e32 v79, 0xffff0000, v66
	v_pk_add_f32 v[104:105], v[92:93], v[78:79]
	v_lshlrev_b32_e32 v64, 16, v98
	v_pk_fma_f32 v[92:93], v[94:95], v[104:105], v[78:79] op_sel_hi:[0,1,1] neg_lo:[0,0,1] neg_hi:[0,0,1]
	v_pk_add_f32 v[92:93], v[92:93], v[0:1]
	v_and_b32_e32 v65, 0xffff0000, v98
	v_pk_mul_f32 v[92:93], v[92:93], v[4:5]
	s_nop 0
	v_pk_mul_f32 v[112:113], v[92:93], v[64:65]
	v_lshlrev_b32_e32 v64, 16, v67
	v_and_b32_e32 v65, 0xffff0000, v67
	v_lshlrev_b32_e32 v92, 16, v99
	v_and_b32_e32 v93, 0xffff0000, v99
	v_pk_add_f32 v[98:99], v[82:83], v[64:65]
	v_div_scale_f32 v82, s[0:1], v90, v90, 1.0
	v_pk_fma_f32 v[66:67], v[94:95], v[98:99], v[64:65] op_sel_hi:[0,1,1] neg_lo:[0,0,1] neg_hi:[0,0,1]
	v_pk_add_f32 v[66:67], v[66:67], v[2:3]
	v_rcp_f32_e32 v83, v82
	v_pk_mul_f32 v[66:67], v[66:67], v[6:7]
	v_cvt_pk_bf16_f32 v94, v112, v113
	v_pk_mul_f32 v[66:67], v[66:67], v[92:93]
	v_cvt_pk_bf16_f32 v92, v110, v111
	v_cvt_pk_bf16_f32 v95, v66, v67
	v_add_u32_e32 v66, 0xffff8001, v150
	v_ashrrev_i32_e32 v67, 31, v66
	v_lshlrev_b64 v[66:67], 12, v[66:67]
	v_cvt_pk_bf16_f32 v93, v102, v103
	v_lshl_add_u64 v[66:67], v[162:163], 0, v[66:67]
	global_store_dwordx4 v[66:67], v[92:95], off offset:2048 nt
	v_fma_f32 v66, -v82, v83, 1.0
	v_fmac_f32_e32 v83, v66, v83
	v_div_scale_f32 v66, vcc, 1.0, v90, 1.0
	v_mul_f32_e32 v67, v66, v83
	v_fma_f32 v91, -v82, v67, v66
	v_fmac_f32_e32 v67, v91, v83
	v_fma_f32 v66, -v82, v67, v66
	v_div_fmas_f32 v66, v66, v83, v67
	v_div_fixup_f32 v90, v66, v90, 1.0
	v_pk_add_f32 v[92:93], v[100:101], v[108:109] neg_lo:[0,1] neg_hi:[0,1]
	v_lshlrev_b32_e32 v66, 16, v48
	v_and_b32_e32 v67, 0xffff0000, v48
	v_pk_add_f32 v[94:95], v[92:93], v[66:67]
	v_lshlrev_b32_e32 v82, 16, v68
	v_pk_fma_f32 v[92:93], v[90:91], v[94:95], v[66:67] op_sel_hi:[0,1,1] neg_lo:[0,0,1] neg_hi:[0,0,1]
	v_pk_add_f32 v[92:93], v[92:93], v[8:9]
	v_and_b32_e32 v83, 0xffff0000, v68
	v_pk_mul_f32 v[92:93], v[92:93], v[12:13]
	v_lshlrev_b32_e32 v68, 16, v69
	v_pk_mul_f32 v[92:93], v[92:93], v[82:83]
	v_lshlrev_b32_e32 v82, 16, v49
	v_and_b32_e32 v83, 0xffff0000, v49
	v_pk_add_f32 v[96:97], v[96:97], v[82:83]
	v_and_b32_e32 v69, 0xffff0000, v69
	v_pk_fma_f32 v[48:49], v[90:91], v[96:97], v[82:83] op_sel_hi:[0,1,1] neg_lo:[0,0,1] neg_hi:[0,0,1]
	v_pk_add_f32 v[48:49], v[48:49], v[10:11]
	v_pk_add_f32 v[102:103], v[104:105], v[118:119] neg_lo:[0,1] neg_hi:[0,1]
	v_pk_mul_f32 v[48:49], v[48:49], v[14:15]
	v_pk_add_f32 v[98:99], v[98:99], v[124:125] neg_lo:[0,1] neg_hi:[0,1]
	v_pk_mul_f32 v[48:49], v[48:49], v[68:69]
	v_lshlrev_b32_e32 v68, 16, v50
	v_and_b32_e32 v69, 0xffff0000, v50
	v_lshlrev_b32_e32 v50, 16, v51
	v_and_b32_e32 v51, 0xffff0000, v51
	v_pk_add_f32 v[102:103], v[102:103], v[68:69]
	v_pk_add_f32 v[98:99], v[98:99], v[50:51]
	v_pk_fma_f32 v[104:105], v[90:91], v[102:103], v[68:69] op_sel_hi:[0,1,1] neg_lo:[0,0,1] neg_hi:[0,0,1]
	v_pk_fma_f32 v[90:91], v[90:91], v[98:99], v[50:51] op_sel_hi:[0,1,1] neg_lo:[0,0,1] neg_hi:[0,0,1]
	v_pk_add_f32 v[90:91], v[90:91], v[2:3]
	v_lshlrev_b32_e32 v100, 16, v70
	v_and_b32_e32 v101, 0xffff0000, v70
	v_lshlrev_b32_e32 v70, 16, v71
	v_and_b32_e32 v71, 0xffff0000, v71
	v_pk_mul_f32 v[90:91], v[90:91], v[6:7]
	v_pk_add_f32 v[104:105], v[104:105], v[0:1]
	v_pk_mul_f32 v[70:71], v[90:91], v[70:71]
	v_cvt_pk_bf16_f32 v91, v48, v49
	v_add_u32_e32 v48, 0xffff8002, v150
	v_pk_mul_f32 v[104:105], v[104:105], v[4:5]
	v_ashrrev_i32_e32 v49, 31, v48
	v_pk_mul_f32 v[100:101], v[104:105], v[100:101]
	v_lshlrev_b64 v[48:49], 12, v[48:49]
	v_cvt_pk_bf16_f32 v90, v92, v93
	v_cvt_pk_bf16_f32 v92, v100, v101
	v_cvt_pk_bf16_f32 v93, v70, v71
	v_lshl_add_u64 v[48:49], v[162:163], 0, v[48:49]
	global_store_dwordx4 v[48:49], v[90:93], off offset:2048 nt
	v_pk_add_f32 v[84:85], v[94:95], v[84:85] neg_lo:[0,1] neg_hi:[0,1]
	v_lshlrev_b32_e32 v48, 16, v52
	v_and_b32_e32 v49, 0xffff0000, v52
	v_pk_add_f32 v[90:91], v[84:85], v[48:49]
	s_waitcnt vmcnt(9)
	v_lshlrev_b32_e32 v70, 16, v56
	v_pk_fma_f32 v[84:85], v[90:91], s[52:53], v[48:49] op_sel_hi:[1,0,1] neg_lo:[0,0,1] neg_hi:[0,0,1]
	v_and_b32_e32 v71, 0xffff0000, v56
	v_pk_add_f32 v[84:85], v[84:85], v[8:9]
	v_pk_add_f32 v[86:87], v[96:97], v[86:87] neg_lo:[0,1] neg_hi:[0,1]
	v_pk_mul_f32 v[84:85], v[84:85], v[12:13]
	v_lshlrev_b32_e32 v56, 16, v57
	v_pk_mul_f32 v[84:85], v[84:85], v[70:71]
	v_lshlrev_b32_e32 v70, 16, v53
	v_and_b32_e32 v71, 0xffff0000, v53
	v_pk_add_f32 v[92:93], v[86:87], v[70:71]
	v_and_b32_e32 v57, 0xffff0000, v57
	v_pk_fma_f32 v[52:53], v[92:93], s[52:53], v[70:71] op_sel_hi:[1,0,1] neg_lo:[0,0,1] neg_hi:[0,0,1]
	v_pk_add_f32 v[88:89], v[102:103], v[88:89] neg_lo:[0,1] neg_hi:[0,1]
	v_pk_add_f32 v[52:53], v[52:53], v[10:11]
	v_pk_add_f32 v[96:97], v[98:99], v[122:123] neg_lo:[0,1] neg_hi:[0,1]
	v_pk_mul_f32 v[52:53], v[52:53], v[14:15]
	v_cvt_pk_bf16_f32 v84, v84, v85
	v_pk_mul_f32 v[86:87], v[52:53], v[56:57]
	v_lshlrev_b32_e32 v56, 16, v54
	v_and_b32_e32 v57, 0xffff0000, v54
	v_pk_add_f32 v[88:89], v[88:89], v[56:57]
	v_lshlrev_b32_e32 v52, 16, v58
	v_pk_fma_f32 v[94:95], v[88:89], s[52:53], v[56:57] op_sel_hi:[1,0,1] neg_lo:[0,0,1] neg_hi:[0,0,1]
	v_and_b32_e32 v53, 0xffff0000, v58
	v_pk_add_f32 v[94:95], v[94:95], v[0:1]
	v_lshlrev_b32_e32 v58, 16, v59
	v_pk_mul_f32 v[94:95], v[94:95], v[4:5]
	v_and_b32_e32 v59, 0xffff0000, v59
	v_pk_mul_f32 v[94:95], v[94:95], v[52:53]
	v_lshlrev_b32_e32 v52, 16, v55
	v_and_b32_e32 v53, 0xffff0000, v55
	v_pk_add_f32 v[54:55], v[96:97], v[52:53]
	v_cvt_pk_bf16_f32 v85, v86, v87
	v_pk_fma_f32 v[96:97], v[54:55], s[52:53], v[52:53] op_sel_hi:[1,0,1] neg_lo:[0,0,1] neg_hi:[0,0,1]
	v_cvt_pk_bf16_f32 v86, v94, v95
	v_pk_add_f32 v[96:97], v[96:97], v[2:3]
	v_pk_add_f32 v[76:77], v[90:91], v[76:77] neg_lo:[0,1] neg_hi:[0,1]
	v_pk_mul_f32 v[96:97], v[96:97], v[6:7]
	v_pk_add_f32 v[60:61], v[92:93], v[60:61] neg_lo:[0,1] neg_hi:[0,1]
	v_pk_mul_f32 v[58:59], v[96:97], v[58:59]
	v_pk_add_f32 v[72:73], v[88:89], v[72:73] neg_lo:[0,1] neg_hi:[0,1]
	v_cvt_pk_bf16_f32 v87, v58, v59
	v_add_u32_e32 v58, 0xffff8003, v150
	v_ashrrev_i32_e32 v59, 31, v58
	v_lshlrev_b64 v[58:59], 12, v[58:59]
	v_lshl_add_u64 v[58:59], v[162:163], 0, v[58:59]
	global_store_dwordx4 v[58:59], v[84:87], off offset:2048 nt
	s_waitcnt vmcnt(8)
	v_lshlrev_b32_e32 v58, 16, v44
	v_and_b32_e32 v59, 0xffff0000, v44
	v_lshlrev_b32_e32 v84, 16, v40
	v_and_b32_e32 v85, 0xffff0000, v40
	v_pk_add_f32 v[76:77], v[76:77], v[84:85]
	v_lshlrev_b32_e32 v40, 16, v41
	v_pk_fma_f32 v[84:85], v[76:77], s[52:53], v[84:85] op_sel_hi:[1,0,1] neg_lo:[0,0,1] neg_hi:[0,0,1]
	v_and_b32_e32 v41, 0xffff0000, v41
	v_pk_add_f32 v[84:85], v[84:85], v[8:9]
	v_pk_add_f32 v[60:61], v[60:61], v[40:41]
	v_pk_mul_f32 v[84:85], v[84:85], v[12:13]
	v_pk_fma_f32 v[40:41], v[60:61], s[52:53], v[40:41] op_sel_hi:[1,0,1] neg_lo:[0,0,1] neg_hi:[0,0,1]
	v_pk_mul_f32 v[58:59], v[84:85], v[58:59]
	v_lshlrev_b32_e32 v84, 16, v42
	v_and_b32_e32 v85, 0xffff0000, v42
	v_pk_add_f32 v[72:73], v[72:73], v[84:85]
	v_pk_add_f32 v[40:41], v[40:41], v[10:11]
	v_pk_fma_f32 v[84:85], v[72:73], s[52:53], v[84:85] op_sel_hi:[1,0,1] neg_lo:[0,0,1] neg_hi:[0,0,1]
	v_lshlrev_b32_e32 v44, 16, v45
	v_and_b32_e32 v45, 0xffff0000, v45
	v_pk_mul_f32 v[40:41], v[40:41], v[14:15]
	v_pk_add_f32 v[84:85], v[84:85], v[0:1]
	v_pk_mul_f32 v[44:45], v[40:41], v[44:45]
	v_lshlrev_b32_e32 v40, 16, v46
	v_and_b32_e32 v41, 0xffff0000, v46
	v_pk_mul_f32 v[84:85], v[84:85], v[4:5]
	v_lshlrev_b32_e32 v42, 16, v43
	v_pk_mul_f32 v[84:85], v[84:85], v[40:41]
	v_lshlrev_b32_e32 v40, 16, v47
	v_and_b32_e32 v41, 0xffff0000, v47
	v_pk_add_f32 v[46:47], v[54:55], v[62:63] neg_lo:[0,1] neg_hi:[0,1]
	v_and_b32_e32 v43, 0xffff0000, v43
	v_pk_add_f32 v[46:47], v[46:47], v[42:43]
	s_nop 0
	v_pk_fma_f32 v[42:43], v[46:47], s[52:53], v[42:43] op_sel_hi:[1,0,1] neg_lo:[0,0,1] neg_hi:[0,0,1]
	s_nop 0
	v_pk_add_f32 v[42:43], v[42:43], v[2:3]
	s_nop 0
	v_pk_mul_f32 v[42:43], v[42:43], v[6:7]
	s_nop 0
	v_pk_mul_f32 v[54:55], v[42:43], v[40:41]
	v_cvt_pk_bf16_f32 v41, v44, v45
	v_add_u32_e32 v44, 0xffff8004, v150
	v_ashrrev_i32_e32 v45, 31, v44
	v_lshlrev_b64 v[44:45], 12, v[44:45]
	v_cvt_pk_bf16_f32 v40, v58, v59
	v_cvt_pk_bf16_f32 v42, v84, v85
	v_cvt_pk_bf16_f32 v43, v54, v55
	v_lshl_add_u64 v[44:45], v[162:163], 0, v[44:45]
	global_store_dwordx4 v[44:45], v[40:43], off offset:2048 nt
	v_lshlrev_b32_e32 v44, 16, v32
	v_and_b32_e32 v45, 0xffff0000, v32
	v_pk_add_f32 v[42:43], v[76:77], v[74:75] neg_lo:[0,1] neg_hi:[0,1]
	s_waitcnt vmcnt(6)
	v_lshlrev_b32_e32 v40, 16, v36
	v_pk_add_f32 v[42:43], v[42:43], v[44:45]
	v_and_b32_e32 v41, 0xffff0000, v36
	v_pk_fma_f32 v[44:45], v[42:43], s[52:53], v[44:45] op_sel_hi:[1,0,1] neg_lo:[0,0,1] neg_hi:[0,0,1]
	v_lshlrev_b32_e32 v32, 16, v33
	v_pk_add_f32 v[44:45], v[44:45], v[8:9]
	v_and_b32_e32 v33, 0xffff0000, v33
	v_pk_mul_f32 v[44:45], v[44:45], v[12:13]
	v_pk_add_f32 v[54:55], v[72:73], v[78:79] neg_lo:[0,1] neg_hi:[0,1]
	v_pk_mul_f32 v[40:41], v[44:45], v[40:41]
	v_pk_add_f32 v[44:45], v[60:61], v[80:81] neg_lo:[0,1] neg_hi:[0,1]
	v_lshlrev_b32_e32 v58, 16, v34
	v_pk_add_f32 v[44:45], v[44:45], v[32:33]
	v_and_b32_e32 v59, 0xffff0000, v34
	v_pk_fma_f32 v[32:33], v[44:45], s[52:53], v[32:33] op_sel_hi:[1,0,1] neg_lo:[0,0,1] neg_hi:[0,0,1]
	v_pk_add_f32 v[54:55], v[54:55], v[58:59]
	v_pk_add_f32 v[32:33], v[32:33], v[10:11]
	v_pk_fma_f32 v[58:59], v[54:55], s[52:53], v[58:59] op_sel_hi:[1,0,1] neg_lo:[0,0,1] neg_hi:[0,0,1]
	v_lshlrev_b32_e32 v36, 16, v37
	v_and_b32_e32 v37, 0xffff0000, v37
	v_pk_mul_f32 v[32:33], v[32:33], v[14:15]
	v_pk_add_f32 v[58:59], v[58:59], v[0:1]
	v_pk_mul_f32 v[36:37], v[32:33], v[36:37]
	v_lshlrev_b32_e32 v32, 16, v38
	v_and_b32_e32 v33, 0xffff0000, v38
	v_pk_mul_f32 v[58:59], v[58:59], v[4:5]
	v_lshlrev_b32_e32 v34, 16, v35
	v_pk_mul_f32 v[58:59], v[58:59], v[32:33]
	v_lshlrev_b32_e32 v32, 16, v39
	v_and_b32_e32 v33, 0xffff0000, v39
	v_pk_add_f32 v[38:39], v[46:47], v[64:65] neg_lo:[0,1] neg_hi:[0,1]
	v_and_b32_e32 v35, 0xffff0000, v35
	v_pk_add_f32 v[38:39], v[38:39], v[34:35]
	s_nop 0
	v_pk_fma_f32 v[34:35], v[38:39], s[52:53], v[34:35] op_sel_hi:[1,0,1] neg_lo:[0,0,1] neg_hi:[0,0,1]
	s_nop 0
	v_pk_add_f32 v[34:35], v[34:35], v[2:3]
	s_nop 0
	v_pk_mul_f32 v[34:35], v[34:35], v[6:7]
	s_nop 0
	v_pk_mul_f32 v[46:47], v[34:35], v[32:33]
	v_cvt_pk_bf16_f32 v33, v36, v37
	v_add_u32_e32 v36, 0xffff8005, v150
	v_ashrrev_i32_e32 v37, 31, v36
	v_lshlrev_b64 v[36:37], 12, v[36:37]
	v_cvt_pk_bf16_f32 v32, v40, v41
	v_cvt_pk_bf16_f32 v34, v58, v59
	v_cvt_pk_bf16_f32 v35, v46, v47
	v_lshl_add_u64 v[36:37], v[162:163], 0, v[36:37]
	global_store_dwordx4 v[36:37], v[32:35], off offset:2048 nt
	v_lshlrev_b32_e32 v36, 16, v24
	v_and_b32_e32 v37, 0xffff0000, v24
	v_pk_add_f32 v[34:35], v[42:43], v[66:67] neg_lo:[0,1] neg_hi:[0,1]
	v_lshlrev_b32_e32 v32, 16, v28
	v_pk_add_f32 v[34:35], v[34:35], v[36:37]
	v_and_b32_e32 v33, 0xffff0000, v28
	v_pk_fma_f32 v[36:37], v[34:35], s[52:53], v[36:37] op_sel_hi:[1,0,1] neg_lo:[0,0,1] neg_hi:[0,0,1]
	v_lshlrev_b32_e32 v24, 16, v25
	v_pk_add_f32 v[36:37], v[36:37], v[8:9]
	v_and_b32_e32 v25, 0xffff0000, v25
	v_pk_mul_f32 v[36:37], v[36:37], v[12:13]
	v_pk_add_f32 v[40:41], v[54:55], v[68:69] neg_lo:[0,1] neg_hi:[0,1]
	v_pk_mul_f32 v[32:33], v[36:37], v[32:33]
	v_pk_add_f32 v[36:37], v[44:45], v[82:83] neg_lo:[0,1] neg_hi:[0,1]
	v_lshlrev_b32_e32 v42, 16, v26
	v_pk_add_f32 v[36:37], v[36:37], v[24:25]
	v_and_b32_e32 v43, 0xffff0000, v26
	v_pk_fma_f32 v[24:25], v[36:37], s[52:53], v[24:25] op_sel_hi:[1,0,1] neg_lo:[0,0,1] neg_hi:[0,0,1]
	v_pk_add_f32 v[40:41], v[40:41], v[42:43]
	v_pk_add_f32 v[24:25], v[24:25], v[10:11]
	v_pk_fma_f32 v[42:43], v[40:41], s[52:53], v[42:43] op_sel_hi:[1,0,1] neg_lo:[0,0,1] neg_hi:[0,0,1]
	v_lshlrev_b32_e32 v28, 16, v29
	v_and_b32_e32 v29, 0xffff0000, v29
	v_pk_mul_f32 v[24:25], v[24:25], v[14:15]
	v_pk_add_f32 v[42:43], v[42:43], v[0:1]
	v_pk_mul_f32 v[28:29], v[24:25], v[28:29]
	v_lshlrev_b32_e32 v24, 16, v30
	v_and_b32_e32 v25, 0xffff0000, v30
	v_pk_mul_f32 v[42:43], v[42:43], v[4:5]
	v_lshlrev_b32_e32 v26, 16, v27
	v_pk_mul_f32 v[42:43], v[42:43], v[24:25]
	v_lshlrev_b32_e32 v24, 16, v31
	v_and_b32_e32 v25, 0xffff0000, v31
	v_pk_add_f32 v[30:31], v[38:39], v[50:51] neg_lo:[0,1] neg_hi:[0,1]
	v_and_b32_e32 v27, 0xffff0000, v27
	v_pk_add_f32 v[30:31], v[30:31], v[26:27]
	s_nop 0
	v_pk_fma_f32 v[26:27], v[30:31], s[52:53], v[26:27] op_sel_hi:[1,0,1] neg_lo:[0,0,1] neg_hi:[0,0,1]
	s_nop 0
	v_pk_add_f32 v[26:27], v[26:27], v[2:3]
	s_nop 0
	v_pk_mul_f32 v[26:27], v[26:27], v[6:7]
	s_nop 0
	v_pk_mul_f32 v[38:39], v[26:27], v[24:25]
	v_cvt_pk_bf16_f32 v25, v28, v29
	v_add_u32_e32 v28, 0xffff8006, v150
	v_ashrrev_i32_e32 v29, 31, v28
	v_lshlrev_b64 v[28:29], 12, v[28:29]
	v_cvt_pk_bf16_f32 v24, v32, v33
	v_cvt_pk_bf16_f32 v26, v42, v43
	v_cvt_pk_bf16_f32 v27, v38, v39
	v_lshl_add_u64 v[28:29], v[162:163], 0, v[28:29]
	global_store_dwordx4 v[28:29], v[24:27], off offset:2048 nt
	v_lshlrev_b32_e32 v28, 16, v16
	v_and_b32_e32 v29, 0xffff0000, v16
	v_pk_add_f32 v[26:27], v[34:35], v[48:49] neg_lo:[0,1] neg_hi:[0,1]
	s_waitcnt vmcnt(7)
	v_lshlrev_b32_e32 v24, 16, v20
	v_pk_add_f32 v[26:27], v[26:27], v[28:29]
	v_and_b32_e32 v25, 0xffff0000, v20
	v_pk_fma_f32 v[26:27], v[26:27], s[52:53], v[28:29] op_sel_hi:[1,0,1] neg_lo:[0,0,1] neg_hi:[0,0,1]
	v_lshlrev_b32_e32 v16, 16, v17
	v_pk_add_f32 v[8:9], v[26:27], v[8:9]
	v_and_b32_e32 v17, 0xffff0000, v17
	v_pk_mul_f32 v[8:9], v[8:9], v[12:13]
	v_lshlrev_b32_e32 v12, 16, v21
	v_and_b32_e32 v13, 0xffff0000, v21
	v_pk_add_f32 v[20:21], v[36:37], v[70:71] neg_lo:[0,1] neg_hi:[0,1]
	v_pk_mul_f32 v[8:9], v[8:9], v[24:25]
	v_pk_add_f32 v[20:21], v[20:21], v[16:17]
	s_nop 0
	v_pk_fma_f32 v[16:17], v[20:21], s[52:53], v[16:17] op_sel_hi:[1,0,1] neg_lo:[0,0,1] neg_hi:[0,0,1]
	s_nop 0
	v_pk_add_f32 v[10:11], v[16:17], v[10:11]
	v_lshlrev_b32_e32 v16, 16, v18
	v_pk_mul_f32 v[10:11], v[10:11], v[14:15]
	v_pk_add_f32 v[14:15], v[40:41], v[56:57] neg_lo:[0,1] neg_hi:[0,1]
	v_and_b32_e32 v17, 0xffff0000, v18
	v_pk_add_f32 v[14:15], v[14:15], v[16:17]
	v_pk_mul_f32 v[10:11], v[10:11], v[12:13]
	v_pk_fma_f32 v[14:15], v[14:15], s[52:53], v[16:17] op_sel_hi:[1,0,1] neg_lo:[0,0,1] neg_hi:[0,0,1]
	v_lshlrev_b32_e32 v12, 16, v22
	v_pk_add_f32 v[0:1], v[14:15], v[0:1]
	v_and_b32_e32 v13, 0xffff0000, v22
	v_pk_mul_f32 v[0:1], v[0:1], v[4:5]
	v_lshlrev_b32_e32 v14, 16, v19
	v_pk_mul_f32 v[4:5], v[0:1], v[12:13]
	v_pk_add_f32 v[12:13], v[30:31], v[52:53] neg_lo:[0,1] neg_hi:[0,1]
	v_and_b32_e32 v15, 0xffff0000, v19
	v_pk_add_f32 v[12:13], v[12:13], v[14:15]
	v_lshlrev_b32_e32 v0, 16, v23
	v_pk_fma_f32 v[12:13], v[12:13], s[52:53], v[14:15] op_sel_hi:[1,0,1] neg_lo:[0,0,1] neg_hi:[0,0,1]
	v_and_b32_e32 v1, 0xffff0000, v23
	v_pk_add_f32 v[2:3], v[12:13], v[2:3]
	s_nop 0
	v_pk_mul_f32 v[2:3], v[2:3], v[6:7]
	s_nop 0
	v_pk_mul_f32 v[6:7], v[2:3], v[0:1]
	v_cvt_pk_bf16_f32 v2, v4, v5
	v_add_u32_e32 v4, 0xffff8007, v150
	v_ashrrev_i32_e32 v5, 31, v4
	v_lshlrev_b64 v[4:5], 12, v[4:5]
	v_cvt_pk_bf16_f32 v0, v8, v9
	v_cvt_pk_bf16_f32 v1, v10, v11
	v_cvt_pk_bf16_f32 v3, v6, v7
	v_lshl_add_u64 v[4:5], v[162:163], 0, v[4:5]
	global_store_dwordx4 v[4:5], v[0:3], off offset:2048 nt
